# gdn_prep: decay pass rewritten branch-free in place, S4a/S4b LDS loads hoisted+counted waits; scan helper counted vmcnt; LN epilogue gamma/beta hoist
# speedup vs baseline: 1.0068x; 1.0068x over previous
; #define LAS __attribute__((address_space(3)))
; DI float fexp2(float x) { return __builtin_amdgcn_exp2f(x); }
; DI int crow(int r, int hi) { return (r & 3) + 8 * (r >> 2) + 4 * hi; }
; #define MFMA32(a, b, c) __builtin_amdgcn_mfma_f32_32x32x16_bf16((a), (b), (c), 0, 0, 0)
; DI void gdn_prefetch(const Ctx& c, int item, const bf16_t* proj, u32x4 (&x)[12], bf16_t& ga, bf16_t& gb) {
;     const int tid = c.tid; const int b = item >> 9, h = (item >> 6) & 7, n = item & 63; const int t = tid >> 3, cg8 = tid & 7;
; #pragma unroll
;     for (int which = 0; which < 3; ++which)
; #pragma unroll
;         for (int j = 0; j < 4; ++j) { const int sp = n * 64 + t - 3 + j; const int spc = sp >= 0 ? sp : 0;
;             x[which * 4 + j] = *(const u32x4*)(proj + (size_t)(b * SEQ + spc) * NINP + which * 512 + h * 64 + cg8 * 8); }
;     const size_t ro = (size_t)(b * SEQ + n * 64 + (tid & 63)) * NINP; ga = proj[ro + C_GA + h]; gb = proj[ro + C_GB + h];
;     ...
;     { const int l31 = lane & 31, hi = lane >> 5; const int isqk = wid >> 2, jt = (wid >> 1) & 1, it = wid & 1;
;         if (jt <= it) {
;             const LAS bf16_t* BH = isqk ? QH : KH; const LAS bf16_t* BL = isqk ? QL : KL;
;             bf16x8 aH[4], aLo[4], bH[4], bLo[4];
; #pragma unroll
;             for (int ks = 0; ks < 4; ++ks) { const int ao = (32 * jt + l31) * 72 + 16 * ks + 8 * hi, bo = (32 * it + l31) * 72 + 16 * ks + 8 * hi;
;                 aH[ks] = *(const LAS bf16x8*)(KH + ao); aLo[ks] = *(const LAS bf16x8*)(KL + ao); bH[ks] = *(const LAS bf16x8*)(BH + bo); bLo[ks] = *(const LAS bf16x8*)(BL + bo); }
;             __builtin_amdgcn_sched_barrier(0);
;             f32x16 acc;
; #pragma unroll
;             for (int r = 0; r < 16; ++r) acc[r] = 0.f;
; #pragma unroll
;             for (int ks = 0; ks < 4; ++ks) { acc = MFMA32(aH[ks], bH[ks], acc); acc = MFMA32(aH[ks], bLo[ks], acc); acc = MFMA32(aLo[ks], bH[ks], acc); }
;             const int i = 32 * it + l31; const float gi = gcs[i], bi = bet[i];
; #pragma unroll
;             for (int r = 0; r < 16; ++r) { const int j = 32 * jt + crow(r, hi); const float d = fexp2((gi - gcs[j]) * 1.4426950408889634f);
;                 if (isqk) acc[r] = (j <= i) ? acc[r] * d : 0.f; else Lm[j * 68 + i] = (j < i) ? bi * acc[r] * d : 0.f; }
.LBB0_436:
	s_add_i32 s19, s2, s30
	s_cmpk_lt_i32 s19, 0x800
	s_waitcnt lgkmcnt(0)
	s_barrier
	s_cselect_b64 s[42:43], -1, 0
	s_cmpk_gt_i32 s19, 0x7ff
	s_cselect_b64 s[68:69], -1, 0
	s_andn2_b64 vcc, exec, s[0:1]
	s_cbranch_vccnz .LBB0_433
	s_and_b64 s[42:43], s[42:43], exec
	s_mul_i32 s40, s2, 0xa000
	s_cselect_b32 s3, s19, s2
	s_mul_hi_i32 s33, s2, 0xa000
	s_add_u32 s72, s71, s40
	s_addc_u32 s73, s74, s33
	s_lshl_b32 s40, s3, 6
	s_and_b32 s52, s40, 0xfc0
	v_add_u32_e32 v1, s52, v110
	s_bfe_u32 s33, s3, 0x30006
	v_add_u32_e32 v8, -3, v1
	s_lshl_b32 s3, s3, 3
	s_and_b32 s3, s3, 0xfffff000
	s_lshl_b32 s40, s33, 7
	v_max_i32_e32 v4, 0, v8
	v_lshl_add_u64 v[2:3], v[84:85], 0, s[40:41]
	v_add_u32_e32 v4, s3, v4
	v_max_i32_e32 v6, -1, v8
	v_max_i32_e32 v8, -2, v8
	v_mad_i64_i32 v[4:5], s[42:43], v4, s18, v[2:3]
	v_add3_u32 v6, v6, s3, 1
	v_add3_u32 v8, v8, s3, 2
	v_add_u32_e32 v1, s3, v1
	v_mad_i64_i32 v[6:7], s[42:43], v6, s18, v[2:3]
	v_mad_i64_i32 v[8:9], s[42:43], v8, s18, v[2:3]
	v_mad_i64_i32 v[2:3], s[42:43], v1, s18, v[2:3]
	global_load_dwordx4 v[70:73], v[4:5], off
	global_load_dwordx4 v[54:57], v[4:5], off offset:1024
	global_load_dwordx4 v[58:61], v[8:9], off
	global_load_dwordx4 v[50:53], v[8:9], off offset:1024
	global_load_dwordx4 v[74:77], v[6:7], off
	global_load_dwordx4 v[34:37], v[4:5], off offset:2048
	global_load_dwordx4 v[62:65], v[6:7], off offset:1024
	global_load_dwordx4 v[38:41], v[6:7], off offset:2048
	global_load_dwordx4 v[78:81], v[2:3], off
	global_load_dwordx4 v[42:45], v[8:9], off offset:2048
	global_load_dwordx4 v[66:69], v[2:3], off offset:1024
	global_load_dwordx4 v[46:49], v[2:3], off offset:2048
	v_or_b32_e32 v1, s52, v202
	v_or_b32_e32 v1, s3, v1
	v_mov_b64_e32 v[2:3], s[36:37]
	v_mad_i64_i32 v[2:3], s[42:43], v1, s18, v[2:3]
	s_lshl_b32 s40, s33, 1
	v_lshl_add_u64 v[2:3], v[2:3], 0, s[40:41]
	v_add_co_u32_e32 v2, vcc, 0x1000, v2
	s_mov_b64 s[42:43], -1
	s_nop 0
	v_addc_co_u32_e32 v3, vcc, 0, v3, vcc
	global_load_ushort v1, v[2:3], off
	global_load_ushort v100, v[2:3], off offset:16
	v_mov_b32_e32 v2, s17
	ds_read_b32 v82, v2
	s_andn2_b64 vcc, exec, s[22:23]
	s_cbranch_vccnz .LBB0_508
	ds_read_b128 v[18:21], v119
	ds_read_b128 v[22:25], v120
	ds_read_b128 v[26:29], v123
	ds_read_b128 v[30:33], v124
	ds_read_b128 v[94:97], v121
	ds_read_b128 v[196:199], v121 offset:32
	ds_read_b128 v[204:207], v122
	ds_read_b128 v[208:211], v122 offset:32
	ds_read_b128 v[212:215], v125
	ds_read_b128 v[216:219], v126
	ds_read_b128 v[220:223], v127
	ds_read_b128 v[224:227], v128
	ds_read_b128 v[228:231], v121 offset:64
	ds_read_b128 v[232:235], v121 offset:96
	ds_read_b128 v[236:239], v122 offset:64
	ds_read_b128 v[240:243], v122 offset:96
	s_waitcnt lgkmcnt(11)
	v_mfma_f32_32x32x16_bf16 v[2:17], v[18:21], v[94:97], 0
	s_and_b64 vcc, exec, s[24:25]
	s_waitcnt lgkmcnt(9)
	v_mfma_f32_32x32x16_bf16 v[2:17], v[18:21], v[204:207], v[2:17]
	v_mfma_f32_32x32x16_bf16 v[2:17], v[22:25], v[94:97], v[2:17]
	ds_read_b32 v95, v129
	ds_read_b32 v18, v131
	ds_read_b32 v94, v130
	s_waitcnt lgkmcnt(1)
	v_sub_f32_e32 v18, v95, v18
	v_mul_f32_e32 v18, 0x3fb8aa3b, v18
	v_exp_f32_e32 v96, v18
	v_mfma_f32_32x32x16_bf16 v[2:17], v[26:29], v[196:199], v[2:17]
	v_mfma_f32_32x32x16_bf16 v[2:17], v[26:29], v[208:211], v[2:17]
	v_mfma_f32_32x32x16_bf16 v[2:17], v[30:33], v[196:199], v[2:17]
	v_mfma_f32_32x32x16_bf16 v[2:17], v[212:215], v[228:231], v[2:17]
	v_mfma_f32_32x32x16_bf16 v[2:17], v[212:215], v[236:239], v[2:17]
	v_mfma_f32_32x32x16_bf16 v[2:17], v[216:219], v[228:231], v[2:17]
	v_mfma_f32_32x32x16_bf16 v[2:17], v[220:223], v[232:235], v[2:17]
	v_mfma_f32_32x32x16_bf16 v[2:17], v[220:223], v[240:243], v[2:17]
	v_mfma_f32_32x32x16_bf16 v[2:17], v[224:227], v[232:235], v[2:17]
	ds_read_b32 v19, v132
	ds_read_b32 v20, v133
	ds_read_b32 v21, v134
	ds_read_b32 v22, v135
	ds_read_b32 v23, v136
	ds_read_b32 v24, v137
	ds_read_b32 v25, v138
	ds_read_b32 v26, v139
	ds_read_b32 v27, v140
	ds_read_b32 v28, v141
	ds_read_b32 v29, v142
	ds_read_b32 v30, v143
	ds_read_b32 v31, v144
	ds_read_b32 v32, v145
	ds_read_b32 v33, v146
	v_mov_b32_e32 v18, v96
	s_waitcnt lgkmcnt(0)
	v_sub_f32_e32 v19, v95, v19
	v_sub_f32_e32 v20, v95, v20
	v_sub_f32_e32 v21, v95, v21
	v_sub_f32_e32 v22, v95, v22
	v_sub_f32_e32 v23, v95, v23
	v_sub_f32_e32 v24, v95, v24
	v_sub_f32_e32 v25, v95, v25
	v_sub_f32_e32 v26, v95, v26
	v_sub_f32_e32 v27, v95, v27
	v_sub_f32_e32 v28, v95, v28
	v_sub_f32_e32 v29, v95, v29
	v_sub_f32_e32 v30, v95, v30
	v_sub_f32_e32 v31, v95, v31
	v_sub_f32_e32 v32, v95, v32
	v_sub_f32_e32 v33, v95, v33
	v_mul_f32_e32 v19, 0x3fb8aa3b, v19
	v_mul_f32_e32 v20, 0x3fb8aa3b, v20
	v_mul_f32_e32 v21, 0x3fb8aa3b, v21
	v_mul_f32_e32 v22, 0x3fb8aa3b, v22
	v_mul_f32_e32 v23, 0x3fb8aa3b, v23
	v_mul_f32_e32 v24, 0x3fb8aa3b, v24
	v_mul_f32_e32 v25, 0x3fb8aa3b, v25
	v_mul_f32_e32 v26, 0x3fb8aa3b, v26
	v_mul_f32_e32 v27, 0x3fb8aa3b, v27
	v_mul_f32_e32 v28, 0x3fb8aa3b, v28
	v_mul_f32_e32 v29, 0x3fb8aa3b, v29
	v_mul_f32_e32 v30, 0x3fb8aa3b, v30
	v_mul_f32_e32 v31, 0x3fb8aa3b, v31
	v_mul_f32_e32 v32, 0x3fb8aa3b, v32
	v_mul_f32_e32 v33, 0x3fb8aa3b, v33
	v_exp_f32_e32 v19, v19
	v_exp_f32_e32 v20, v20
	v_exp_f32_e32 v21, v21
	v_exp_f32_e32 v22, v22
	v_exp_f32_e32 v23, v23
	v_exp_f32_e32 v24, v24
	v_exp_f32_e32 v25, v25
	v_exp_f32_e32 v26, v26
	v_exp_f32_e32 v27, v27
	v_exp_f32_e32 v28, v28
	v_exp_f32_e32 v29, v29
	v_exp_f32_e32 v30, v30
	v_exp_f32_e32 v31, v31
	v_exp_f32_e32 v32, v32
	v_exp_f32_e32 v33, v33
	s_andn2_b64 vcc, exec, s[24:25]
	s_cbranch_vccnz .Ldecay_l_0
; DI float fexp2(float x) { return __builtin_amdgcn_exp2f(x); }
; DI int crow(int r, int hi) { return (r & 3) + 8 * (r >> 2) + 4 * hi; }
;     ...
;             const int i = 32 * it + l31; const float gi = gcs[i], bi = bet[i];
; #pragma unroll
;             for (int r = 0; r < 16; ++r) { const int j = 32 * jt + crow(r, hi); const float d = fexp2((gi - gcs[j]) * 1.4426950408889634f);
;                 if (isqk) acc[r] = (j <= i) ? acc[r] * d : 0.f; else Lm[j * 68 + i] = (j < i) ? bi * acc[r] * d : 0.f; }
	v_readlane_b32 s42, v247, 37
	v_readlane_b32 s43, v247, 38
	v_mul_f32_e32 v2, v2, v18
	s_nop 1
	v_cndmask_b32_e64 v2, v2, 0, s[42:43]
	v_readlane_b32 s42, v247, 39
	v_readlane_b32 s43, v247, 40
	v_mul_f32_e32 v3, v3, v19
	s_nop 1
	v_cndmask_b32_e64 v3, 0, v3, s[42:43]
	v_readlane_b32 s42, v247, 43
	v_readlane_b32 s43, v247, 44
	v_mul_f32_e32 v4, v4, v20
	s_nop 1
	v_cndmask_b32_e64 v4, v4, 0, s[42:43]
	v_readlane_b32 s42, v247, 47
	v_readlane_b32 s43, v247, 48
	v_mul_f32_e32 v5, v5, v21
	s_nop 1
	v_cndmask_b32_e64 v5, v5, 0, s[42:43]
	v_readlane_b32 s42, v247, 51
	v_readlane_b32 s43, v247, 52
	v_mul_f32_e32 v6, v6, v22
	s_nop 1
	v_cndmask_b32_e64 v6, v6, 0, s[42:43]
	v_readlane_b32 s42, v247, 55
	v_readlane_b32 s43, v247, 56
	v_mul_f32_e32 v7, v7, v23
	s_nop 1
	v_cndmask_b32_e64 v7, v7, 0, s[42:43]
	v_readlane_b32 s42, v247, 59
	v_readlane_b32 s43, v247, 60
	v_mul_f32_e32 v8, v8, v24
	s_nop 1
	v_cndmask_b32_e64 v8, v8, 0, s[42:43]
	v_readlane_b32 s42, v247, 63
	v_readlane_b32 s43, v246, 0
	v_mul_f32_e32 v9, v9, v25
	s_nop 1
	v_cndmask_b32_e64 v9, v9, 0, s[42:43]
	v_readlane_b32 s42, v246, 3
	v_readlane_b32 s43, v246, 4
	v_mul_f32_e32 v10, v10, v26
	s_nop 1
	v_cndmask_b32_e64 v10, v10, 0, s[42:43]
	v_readlane_b32 s42, v246, 7
	v_readlane_b32 s43, v246, 8
	v_mul_f32_e32 v11, v11, v27
	s_nop 1
	v_cndmask_b32_e64 v11, v11, 0, s[42:43]
	v_readlane_b32 s42, v246, 11
	v_readlane_b32 s43, v246, 12
	v_mul_f32_e32 v12, v12, v28
	s_nop 1
	v_cndmask_b32_e64 v12, v12, 0, s[42:43]
	v_readlane_b32 s42, v246, 15
	v_readlane_b32 s43, v246, 16
	v_mul_f32_e32 v13, v13, v29
	s_nop 1
	v_cndmask_b32_e64 v13, v13, 0, s[42:43]
	v_readlane_b32 s42, v246, 19
	v_readlane_b32 s43, v246, 20
	v_mul_f32_e32 v14, v14, v30
	s_nop 1
	v_cndmask_b32_e64 v14, v14, 0, s[42:43]
	v_readlane_b32 s42, v246, 23
	v_readlane_b32 s43, v246, 24
	v_mul_f32_e32 v15, v15, v31
	s_nop 1
	v_cndmask_b32_e64 v15, v15, 0, s[42:43]
	v_readlane_b32 s42, v246, 27
	v_readlane_b32 s43, v246, 28
	v_mul_f32_e32 v16, v16, v32
	s_nop 1
	v_cndmask_b32_e64 v16, v16, 0, s[42:43]
	v_readlane_b32 s42, v246, 31
	v_readlane_b32 s43, v246, 32
	v_mul_f32_e32 v17, v17, v33
	s_nop 1
	v_cndmask_b32_e64 v17, v17, 0, s[42:43]
	s_mov_b64 s[42:43], -1
	s_branch .LBB0_504
.Ldecay_l_0:
	v_mul_f32_e32 v96, v94, v2
	v_readlane_b32 s42, v247, 39
	v_readlane_b32 s43, v247, 40
	v_mul_f32_e32 v96, v96, v18
	s_nop 1
	v_cndmask_b32_e64 v96, 0, v96, s[42:43]
	ds_write_b32 v194, v96 offset:52224
	v_mul_f32_e32 v97, v94, v3
	v_readlane_b32 s42, v247, 41
	v_readlane_b32 s43, v247, 42
	v_mul_f32_e32 v97, v97, v19
	s_nop 1
	v_cndmask_b32_e64 v97, 0, v97, s[42:43]
	ds_write_b32 v194, v97 offset:52496
	v_mul_f32_e32 v96, v94, v4
	v_readlane_b32 s42, v247, 45
	v_readlane_b32 s43, v247, 46
	v_mul_f32_e32 v96, v96, v20
	s_nop 1
	v_cndmask_b32_e64 v96, 0, v96, s[42:43]
	ds_write_b32 v194, v96 offset:52768
	v_mul_f32_e32 v97, v94, v5
	v_readlane_b32 s42, v247, 49
	v_readlane_b32 s43, v247, 50
	v_mul_f32_e32 v97, v97, v21
	s_nop 1
	v_cndmask_b32_e64 v97, 0, v97, s[42:43]
	ds_write_b32 v194, v97 offset:53040
	v_mul_f32_e32 v96, v94, v6
	v_readlane_b32 s42, v247, 53
	v_readlane_b32 s43, v247, 54
	v_mul_f32_e32 v96, v96, v22
	s_nop 1
	v_cndmask_b32_e64 v96, 0, v96, s[42:43]
	ds_write_b32 v194, v96 offset:54400
	v_mul_f32_e32 v97, v94, v7
	v_readlane_b32 s42, v247, 57
	v_readlane_b32 s43, v247, 58
	v_mul_f32_e32 v97, v97, v23
	s_nop 1
	v_cndmask_b32_e64 v97, 0, v97, s[42:43]
	ds_write_b32 v194, v97 offset:54672
	v_mul_f32_e32 v96, v94, v8
	v_readlane_b32 s42, v247, 61
	v_readlane_b32 s43, v247, 62
	v_mul_f32_e32 v96, v96, v24
	s_nop 1
	v_cndmask_b32_e64 v96, 0, v96, s[42:43]
	ds_write_b32 v194, v96 offset:54944
	v_mul_f32_e32 v97, v94, v9
	v_readlane_b32 s42, v246, 1
	v_readlane_b32 s43, v246, 2
	v_mul_f32_e32 v97, v97, v25
	s_nop 1
	v_cndmask_b32_e64 v97, 0, v97, s[42:43]
	ds_write_b32 v194, v97 offset:55216
	v_mul_f32_e32 v96, v94, v10
	v_readlane_b32 s42, v246, 5
	v_readlane_b32 s43, v246, 6
	v_mul_f32_e32 v96, v96, v26
	s_nop 1
	v_cndmask_b32_e64 v96, 0, v96, s[42:43]
	ds_write_b32 v194, v96 offset:56576
	v_mul_f32_e32 v97, v94, v11
	v_readlane_b32 s42, v246, 9
	v_readlane_b32 s43, v246, 10
	v_mul_f32_e32 v97, v97, v27
	s_nop 1
	v_cndmask_b32_e64 v97, 0, v97, s[42:43]
	ds_write_b32 v194, v97 offset:56848
	v_mul_f32_e32 v96, v94, v12
	v_readlane_b32 s42, v246, 13
	v_readlane_b32 s43, v246, 14
	v_mul_f32_e32 v96, v96, v28
	s_nop 1
	v_cndmask_b32_e64 v96, 0, v96, s[42:43]
	ds_write_b32 v194, v96 offset:57120
	v_mul_f32_e32 v97, v94, v13
	v_readlane_b32 s42, v246, 17
	v_readlane_b32 s43, v246, 18
	v_mul_f32_e32 v97, v97, v29
	s_nop 1
	v_cndmask_b32_e64 v97, 0, v97, s[42:43]
	ds_write_b32 v194, v97 offset:57392
	v_mul_f32_e32 v96, v94, v14
	v_readlane_b32 s42, v246, 21
	v_readlane_b32 s43, v246, 22
	v_mul_f32_e32 v96, v96, v30
	s_nop 1
	v_cndmask_b32_e64 v96, 0, v96, s[42:43]
	ds_write_b32 v194, v96 offset:58752
	v_mul_f32_e32 v97, v94, v15
	v_readlane_b32 s42, v246, 25
	v_readlane_b32 s43, v246, 26
	v_mul_f32_e32 v97, v97, v31
	s_nop 1
	v_cndmask_b32_e64 v97, 0, v97, s[42:43]
	ds_write_b32 v194, v97 offset:59024
	v_mul_f32_e32 v96, v94, v16
	v_readlane_b32 s42, v246, 29
	v_readlane_b32 s43, v246, 30
	v_mul_f32_e32 v96, v96, v32
	s_nop 1
	v_cndmask_b32_e64 v96, 0, v96, s[42:43]
	ds_write_b32 v194, v96 offset:59296
	v_mul_f32_e32 v97, v94, v17
	v_readlane_b32 s42, v246, 33
	v_readlane_b32 s43, v246, 34
	v_mul_f32_e32 v97, v97, v33
	s_nop 1
	v_cndmask_b32_e64 v97, 0, v97, s[42:43]
	ds_write_b32 v194, v97 offset:59568
	s_mov_b64 s[42:43], -1
	s_branch .LBB0_505

; #define LAS __attribute__((address_space(3)))
;     ...
;             else if (jt == it) {
;                 const int bb = 2 * jt + ((lane >> 4) & 1), col = lane & 15;
;                 float y[16];
; #pragma unroll
;                 for (int ii = 0; ii < 16; ++ii) y[ii] = (ii == col) ? 1.f : 0.f;
; #pragma unroll
;                 for (int j = 0; j < 15; ++j) { const float yj = y[j];
; #pragma unroll
;                     for (int q4 = (j + 1) / 4; q4 < 4; ++q4) { const f32x4 l4 = *(const LAS f32x4*)(Lm + (16 * bb + j) * 68 + 16 * bb + 4 * q4);
; #pragma unroll
;                         for (int e = 0; e < 4; ++e) if (4 * q4 + e > j) y[4 * q4 + e] -= l4[e] * yj; } }
; #pragma unroll
;                 for (int ii = 0; ii < 16; ++ii) DIV[bb * 320 + ii * 20 + col] = y[ii];
.LBB0_505:
	v_readlane_b32 s42, v246, 35
	v_readlane_b32 s43, v246, 36
	s_andn2_b64 vcc, exec, s[42:43]
	s_cbranch_vccnz .LBB0_507
	ds_read_b128 v[196:199], v178 offset:52224
	ds_read_b128 v[204:207], v178 offset:52240
	ds_read_b128 v[208:211], v178 offset:52256
	ds_read_b128 v[212:215], v178 offset:52272
	ds_read_b128 v[216:219], v178 offset:52496
	ds_read_b128 v[220:223], v178 offset:52512
	ds_read_b128 v[224:227], v178 offset:52528
	ds_read_b128 v[228:231], v178 offset:52544
	ds_read_b128 v[232:235], v178 offset:52768
	s_waitcnt lgkmcnt(8)
	v_fma_f32 v2, -v147, v197, v148
	v_fma_f32 v3, -v147, v198, v149
	v_fma_f32 v18, -v147, v199, v150
	ds_read_b128 v[236:239], v178 offset:52784
	s_waitcnt lgkmcnt(8)
	v_fma_f32 v19, -v147, v204, v151
	v_fma_f32 v20, -v147, v205, v153
	v_fma_f32 v8, -v147, v206, v154
	v_fma_f32 v9, -v147, v207, v155
	ds_read_b128 v[240:243], v178 offset:52800
	s_waitcnt lgkmcnt(8)
	v_fma_f32 v10, -v147, v208, v156
	v_fma_f32 v11, -v147, v209, v157
	s_waitcnt lgkmcnt(6)
	v_fma_f32 v3, -v2, v218, v3
	v_fma_f32 v18, -v2, v219, v18
	v_fma_f32 v12, -v147, v210, v158
	v_fma_f32 v13, -v147, v211, v159
	ds_read_b128 v[196:199], v178 offset:52816
	ds_read_b128 v[204:207], v178 offset:53056
	v_fma_f32 v14, -v147, v212, v160
	v_fma_f32 v15, -v147, v213, v161
	ds_read_b128 v[208:211], v178 offset:53072
	s_waitcnt lgkmcnt(8)
	v_fma_f32 v19, -v2, v220, v19
	v_fma_f32 v20, -v2, v221, v20
	v_fma_f32 v21, -v2, v222, v8
	v_fma_f32 v22, -v2, v223, v9
	v_fma_f32 v16, -v147, v214, v162
	v_fma_f32 v17, -v147, v215, v163
	ds_read_b128 v[212:215], v178 offset:53088
	s_waitcnt lgkmcnt(8)
	v_fma_f32 v10, -v2, v224, v10
	v_fma_f32 v11, -v2, v225, v11
	v_fma_f32 v12, -v2, v226, v12
	v_fma_f32 v13, -v2, v227, v13
	ds_read_b128 v[216:219], v178 offset:53328
	s_waitcnt lgkmcnt(8)
	v_fma_f32 v14, -v2, v228, v14
	v_fma_f32 v15, -v2, v229, v15
	v_fma_f32 v16, -v2, v230, v16
	v_fma_f32 v17, -v2, v231, v17
	ds_read_b128 v[220:223], v178 offset:53344
	s_waitcnt lgkmcnt(8)
	v_fma_f32 v4, -v3, v235, v18
	ds_read_b128 v[224:227], v178 offset:53360
	s_waitcnt lgkmcnt(8)
	v_fma_f32 v5, -v3, v236, v19
	v_fma_f32 v18, -v3, v237, v20
	v_fma_f32 v19, -v3, v238, v21
	v_fma_f32 v20, -v3, v239, v22
	ds_read_b128 v[228:231], v178 offset:53600
	s_waitcnt lgkmcnt(8)
	v_fma_f32 v10, -v3, v240, v10
	v_fma_f32 v11, -v3, v241, v11
	v_fma_f32 v12, -v3, v242, v12
	v_fma_f32 v13, -v3, v243, v13
	ds_read_b128 v[232:235], v178 offset:53616
	s_waitcnt lgkmcnt(8)
	v_fma_f32 v14, -v3, v196, v14
	v_fma_f32 v15, -v3, v197, v15
	v_fma_f32 v16, -v3, v198, v16
	v_fma_f32 v17, -v3, v199, v17
	ds_read_b128 v[236:239], v178 offset:53632
	s_waitcnt lgkmcnt(8)
	v_fma_f32 v5, -v4, v204, v5
	v_fma_f32 v18, -v4, v205, v18
	v_fma_f32 v19, -v4, v206, v19
	v_fma_f32 v20, -v4, v207, v20
	ds_read_b128 v[240:243], v178 offset:53872
	s_waitcnt lgkmcnt(8)
	v_fma_f32 v21, -v4, v208, v10
	v_fma_f32 v22, -v4, v209, v11
	v_fma_f32 v12, -v4, v210, v12
	v_fma_f32 v13, -v4, v211, v13
	ds_read_b128 v[196:199], v178 offset:53888
	s_waitcnt lgkmcnt(8)
	v_fma_f32 v14, -v4, v212, v14
	v_fma_f32 v15, -v4, v213, v15
	v_fma_f32 v16, -v4, v214, v16
	v_fma_f32 v17, -v4, v215, v17
	ds_read_b128 v[204:207], v178 offset:53904
	s_waitcnt lgkmcnt(8)
	v_fma_f32 v6, -v5, v217, v18
	v_fma_f32 v7, -v5, v218, v19
	v_fma_f32 v18, -v5, v219, v20
	ds_read_b128 v[208:211], v178 offset:54160
	s_waitcnt lgkmcnt(8)
	v_fma_f32 v19, -v5, v220, v21
	v_fma_f32 v20, -v5, v221, v22
	v_fma_f32 v12, -v5, v222, v12
	v_fma_f32 v13, -v5, v223, v13
	ds_read_b128 v[212:215], v178 offset:54176
	s_waitcnt lgkmcnt(8)
	v_fma_f32 v14, -v5, v224, v14
	v_fma_f32 v15, -v5, v225, v15
	v_fma_f32 v16, -v5, v226, v16
	v_fma_f32 v17, -v5, v227, v17
	ds_read_b128 v[216:219], v178 offset:54432
	s_waitcnt lgkmcnt(8)
	v_fma_f32 v7, -v6, v230, v7
	v_fma_f32 v18, -v6, v231, v18
	ds_read_b128 v[220:223], v178 offset:54448
	s_waitcnt lgkmcnt(8)
	v_fma_f32 v19, -v6, v232, v19
	v_fma_f32 v20, -v6, v233, v20
	v_fma_f32 v12, -v6, v234, v12
	v_fma_f32 v13, -v6, v235, v13
	ds_read_b128 v[224:227], v178 offset:54704
	s_waitcnt lgkmcnt(8)
	v_fma_f32 v14, -v6, v236, v14
	v_fma_f32 v15, -v6, v237, v15
	v_fma_f32 v16, -v6, v238, v16
	v_fma_f32 v17, -v6, v239, v17
	ds_read_b128 v[228:231], v178 offset:54720
	s_waitcnt lgkmcnt(8)
	v_fma_f32 v18, -v7, v243, v18
	ds_read_b128 v[232:235], v178 offset:54976
	s_waitcnt lgkmcnt(8)
	v_fma_f32 v19, -v7, v196, v19
	v_fma_f32 v20, -v7, v197, v20
	v_fma_f32 v12, -v7, v198, v12
	v_fma_f32 v13, -v7, v199, v13
	ds_read_b128 v[236:239], v178 offset:54992
	s_waitcnt lgkmcnt(8)
	v_fma_f32 v14, -v7, v204, v14
	v_fma_f32 v15, -v7, v205, v15
	v_fma_f32 v16, -v7, v206, v16
	v_fma_f32 v17, -v7, v207, v17
	ds_read_b128 v[240:243], v178 offset:55264
	s_waitcnt lgkmcnt(8)
	v_fma_f32 v19, -v18, v208, v19
	v_fma_f32 v20, -v18, v209, v20
	v_fma_f32 v12, -v18, v210, v12
	v_fma_f32 v13, -v18, v211, v13
	ds_read_b128 v[196:199], v178 offset:55536
	s_waitcnt lgkmcnt(8)
	v_fma_f32 v14, -v18, v212, v14
	v_fma_f32 v15, -v18, v213, v15
	v_fma_f32 v16, -v18, v214, v16
	v_fma_f32 v17, -v18, v215, v17
	ds_read_b128 v[204:207], v178 offset:55808
	s_waitcnt lgkmcnt(8)
	v_fma_f32 v20, -v19, v217, v20
	v_fma_f32 v12, -v19, v218, v12
	v_fma_f32 v13, -v19, v219, v13
	ds_read_b128 v[208:211], v178 offset:56080
	s_waitcnt lgkmcnt(8)
	v_fma_f32 v14, -v19, v220, v14
	v_fma_f32 v15, -v19, v221, v15
	v_fma_f32 v16, -v19, v222, v16
	v_fma_f32 v17, -v19, v223, v17
	s_waitcnt lgkmcnt(7)
	v_fma_f32 v12, -v20, v226, v12
	v_fma_f32 v13, -v20, v227, v13
	s_waitcnt lgkmcnt(6)
	v_fma_f32 v14, -v20, v228, v14
	v_fma_f32 v15, -v20, v229, v15
	v_fma_f32 v16, -v20, v230, v16
	v_fma_f32 v17, -v20, v231, v17
	s_waitcnt lgkmcnt(5)
	v_fma_f32 v13, -v12, v235, v13
	s_waitcnt lgkmcnt(4)
	v_fma_f32 v14, -v12, v236, v14
	v_fma_f32 v15, -v12, v237, v15
	v_fma_f32 v16, -v12, v238, v16
	v_fma_f32 v17, -v12, v239, v17
	s_waitcnt lgkmcnt(3)
	v_fma_f32 v14, -v13, v240, v14
	v_fma_f32 v15, -v13, v241, v15
	v_fma_f32 v16, -v13, v242, v16
	v_fma_f32 v17, -v13, v243, v17
	s_waitcnt lgkmcnt(2)
	v_fma_f32 v15, -v197, v14, v15
	v_fma_f32 v16, -v198, v14, v16
	v_fma_f32 v17, -v199, v14, v17
	s_waitcnt lgkmcnt(1)
	v_fma_f32 v16, -v206, v15, v16
	v_fma_f32 v17, -v207, v15, v17
	ds_write2_b32 v164, v147, v2 offset1:20
	ds_write2_b32 v164, v3, v4 offset0:40 offset1:60
	ds_write2_b32 v164, v5, v6 offset0:80 offset1:100
	ds_write2_b32 v164, v7, v18 offset0:120 offset1:140
	ds_write2_b32 v164, v19, v20 offset0:160 offset1:180
	ds_write2_b32 v164, v12, v13 offset0:200 offset1:220
	v_add_u32_e32 v2, 0x200, v164
	ds_write2_b32 v2, v14, v15 offset0:112 offset1:132
	v_add_u32_e32 v2, 0x400, v164
	s_waitcnt lgkmcnt(7)
	v_fma_f32 v8, -v211, v16, v17
	ds_write2_b32 v2, v16, v8 offset0:24 offset1:44

;     ...
;     {
;         const int g = lane >> 4, nn = lane & 15, cb = 16 * wid + nn;
; #pragma unroll
;         for (int blk = 0; blk < 4; ++blk) {
;             f32x4 acc;
; #pragma unroll
;             for (int r = 0; r < 4; ++r) acc[r] = rhs[(16 * blk + 4 * g + r) * 132 + cb];
; #pragma unroll
;             for (int k4 = 0; k4 < 4 * blk; ++k4) { const float av = -Lm[(4 * k4 + g) * 68 + 16 * blk + nn], bv = rhs[(4 * k4 + g) * 132 + cb];
;                 acc = __builtin_amdgcn_mfma_f32_16x16x4f32(av, bv, acc, 0, 0, 0); }
; #pragma unroll
;             for (int r = 0; r < 4; ++r) rhs[(16 * blk + 4 * g + r) * 132 + cb] = acc[r];
;             f32x4 xs = (f32x4){0.f, 0.f, 0.f, 0.f};
; #pragma unroll
;             for (int k4 = 0; k4 < 4; ++k4) { const float av = DIV[blk * 320 + nn * 20 + 4 * k4 + g], bv = rhs[(16 * blk + 4 * k4 + g) * 132 + cb];
;                 xs = __builtin_amdgcn_mfma_f32_16x16x4f32(av, bv, xs, 0, 0, 0); }
; #pragma unroll
;             for (int r = 0; r < 4; ++r) rhs[(16 * blk + 4 * g + r) * 132 + cb] = xs[r];
;         }
;     }
.LBB0_533:
	s_waitcnt lgkmcnt(0)
	s_barrier
	s_and_b64 vcc, exec, s[96:97]
	s_cbranch_vccz .LBB0_433
	ds_read_b32 v196, v184 offset:52288
	ds_read_b32 v197, v184 offset:53376
	ds_read_b32 v198, v184 offset:54464
	ds_read_b32 v199, v184 offset:55552
	ds_read_b32 v204, v184 offset:52352
	ds_read_b32 v205, v184 offset:53440
	ds_read_b32 v206, v184 offset:54528
	ds_read_b32 v207, v184 offset:55616
	ds_read_b32 v208, v184 offset:56704
	ds_read_b32 v209, v184 offset:57792
	ds_read_b32 v210, v184 offset:58880
	ds_read_b32 v211, v184 offset:59968
	ds_read_b32 v212, v184 offset:52416
	ds_read_b32 v213, v184 offset:53504
	ds_read_b32 v214, v184 offset:54592
	ds_read_b32 v215, v184 offset:55680
	ds_read_b32 v216, v184 offset:56768
	ds_read_b32 v217, v184 offset:57856
	ds_read_b32 v218, v184 offset:58944
	ds_read_b32 v219, v184 offset:60032
	ds_read_b32 v220, v184 offset:61120
	ds_read_b32 v221, v184 offset:62208
	ds_read_b32 v222, v184 offset:63296
	ds_read_b32 v223, v184 offset:64384
	ds_read2_b32 v[6:7], v168 offset1:4
	ds_read_b32 v2, v182
	v_add_u32_e32 v9, 0x2400, v183
	v_add_u32_e32 v12, 0x400, v168
	v_add_u32_e32 v16, 0x800, v168
	v_readlane_b32 s42, v247, 35
	s_waitcnt lgkmcnt(0)
	v_mfma_f32_16x16x4_f32 v[2:5], v6, v2, 0
	ds_read_b32 v6, v182 offset:2112
	v_readlane_b32 s43, v247, 36
	s_andn2_b64 vcc, exec, s[42:43]
	s_waitcnt lgkmcnt(0)
	v_mfma_f32_16x16x4_f32 v[2:5], v7, v6, v[2:5]
	ds_read2_b32 v[6:7], v168 offset0:8 offset1:12
	ds_read_b32 v8, v182 offset:4224
	s_waitcnt lgkmcnt(0)
	v_mfma_f32_16x16x4_f32 v[2:5], v6, v8, v[2:5]
	ds_read_b32 v6, v182 offset:6336
	v_add_u32_e32 v8, 0x400, v183
	s_waitcnt lgkmcnt(0)
	v_mfma_f32_16x16x4_f32 v[2:5], v7, v6, v[2:5]
	s_nop 9
	ds_write2_b32 v183, v2, v3 offset1:132
	ds_write2_b32 v8, v4, v5 offset0:8 offset1:140
	v_add_u32_e32 v2, 0x2000, v183
	ds_read2_b32 v[4:5], v9 offset0:72 offset1:204
	ds_read2_b32 v[2:3], v2 offset0:64 offset1:196
	ds_read_b32 v8, v182
	s_waitcnt lgkmcnt(0)
	v_xor_b32_e32 v6, 0x80000000, v196
	s_waitcnt lgkmcnt(0)
	s_nop 0
	v_mfma_f32_16x16x4_f32 v[2:5], v6, v8, v[2:5]
	ds_read_b32 v9, v182 offset:2112
	s_waitcnt lgkmcnt(0)
	v_xor_b32_e32 v6, 0x80000000, v197
	s_waitcnt lgkmcnt(0)
	s_nop 0
	v_mfma_f32_16x16x4_f32 v[2:5], v6, v9, v[2:5]
	ds_read_b32 v10, v182 offset:4224
	s_waitcnt lgkmcnt(0)
	v_xor_b32_e32 v6, 0x80000000, v198
	s_waitcnt lgkmcnt(0)
	s_nop 0
	v_mfma_f32_16x16x4_f32 v[2:5], v6, v10, v[2:5]
	ds_read_b32 v11, v182 offset:6336
	s_waitcnt lgkmcnt(0)
	v_xor_b32_e32 v6, 0x80000000, v199
	s_waitcnt lgkmcnt(0)
	s_nop 0
	v_mfma_f32_16x16x4_f32 v[2:5], v6, v11, v[2:5]
	s_nop 9
	ds_write_b32 v183, v2 offset:8448
	ds_write_b32 v183, v3 offset:8976
	ds_write_b32 v183, v4 offset:9504
	ds_write_b32 v183, v5 offset:10032
	ds_read2_b32 v[6:7], v12 offset0:64 offset1:68
	ds_read_b32 v2, v182 offset:8448
	s_waitcnt lgkmcnt(0)
	v_mfma_f32_16x16x4_f32 v[2:5], v6, v2, 0
	ds_read_b32 v6, v182 offset:10560
	s_waitcnt lgkmcnt(0)
	v_mfma_f32_16x16x4_f32 v[2:5], v7, v6, v[2:5]
	ds_read2_b32 v[6:7], v12 offset0:72 offset1:76
	ds_read_b32 v12, v182 offset:12672
	s_waitcnt lgkmcnt(0)
	v_mfma_f32_16x16x4_f32 v[2:5], v6, v12, v[2:5]
	ds_read_b32 v6, v182 offset:14784
	s_waitcnt lgkmcnt(0)
	v_mfma_f32_16x16x4_f32 v[2:5], v7, v6, v[2:5]
	s_nop 9
	ds_write_b32 v183, v2 offset:8448
	ds_write_b32 v183, v3 offset:8976
	ds_write_b32 v183, v4 offset:9504
	ds_write_b32 v183, v5 offset:10032
	v_add_u32_e32 v2, 0x4200, v183
	v_add_u32_e32 v4, 0x4600, v183
	ds_read2_b32 v[2:3], v2 offset1:132
	ds_read2_b32 v[4:5], v4 offset0:8 offset1:140
	s_waitcnt lgkmcnt(0)
	v_xor_b32_e32 v6, 0x80000000, v204
	s_waitcnt lgkmcnt(0)
	s_nop 0
	v_mfma_f32_16x16x4_f32 v[2:5], v6, v8, v[2:5]
	s_waitcnt lgkmcnt(0)
	v_xor_b32_e32 v6, 0x80000000, v205
	s_nop 1
	v_mfma_f32_16x16x4_f32 v[2:5], v6, v9, v[2:5]
	s_waitcnt lgkmcnt(0)
	v_xor_b32_e32 v6, 0x80000000, v206
	s_nop 1
	v_mfma_f32_16x16x4_f32 v[2:5], v6, v10, v[2:5]
	s_waitcnt lgkmcnt(0)
	v_xor_b32_e32 v6, 0x80000000, v207
	s_nop 1
	v_mfma_f32_16x16x4_f32 v[2:5], v6, v11, v[2:5]
	ds_read_b32 v12, v182 offset:8448
	s_waitcnt lgkmcnt(0)
	v_xor_b32_e32 v6, 0x80000000, v208
	s_waitcnt lgkmcnt(0)
	s_nop 0
	v_mfma_f32_16x16x4_f32 v[2:5], v6, v12, v[2:5]
	ds_read_b32 v13, v182 offset:10560
	s_waitcnt lgkmcnt(0)
	v_xor_b32_e32 v6, 0x80000000, v209
	s_waitcnt lgkmcnt(0)
	s_nop 0
	v_mfma_f32_16x16x4_f32 v[2:5], v6, v13, v[2:5]
	ds_read_b32 v14, v182 offset:12672
	s_waitcnt lgkmcnt(0)
	v_xor_b32_e32 v6, 0x80000000, v210
	s_waitcnt lgkmcnt(0)
	s_nop 0
	v_mfma_f32_16x16x4_f32 v[2:5], v6, v14, v[2:5]
	ds_read_b32 v15, v182 offset:14784
	s_waitcnt lgkmcnt(0)
	v_xor_b32_e32 v6, 0x80000000, v211
	s_waitcnt lgkmcnt(0)
	s_nop 0
	v_mfma_f32_16x16x4_f32 v[2:5], v6, v15, v[2:5]
	s_nop 9
	ds_write_b32 v183, v2 offset:16896
	ds_write_b32 v183, v3 offset:17424
	ds_write_b32 v183, v4 offset:17952
	ds_write_b32 v183, v5 offset:18480
	ds_read2_b32 v[6:7], v16 offset0:128 offset1:132
	ds_read_b32 v2, v182 offset:16896
	s_waitcnt lgkmcnt(0)
; #define LAS __attribute__((address_space(3)))
; DI unsigned pk2(float lo, float hi) { typedef __bf16 b2 __attribute__((ext_vector_type(2))); f32x2 v = {lo, hi}; b2 b = __builtin_convertvector(v, b2); return __builtin_bit_cast(unsigned, b); }
; #define LBAR() do { asm volatile("s_waitcnt lgkmcnt(0)" ::: "memory"); __builtin_amdgcn_s_barrier(); asm volatile("" ::: "memory"); } while (0)
; DI int crow(int r, int hi) { return (r & 3) + 8 * (r >> 2) + 4 * hi; }
;     ...
;             for (int r = 0; r < 4; ++r) acc[r] = rhs[(16 * blk + 4 * g + r) * 132 + cb];
; #pragma unroll
;             for (int k4 = 0; k4 < 4 * blk; ++k4) { const float av = -Lm[(4 * k4 + g) * 68 + 16 * blk + nn], bv = rhs[(4 * k4 + g) * 132 + cb];
;                 acc = __builtin_amdgcn_mfma_f32_16x16x4f32(av, bv, acc, 0, 0, 0); }
; #pragma unroll
;             for (int r = 0; r < 4; ++r) rhs[(16 * blk + 4 * g + r) * 132 + cb] = acc[r];
;             f32x4 xs = (f32x4){0.f, 0.f, 0.f, 0.f};
; #pragma unroll
;             for (int k4 = 0; k4 < 4; ++k4) { const float av = DIV[blk * 320 + nn * 20 + 4 * k4 + g], bv = rhs[(16 * blk + 4 * k4 + g) * 132 + cb];
;                 xs = __builtin_amdgcn_mfma_f32_16x16x4f32(av, bv, xs, 0, 0, 0); }
; #pragma unroll
;             for (int r = 0; r < 4; ++r) rhs[(16 * blk + 4 * g + r) * 132 + cb] = xs[r];
;         }
;     }
;     LBAR();
;     if (stop == 5) return;
;     {
;         const int idx = tid; const int mt = idx >> 8, ks = (idx >> 6) & 3, ln = idx & 63, i = 32 * mt + (ln & 31), hh = ln >> 5, k0 = 16 * ks + 4 * hh;
;         const f32x4 a = *(const LAS f32x4*)(rhs + i * 132 + 64 + k0), bq = *(const LAS f32x4*)(rhs + i * 132 + 64 + k0 + 8);
;         u32x4 w; w.x = pk2(-a[0], -a[1]); w.y = pk2(-a[2], -a[3]); w.z = pk2(-bq[0], -bq[1]); w.w = pk2(-bq[2], -bq[3]);
;         *(u32x4*)(gout + idx * 16) = w;
;         const int tile = idx >> 7, ln2 = (idx >> 1) & 63, half = idx & 1, ct = tile >> 1, vt = tile & 1, vcol = 32 * vt + (ln2 & 31), h2 = ln2 >> 5;
;         float v[8];
; #pragma unroll
;         for (int e = 0; e < 8; ++e) { const int r = 8 * half + e; v[e] = rhs[(32 * ct + crow(r, h2)) * 132 + vcol]; }
;         u32x4 wu; wu.x = pk2(v[0], v[1]); wu.y = pk2(v[2], v[3]); wu.z = pk2(v[4], v[5]); wu.w = pk2(v[6], v[7]);
;         *(u32x4*)(gout + 4 * 8192 + idx * 16) = wu;
;         if (tid == 0) GL[item] = expf(glog);
	v_mfma_f32_16x16x4_f32 v[2:5], v6, v2, 0
	ds_read_b32 v6, v182 offset:19008
	s_waitcnt lgkmcnt(0)
	v_mfma_f32_16x16x4_f32 v[2:5], v7, v6, v[2:5]
	ds_read2_b32 v[6:7], v16 offset0:136 offset1:140
	ds_read_b32 v16, v182 offset:21120
	s_waitcnt lgkmcnt(0)
	v_mfma_f32_16x16x4_f32 v[2:5], v6, v16, v[2:5]
	ds_read_b32 v6, v182 offset:23232
	s_waitcnt lgkmcnt(0)
	v_mfma_f32_16x16x4_f32 v[2:5], v7, v6, v[2:5]
	s_nop 9
	ds_write_b32 v183, v2 offset:16896
	ds_write_b32 v183, v3 offset:17424
	ds_write_b32 v183, v4 offset:17952
	ds_write_b32 v183, v5 offset:18480
	v_add_u32_e32 v2, 0x6200, v183
	v_add_u32_e32 v4, 0x6600, v183
	ds_read2_b32 v[2:3], v2 offset0:64 offset1:196
	ds_read2_b32 v[4:5], v4 offset0:72 offset1:204
	s_waitcnt lgkmcnt(0)
	v_xor_b32_e32 v6, 0x80000000, v212
	s_waitcnt lgkmcnt(0)
	s_nop 0
	v_mfma_f32_16x16x4_f32 v[2:5], v6, v8, v[2:5]
	v_add_u32_e32 v8, 0xc00, v168
	s_waitcnt lgkmcnt(0)
	v_xor_b32_e32 v6, 0x80000000, v213
	s_nop 1
	v_mfma_f32_16x16x4_f32 v[2:5], v6, v9, v[2:5]
	s_waitcnt lgkmcnt(0)
	v_xor_b32_e32 v6, 0x80000000, v214
	s_nop 1
	v_mfma_f32_16x16x4_f32 v[2:5], v6, v10, v[2:5]
	s_waitcnt lgkmcnt(0)
	v_xor_b32_e32 v6, 0x80000000, v215
	s_nop 1
	v_mfma_f32_16x16x4_f32 v[2:5], v6, v11, v[2:5]
	s_waitcnt lgkmcnt(0)
	v_xor_b32_e32 v6, 0x80000000, v216
	s_nop 1
	v_mfma_f32_16x16x4_f32 v[2:5], v6, v12, v[2:5]
	s_waitcnt lgkmcnt(0)
	v_xor_b32_e32 v6, 0x80000000, v217
	s_nop 1
	v_mfma_f32_16x16x4_f32 v[2:5], v6, v13, v[2:5]
	s_waitcnt lgkmcnt(0)
	v_xor_b32_e32 v6, 0x80000000, v218
	s_nop 1
	v_mfma_f32_16x16x4_f32 v[2:5], v6, v14, v[2:5]
	s_waitcnt lgkmcnt(0)
	v_xor_b32_e32 v6, 0x80000000, v219
	s_nop 1
	v_mfma_f32_16x16x4_f32 v[2:5], v6, v15, v[2:5]
	ds_read_b32 v7, v182 offset:16896
	s_waitcnt lgkmcnt(0)
	v_xor_b32_e32 v6, 0x80000000, v220
	s_waitcnt lgkmcnt(0)
	s_nop 0
	v_mfma_f32_16x16x4_f32 v[2:5], v6, v7, v[2:5]
	ds_read_b32 v7, v182 offset:19008
	s_waitcnt lgkmcnt(0)
	v_xor_b32_e32 v6, 0x80000000, v221
	s_waitcnt lgkmcnt(0)
	s_nop 0
	v_mfma_f32_16x16x4_f32 v[2:5], v6, v7, v[2:5]
	ds_read_b32 v7, v182 offset:21120
	s_waitcnt lgkmcnt(0)
	v_xor_b32_e32 v6, 0x80000000, v222
	s_waitcnt lgkmcnt(0)
	s_nop 0
	v_mfma_f32_16x16x4_f32 v[2:5], v6, v7, v[2:5]
	ds_read_b32 v7, v182 offset:23232
	s_waitcnt lgkmcnt(0)
	v_xor_b32_e32 v6, 0x80000000, v223
	s_waitcnt lgkmcnt(0)
	s_nop 0
	v_mfma_f32_16x16x4_f32 v[2:5], v6, v7, v[2:5]
	s_nop 9
	ds_write_b32 v183, v2 offset:25344
	ds_write_b32 v183, v3 offset:25872
	ds_write_b32 v183, v4 offset:26400
	ds_write_b32 v183, v5 offset:26928
	ds_read2_b32 v[6:7], v8 offset0:192 offset1:196
	ds_read_b32 v2, v182 offset:25344
	s_waitcnt lgkmcnt(0)
	v_mfma_f32_16x16x4_f32 v[2:5], v6, v2, 0
	ds_read_b32 v6, v182 offset:27456
	s_waitcnt lgkmcnt(0)
	v_mfma_f32_16x16x4_f32 v[2:5], v7, v6, v[2:5]
	ds_read2_b32 v[6:7], v8 offset0:200 offset1:204
	ds_read_b32 v8, v182 offset:29568
	s_waitcnt lgkmcnt(0)
	v_mfma_f32_16x16x4_f32 v[2:5], v6, v8, v[2:5]
	ds_read_b32 v6, v182 offset:31680
	s_waitcnt lgkmcnt(0)
	v_mfma_f32_16x16x4_f32 v[2:5], v7, v6, v[2:5]
	s_nop 9
	ds_write_b32 v183, v2 offset:25344
	ds_write_b32 v183, v3 offset:25872
	ds_write_b32 v183, v4 offset:26400
	ds_write_b32 v183, v5 offset:26928
	s_waitcnt lgkmcnt(0)
	s_barrier
	s_cbranch_vccnz .LBB0_433
	ds_read_b128 v[2:5], v169 offset:256
	ds_read_b128 v[6:9], v169 offset:288
	s_waitcnt lgkmcnt(1)
	v_xor_b32_e32 v3, 0x80000000, v3
	v_xor_b32_e32 v2, 0x80000000, v2
	v_xor_b32_e32 v4, 0x80000000, v4
	v_xor_b32_e32 v5, 0x80000000, v5
	v_cvt_pk_bf16_f32 v2, v2, v3
	v_cvt_pk_bf16_f32 v3, v4, v5
	s_waitcnt lgkmcnt(0)
	v_xor_b32_e32 v4, 0x80000000, v7
	v_xor_b32_e32 v5, 0x80000000, v6
	v_cvt_pk_bf16_f32 v4, v5, v4
	v_xor_b32_e32 v5, 0x80000000, v8
	v_xor_b32_e32 v6, 0x80000000, v9
	ds_read_b32 v8, v185
	ds_read_b32 v9, v186
	ds_read_b32 v10, v187
	ds_read_b32 v11, v188
	ds_read_b32 v12, v189
	ds_read_b32 v13, v190
	ds_read_b32 v14, v191
	ds_read_b32 v15, v192
	v_cvt_pk_bf16_f32 v5, v5, v6
	v_lshl_add_u64 v[6:7], s[72:73], 0, v[90:91]
	global_store_dwordx4 v[6:7], v[2:5], off
	v_add_co_u32_e32 v6, vcc, 0x8000, v6
	s_waitcnt lgkmcnt(6)
	v_cvt_pk_bf16_f32 v2, v8, v9
	s_waitcnt lgkmcnt(4)
	v_cvt_pk_bf16_f32 v3, v10, v11
	s_waitcnt lgkmcnt(2)
	v_cvt_pk_bf16_f32 v4, v12, v13
	s_waitcnt lgkmcnt(0)
	v_cvt_pk_bf16_f32 v5, v14, v15
	v_addc_co_u32_e32 v7, vcc, 0, v7, vcc
	global_store_dwordx4 v[6:7], v[2:5], off
	s_and_saveexec_b64 s[42:43], s[86:87]
	s_cbranch_execz .LBB0_432
	v_mul_f32_e32 v2, 0x3fb8aa3b, v82
	v_rndne_f32_e32 v3, v2
	v_sub_f32_e32 v4, v2, v3
	v_fma_f32 v2, v82, s27, -v2
	v_fmac_f32_e32 v2, 0x32a5705f, v82
	v_add_f32_e32 v2, v4, v2
	v_exp_f32_e32 v2, v2
	v_cvt_i32_f32_e32 v3, v3
	s_lshl_b64 s[2:3], s[2:3], 2
	v_readlane_b32 s33, v247, 33
	v_cmp_ngt_f32_e32 vcc, s95, v82
	v_ldexp_f32 v2, v2, v3
	s_add_u32 s2, s33, s2
	v_readlane_b32 s33, v247, 34
	v_cndmask_b32_e32 v2, 0, v2, vcc
	v_cmp_nlt_f32_e32 vcc, s16, v82
	s_addc_u32 s3, s33, s3
	s_nop 0
	v_cndmask_b32_e32 v2, v193, v2, vcc
	global_store_dword v83, v2, s[2:3]
	s_branch .LBB0_432

; #define LBAR() do { asm volatile("s_waitcnt lgkmcnt(0)" ::: "memory"); __builtin_amdgcn_s_barrier(); asm volatile("" ::: "memory"); } while (0)
; #define GZLOAD(ZR, chunk) do { const bf16_t* zp_ = proj + (size_t)(b * SEQ + (chunk) * 64 + lane) * NINP + C_GZ + h * 64 + 32 * hc; \
;         _Pragma("unroll") for (int k = 0; k < 4; ++k) ZR[k] = *(const u32x4*)(zp_ + 8 * k); } while (0)
; DI void gdn_scan(const Ctx& c, int bh, const unsigned char* gbase, const float* GL, bf16_t* proj, const float* normw) {
;     ...
;         for (int n = 0; n < 64; n += 2) {
;             LBAR(); if (n > 0) GHELP(n - 1, zB); GZLOAD(zB, n + 1);
;             LBAR(); GHELP(n, zA); { const int nx = n + 2 < 64 ? n + 2 : 63; GZLOAD(zA, nx); }
.LBB0_861:
	s_waitcnt lgkmcnt(0)
	s_barrier
	s_waitcnt vmcnt(0)
	v_add_u32_e32 v3, 0x20600, v135
	ds_read_b128 v[48:51], v3
	ds_read_b128 v[36:39], v3 offset:16
	ds_read_b128 v[28:31], v3 offset:32
	ds_read_b128 v[16:19], v3 offset:48
	ds_read_b128 v[52:55], v3 offset:64
	ds_read_b128 v[40:43], v3 offset:80
	ds_read_b128 v[32:35], v3 offset:96
	ds_read_b128 v[24:27], v3 offset:112
	s_waitcnt lgkmcnt(6)
	v_and_b32_e32 v47, 0xffff0000, v36
	v_and_b32_e32 v46, 0xffff0000, v48
	v_lshlrev_b32_e32 v45, 16, v36
	v_lshlrev_b32_e32 v44, 16, v48
	v_pk_mul_f32 v[46:47], v[46:47], v[46:47]
	s_waitcnt lgkmcnt(4)
	v_and_b32_e32 v57, 0xffff0000, v16
	v_pk_fma_f32 v[44:45], v[44:45], v[44:45], v[46:47]
	v_lshlrev_b32_e32 v47, 16, v37
	v_lshlrev_b32_e32 v46, 16, v49
	v_pk_fma_f32 v[44:45], v[46:47], v[46:47], v[44:45]
	v_and_b32_e32 v47, 0xffff0000, v37
	v_and_b32_e32 v46, 0xffff0000, v49
	v_pk_fma_f32 v[44:45], v[46:47], v[46:47], v[44:45]
	v_lshlrev_b32_e32 v47, 16, v38
	v_lshlrev_b32_e32 v46, 16, v50
	v_pk_fma_f32 v[44:45], v[46:47], v[46:47], v[44:45]
	v_and_b32_e32 v47, 0xffff0000, v38
	v_and_b32_e32 v46, 0xffff0000, v50
	v_pk_fma_f32 v[44:45], v[46:47], v[46:47], v[44:45]
	v_lshlrev_b32_e32 v47, 16, v39
	v_lshlrev_b32_e32 v46, 16, v51
	v_pk_fma_f32 v[44:45], v[46:47], v[46:47], v[44:45]
	v_and_b32_e32 v47, 0xffff0000, v39
	v_and_b32_e32 v46, 0xffff0000, v51
	v_and_b32_e32 v56, 0xffff0000, v28
	v_pk_fma_f32 v[44:45], v[46:47], v[46:47], v[44:45]
	v_lshlrev_b32_e32 v47, 16, v16
	v_lshlrev_b32_e32 v46, 16, v28
	v_pk_mul_f32 v[56:57], v[56:57], v[56:57]
	s_waitcnt lgkmcnt(2)
	v_and_b32_e32 v59, 0xffff0000, v40
	v_pk_fma_f32 v[46:47], v[46:47], v[46:47], v[56:57]
	v_lshlrev_b32_e32 v57, 16, v17
	v_lshlrev_b32_e32 v56, 16, v29
	v_pk_fma_f32 v[46:47], v[56:57], v[56:57], v[46:47]
	v_and_b32_e32 v57, 0xffff0000, v17
	v_and_b32_e32 v56, 0xffff0000, v29
	v_pk_fma_f32 v[46:47], v[56:57], v[56:57], v[46:47]
	v_lshlrev_b32_e32 v57, 16, v18
	v_lshlrev_b32_e32 v56, 16, v30
	v_pk_fma_f32 v[46:47], v[56:57], v[56:57], v[46:47]
	v_and_b32_e32 v57, 0xffff0000, v18
	v_and_b32_e32 v56, 0xffff0000, v30
	v_pk_fma_f32 v[46:47], v[56:57], v[56:57], v[46:47]
	v_lshlrev_b32_e32 v57, 16, v19
	v_lshlrev_b32_e32 v56, 16, v31
	v_pk_fma_f32 v[46:47], v[56:57], v[56:57], v[46:47]
	v_and_b32_e32 v57, 0xffff0000, v19
	v_and_b32_e32 v56, 0xffff0000, v31
	v_and_b32_e32 v58, 0xffff0000, v52
	v_pk_fma_f32 v[46:47], v[56:57], v[56:57], v[46:47]
	v_lshlrev_b32_e32 v57, 16, v40
	v_lshlrev_b32_e32 v56, 16, v52
	v_pk_mul_f32 v[58:59], v[58:59], v[58:59]
	s_waitcnt lgkmcnt(0)
	v_and_b32_e32 v61, 0xffff0000, v24
	v_pk_fma_f32 v[56:57], v[56:57], v[56:57], v[58:59]
	v_lshlrev_b32_e32 v59, 16, v41
	v_lshlrev_b32_e32 v58, 16, v53
	v_pk_fma_f32 v[56:57], v[58:59], v[58:59], v[56:57]
	v_and_b32_e32 v59, 0xffff0000, v41
	v_and_b32_e32 v58, 0xffff0000, v53
	v_pk_fma_f32 v[56:57], v[58:59], v[58:59], v[56:57]
	v_lshlrev_b32_e32 v59, 16, v42
	v_lshlrev_b32_e32 v58, 16, v54
	v_pk_fma_f32 v[56:57], v[58:59], v[58:59], v[56:57]
	v_and_b32_e32 v59, 0xffff0000, v42
	v_and_b32_e32 v58, 0xffff0000, v54
	v_pk_fma_f32 v[56:57], v[58:59], v[58:59], v[56:57]
	v_lshlrev_b32_e32 v59, 16, v43
	v_lshlrev_b32_e32 v58, 16, v55
	v_pk_fma_f32 v[56:57], v[58:59], v[58:59], v[56:57]
	v_and_b32_e32 v59, 0xffff0000, v43
	v_and_b32_e32 v58, 0xffff0000, v55
	v_and_b32_e32 v60, 0xffff0000, v32
	v_pk_fma_f32 v[56:57], v[58:59], v[58:59], v[56:57]
	v_lshlrev_b32_e32 v59, 16, v24
	v_lshlrev_b32_e32 v58, 16, v32
	v_pk_mul_f32 v[60:61], v[60:61], v[60:61]
	v_add_f32_e32 v3, v44, v45
	v_pk_fma_f32 v[58:59], v[58:59], v[58:59], v[60:61]
	v_lshlrev_b32_e32 v61, 16, v25
	v_lshlrev_b32_e32 v60, 16, v33
	v_pk_fma_f32 v[58:59], v[60:61], v[60:61], v[58:59]
	v_and_b32_e32 v61, 0xffff0000, v25
	v_and_b32_e32 v60, 0xffff0000, v33
	v_pk_fma_f32 v[58:59], v[60:61], v[60:61], v[58:59]
	v_lshlrev_b32_e32 v61, 16, v26
	v_lshlrev_b32_e32 v60, 16, v34
	v_pk_fma_f32 v[58:59], v[60:61], v[60:61], v[58:59]
	v_and_b32_e32 v61, 0xffff0000, v26
	v_and_b32_e32 v60, 0xffff0000, v34
	v_add_f32_e32 v3, v3, v46
	v_pk_fma_f32 v[58:59], v[60:61], v[60:61], v[58:59]
	v_lshlrev_b32_e32 v61, 16, v27
	v_lshlrev_b32_e32 v60, 16, v35
	v_add_f32_e32 v3, v3, v47
	v_pk_fma_f32 v[58:59], v[60:61], v[60:61], v[58:59]
	v_and_b32_e32 v61, 0xffff0000, v27
	v_and_b32_e32 v60, 0xffff0000, v35
	v_add_f32_e32 v3, v3, v56
	v_pk_fma_f32 v[58:59], v[60:61], v[60:61], v[58:59]
	v_add_f32_e32 v3, v3, v57
	v_add_f32_e32 v3, v3, v58
	v_add_f32_e32 v3, v3, v59
	v_fmamk_f32 v3, v3, 0x3c800000, v134
	v_rsq_f32_e32 v46, v3
	v_or_b32_e32 v3, s12, v132
	v_mov_b64_e32 v[44:45], s[2:3]
	v_mad_i64_i32 v[44:45], s[8:9], v3, s73, v[44:45]
	v_mov_b32_e32 v3, s68
	ds_read_b128 v[56:59], v3
	ds_read_b128 v[60:63], v3 offset:16
	ds_read_b128 v[64:67], v3 offset:32
	ds_read_b128 v[68:71], v3 offset:48
	v_cndmask_b32_e64 v54, v54, v50, s[6:7]
	v_lshlrev_b32_e32 v50, 16, v20
	s_waitcnt lgkmcnt(2)
	v_pk_mul_f32 v[62:63], v[62:63], v[46:47] op_sel_hi:[1,0]
	v_pk_mul_f32 v[58:59], v[58:59], v[46:47] op_sel_hi:[1,0]
	v_pk_mul_f32 v[56:57], v[56:57], v[46:47] op_sel_hi:[1,0]
	v_pk_mul_f32 v[60:61], v[60:61], v[46:47] op_sel_hi:[1,0]
	v_cndmask_b32_e64 v47, v55, v51, s[6:7]
	v_and_b32_e32 v51, 0xffff0000, v20
	v_mul_f32_e32 v20, 0xbfb8aa3b, v50
	v_cndmask_b32_e64 v55, v53, v49, s[6:7]
	v_exp_f32_e32 v20, v20
	v_mul_f32_e32 v49, 0xbfb8aa3b, v51
	v_exp_f32_e32 v49, v49
	v_cndmask_b32_e64 v53, v52, v48, s[6:7]
	v_add_f32_e32 v20, 1.0, v20
	v_rcp_f32_e32 v48, v20
	v_add_f32_e32 v20, 1.0, v49
	v_rcp_f32_e32 v49, v20
	v_lshlrev_b32_e32 v52, 16, v53
	v_and_b32_e32 v53, 0xffff0000, v53
	v_pk_mul_f32 v[52:53], v[56:57], v[52:53]
	v_pk_mul_f32 v[48:49], v[48:49], v[50:51]
	v_lshlrev_b32_e32 v50, 16, v21
	v_and_b32_e32 v51, 0xffff0000, v21
	v_mul_f32_e32 v20, 0xbfb8aa3b, v50
	v_exp_f32_e32 v21, v20
	v_mul_f32_e32 v20, 0xbfb8aa3b, v51
	v_pk_mul_f32 v[48:49], v[48:49], v[52:53]
	v_exp_f32_e32 v52, v20
	v_add_f32_e32 v21, 1.0, v21
	v_cvt_pk_bf16_f32 v20, v48, v49
	v_rcp_f32_e32 v48, v21
	v_add_f32_e32 v21, 1.0, v52
	v_rcp_f32_e32 v49, v21
	v_lshlrev_b32_e32 v52, 16, v55
	v_and_b32_e32 v53, 0xffff0000, v55
	v_pk_mul_f32 v[52:53], v[58:59], v[52:53]
	v_pk_mul_f32 v[48:49], v[48:49], v[50:51]
	v_lshlrev_b32_e32 v50, 16, v22
	v_and_b32_e32 v51, 0xffff0000, v22
	v_mul_f32_e32 v21, 0xbfb8aa3b, v50
	v_exp_f32_e32 v22, v21
	v_mul_f32_e32 v21, 0xbfb8aa3b, v51
	v_pk_mul_f32 v[48:49], v[48:49], v[52:53]
	v_exp_f32_e32 v52, v21
	v_add_f32_e32 v22, 1.0, v22
	v_cvt_pk_bf16_f32 v21, v48, v49
	v_rcp_f32_e32 v48, v22
	v_add_f32_e32 v22, 1.0, v52
	v_rcp_f32_e32 v49, v22
	v_lshlrev_b32_e32 v52, 16, v54
	v_and_b32_e32 v53, 0xffff0000, v54
	v_pk_mul_f32 v[52:53], v[60:61], v[52:53]
	v_pk_mul_f32 v[48:49], v[48:49], v[50:51]
	v_lshlrev_b32_e32 v50, 16, v23
	v_and_b32_e32 v51, 0xffff0000, v23
	v_mul_f32_e32 v22, 0xbfb8aa3b, v50
	v_exp_f32_e32 v23, v22
	v_mul_f32_e32 v22, 0xbfb8aa3b, v51
	v_pk_mul_f32 v[48:49], v[48:49], v[52:53]
	v_exp_f32_e32 v52, v22
	v_add_f32_e32 v23, 1.0, v23
	v_cvt_pk_bf16_f32 v22, v48, v49
	v_rcp_f32_e32 v48, v23
	v_add_f32_e32 v23, 1.0, v52
	v_rcp_f32_e32 v49, v23
	v_lshlrev_b32_e32 v52, 16, v47
	v_and_b32_e32 v53, 0xffff0000, v47
	s_lshl_b32 s12, s28, 1
	v_pk_mul_f32 v[52:53], v[62:63], v[52:53]
	v_pk_mul_f32 v[48:49], v[48:49], v[50:51]
	v_lshl_add_u64 v[44:45], v[44:45], 0, s[12:13]
	v_pk_mul_f32 v[48:49], v[48:49], v[52:53]
	v_cndmask_b32_e64 v42, v42, v38, s[6:7]
	v_lshlrev_b32_e32 v38, 16, v12
	v_lshl_add_u64 v[44:45], s[20:21], 1, v[44:45]
	v_cvt_pk_bf16_f32 v23, v48, v49
	v_cndmask_b32_e64 v43, v43, v39, s[6:7]
	v_and_b32_e32 v39, 0xffff0000, v12
	v_mul_f32_e32 v12, 0xbfb8aa3b, v38
	global_store_dwordx4 v[44:45], v[20:23], off
	s_waitcnt lgkmcnt(0)
	v_pk_mul_f32 v[48:49], v[70:71], v[46:47] op_sel_hi:[1,0]
	v_pk_mul_f32 v[50:51], v[68:69], v[46:47] op_sel_hi:[1,0]
	v_pk_mul_f32 v[20:21], v[66:67], v[46:47] op_sel_hi:[1,0]
	v_pk_mul_f32 v[22:23], v[64:65], v[46:47] op_sel_hi:[1,0]
	v_cndmask_b32_e64 v47, v41, v37, s[6:7]
	v_exp_f32_e32 v12, v12
	v_mul_f32_e32 v37, 0xbfb8aa3b, v39
	v_exp_f32_e32 v37, v37
	v_cndmask_b32_e64 v41, v40, v36, s[6:7]
	v_add_f32_e32 v12, 1.0, v12
	v_rcp_f32_e32 v36, v12
	v_add_f32_e32 v12, 1.0, v37
	v_rcp_f32_e32 v37, v12
	v_lshlrev_b32_e32 v40, 16, v41
	v_and_b32_e32 v41, 0xffff0000, v41
	v_pk_mul_f32 v[22:23], v[22:23], v[40:41]
	v_pk_mul_f32 v[36:37], v[36:37], v[38:39]
	v_and_b32_e32 v39, 0xffff0000, v47
	v_pk_mul_f32 v[22:23], v[36:37], v[22:23]
	v_lshlrev_b32_e32 v36, 16, v13
	v_and_b32_e32 v37, 0xffff0000, v13
	v_mul_f32_e32 v12, 0xbfb8aa3b, v36
	v_exp_f32_e32 v13, v12
	v_mul_f32_e32 v12, 0xbfb8aa3b, v37
	v_exp_f32_e32 v38, v12
	v_cvt_pk_bf16_f32 v12, v22, v23
	v_add_f32_e32 v13, 1.0, v13
	v_rcp_f32_e32 v22, v13
	v_add_f32_e32 v13, 1.0, v38
	v_rcp_f32_e32 v23, v13
	v_lshlrev_b32_e32 v38, 16, v47
	v_pk_mul_f32 v[20:21], v[20:21], v[38:39]
	v_cndmask_b32_e64 v34, v34, v30, s[6:7]
	v_pk_mul_f32 v[22:23], v[22:23], v[36:37]
	v_and_b32_e32 v37, 0xffff0000, v42
	v_pk_mul_f32 v[20:21], v[22:23], v[20:21]
	v_lshlrev_b32_e32 v22, 16, v14
	v_and_b32_e32 v23, 0xffff0000, v14
	v_mul_f32_e32 v13, 0xbfb8aa3b, v22
	v_exp_f32_e32 v14, v13
	v_mul_f32_e32 v13, 0xbfb8aa3b, v23
	v_exp_f32_e32 v36, v13
	v_cvt_pk_bf16_f32 v13, v20, v21
	v_add_f32_e32 v14, 1.0, v14
	v_rcp_f32_e32 v20, v14
	v_add_f32_e32 v14, 1.0, v36
	v_rcp_f32_e32 v21, v14
	v_lshlrev_b32_e32 v36, 16, v42
	v_pk_mul_f32 v[36:37], v[50:51], v[36:37]
	v_lshlrev_b32_e32 v30, 16, v8
	v_pk_mul_f32 v[20:21], v[20:21], v[22:23]
	v_lshlrev_b32_e32 v22, 16, v15
	v_and_b32_e32 v23, 0xffff0000, v15
	v_mul_f32_e32 v14, 0xbfb8aa3b, v22
	v_exp_f32_e32 v15, v14
	v_mul_f32_e32 v14, 0xbfb8aa3b, v23
	v_pk_mul_f32 v[20:21], v[20:21], v[36:37]
	v_exp_f32_e32 v36, v14
	v_add_f32_e32 v15, 1.0, v15
	v_cvt_pk_bf16_f32 v14, v20, v21
	v_rcp_f32_e32 v20, v15
	v_add_f32_e32 v15, 1.0, v36
	v_rcp_f32_e32 v21, v15
	v_lshlrev_b32_e32 v36, 16, v43
	v_and_b32_e32 v37, 0xffff0000, v43
	v_pk_mul_f32 v[36:37], v[48:49], v[36:37]
	v_pk_mul_f32 v[38:39], v[20:21], v[22:23]
	ds_read_b128 v[20:23], v3 offset:64
	v_pk_mul_f32 v[40:41], v[38:39], v[36:37]
	ds_read_b128 v[36:39], v3 offset:80
	v_cvt_pk_bf16_f32 v15, v40, v41
	v_cndmask_b32_e64 v35, v35, v31, s[6:7]
	v_and_b32_e32 v31, 0xffff0000, v8
	v_mul_f32_e32 v8, 0xbfb8aa3b, v30
	global_store_dwordx4 v[44:45], v[12:15], off offset:16
	v_exp_f32_e32 v8, v8
	s_waitcnt lgkmcnt(1)
	v_pk_mul_f32 v[12:13], v[22:23], v[46:47] op_sel_hi:[1,0]
	s_waitcnt lgkmcnt(0)
	v_pk_mul_f32 v[22:23], v[36:37], v[46:47] op_sel_hi:[1,0]
	v_cndmask_b32_e64 v36, v33, v29, s[6:7]
	v_mul_f32_e32 v29, 0xbfb8aa3b, v31
	v_exp_f32_e32 v29, v29
	v_add_f32_e32 v8, 1.0, v8
	v_cndmask_b32_e64 v33, v32, v28, s[6:7]
	v_rcp_f32_e32 v28, v8
	v_add_f32_e32 v8, 1.0, v29
	v_rcp_f32_e32 v29, v8
	v_pk_mul_f32 v[14:15], v[20:21], v[46:47] op_sel_hi:[1,0]
	v_lshlrev_b32_e32 v32, 16, v33
	v_and_b32_e32 v33, 0xffff0000, v33
	v_pk_mul_f32 v[14:15], v[14:15], v[32:33]
	v_pk_mul_f32 v[28:29], v[28:29], v[30:31]
	v_and_b32_e32 v31, 0xffff0000, v36
	v_pk_mul_f32 v[14:15], v[28:29], v[14:15]
	v_lshlrev_b32_e32 v28, 16, v9
	v_and_b32_e32 v29, 0xffff0000, v9
	v_mul_f32_e32 v8, 0xbfb8aa3b, v28
	v_exp_f32_e32 v9, v8
	v_mul_f32_e32 v8, 0xbfb8aa3b, v29
	v_exp_f32_e32 v30, v8
	v_cvt_pk_bf16_f32 v8, v14, v15
	v_add_f32_e32 v9, 1.0, v9
	v_rcp_f32_e32 v14, v9
	v_add_f32_e32 v9, 1.0, v30
	v_rcp_f32_e32 v15, v9
	v_lshlrev_b32_e32 v30, 16, v36
	v_pk_mul_f32 v[12:13], v[12:13], v[30:31]
	v_pk_mul_f32 v[20:21], v[38:39], v[46:47] op_sel_hi:[1,0]
	v_pk_mul_f32 v[14:15], v[14:15], v[28:29]
	v_and_b32_e32 v29, 0xffff0000, v34
	v_pk_mul_f32 v[12:13], v[14:15], v[12:13]
	v_lshlrev_b32_e32 v14, 16, v10
	v_and_b32_e32 v15, 0xffff0000, v10
	v_mul_f32_e32 v9, 0xbfb8aa3b, v14
	v_exp_f32_e32 v10, v9
	v_mul_f32_e32 v9, 0xbfb8aa3b, v15
	v_exp_f32_e32 v28, v9
	v_cvt_pk_bf16_f32 v9, v12, v13
	v_add_f32_e32 v10, 1.0, v10
	v_rcp_f32_e32 v12, v10
	v_add_f32_e32 v10, 1.0, v28
	v_rcp_f32_e32 v13, v10
	v_lshlrev_b32_e32 v28, 16, v34
	v_pk_mul_f32 v[22:23], v[22:23], v[28:29]
	v_pk_mul_f32 v[12:13], v[12:13], v[14:15]
	v_lshlrev_b32_e32 v14, 16, v11
	v_and_b32_e32 v15, 0xffff0000, v11
	v_mul_f32_e32 v10, 0xbfb8aa3b, v14
	v_exp_f32_e32 v11, v10
	v_mul_f32_e32 v10, 0xbfb8aa3b, v15
	v_pk_mul_f32 v[12:13], v[12:13], v[22:23]
	v_exp_f32_e32 v22, v10
	v_add_f32_e32 v11, 1.0, v11
	v_cvt_pk_bf16_f32 v10, v12, v13
	v_rcp_f32_e32 v12, v11
	v_add_f32_e32 v11, 1.0, v22
	v_rcp_f32_e32 v13, v11
	v_lshlrev_b32_e32 v22, 16, v35
	v_and_b32_e32 v23, 0xffff0000, v35
	v_pk_mul_f32 v[20:21], v[20:21], v[22:23]
	v_pk_mul_f32 v[22:23], v[12:13], v[14:15]
	ds_read_b128 v[12:15], v3 offset:96
	v_pk_mul_f32 v[28:29], v[22:23], v[20:21]
	ds_read_b128 v[20:23], v3 offset:112
	v_cvt_pk_bf16_f32 v11, v28, v29
	global_store_dwordx4 v[44:45], v[8:11], off offset:32
	v_cndmask_b32_e64 v3, v27, v19, s[6:7]
	v_and_b32_e32 v19, 0xffff0000, v4
	s_waitcnt lgkmcnt(1)
	v_pk_mul_f32 v[10:11], v[12:13], v[46:47] op_sel_hi:[1,0]
	s_waitcnt lgkmcnt(0)
	v_pk_mul_f32 v[12:13], v[22:23], v[46:47] op_sel_hi:[1,0]
	v_cndmask_b32_e64 v22, v26, v18, s[6:7]
	v_lshlrev_b32_e32 v18, 16, v4
	v_mul_f32_e32 v4, 0xbfb8aa3b, v18
	v_cndmask_b32_e64 v23, v25, v17, s[6:7]
	v_exp_f32_e32 v4, v4
	v_mul_f32_e32 v17, 0xbfb8aa3b, v19
	v_exp_f32_e32 v17, v17
	v_pk_mul_f32 v[8:9], v[14:15], v[46:47] op_sel_hi:[1,0]
	v_add_f32_e32 v4, 1.0, v4
	v_pk_mul_f32 v[14:15], v[20:21], v[46:47] op_sel_hi:[1,0]
	v_cndmask_b32_e64 v21, v24, v16, s[6:7]
	v_rcp_f32_e32 v16, v4
	v_add_f32_e32 v4, 1.0, v17
	v_rcp_f32_e32 v17, v4
	v_lshlrev_b32_e32 v20, 16, v21
	v_and_b32_e32 v21, 0xffff0000, v21
	v_pk_mul_f32 v[10:11], v[10:11], v[20:21]
	v_pk_mul_f32 v[16:17], v[16:17], v[18:19]
	v_and_b32_e32 v19, 0xffff0000, v23
	v_pk_mul_f32 v[10:11], v[16:17], v[10:11]
	v_lshlrev_b32_e32 v16, 16, v5
	v_and_b32_e32 v17, 0xffff0000, v5
	v_mul_f32_e32 v4, 0xbfb8aa3b, v16
	v_exp_f32_e32 v5, v4
	v_mul_f32_e32 v4, 0xbfb8aa3b, v17
	v_exp_f32_e32 v18, v4
	v_cvt_pk_bf16_f32 v4, v10, v11
	v_add_f32_e32 v5, 1.0, v5
	v_rcp_f32_e32 v10, v5
	v_add_f32_e32 v5, 1.0, v18
	v_rcp_f32_e32 v11, v5
	v_lshlrev_b32_e32 v18, 16, v23
	v_pk_mul_f32 v[8:9], v[8:9], v[18:19]
	v_pk_mul_f32 v[10:11], v[10:11], v[16:17]
	s_nop 0
	v_pk_mul_f32 v[8:9], v[10:11], v[8:9]
	v_lshlrev_b32_e32 v10, 16, v6
	v_and_b32_e32 v11, 0xffff0000, v6
	v_mul_f32_e32 v5, 0xbfb8aa3b, v10
	v_exp_f32_e32 v6, v5
	v_mul_f32_e32 v5, 0xbfb8aa3b, v11
	v_exp_f32_e32 v16, v5
	v_cvt_pk_bf16_f32 v5, v8, v9
	v_add_f32_e32 v6, 1.0, v6
	v_rcp_f32_e32 v8, v6
	v_add_f32_e32 v6, 1.0, v16
	v_rcp_f32_e32 v9, v6
	v_lshlrev_b32_e32 v16, 16, v22
	v_and_b32_e32 v17, 0xffff0000, v22
	v_pk_mul_f32 v[14:15], v[14:15], v[16:17]
	v_pk_mul_f32 v[8:9], v[8:9], v[10:11]
	v_lshlrev_b32_e32 v10, 16, v7
	v_and_b32_e32 v11, 0xffff0000, v7
	v_mul_f32_e32 v6, 0xbfb8aa3b, v10
	v_exp_f32_e32 v7, v6
	v_mul_f32_e32 v6, 0xbfb8aa3b, v11
	v_pk_mul_f32 v[8:9], v[8:9], v[14:15]
	v_exp_f32_e32 v14, v6
	v_add_f32_e32 v7, 1.0, v7
	v_cvt_pk_bf16_f32 v6, v8, v9
	v_rcp_f32_e32 v8, v7
	v_add_f32_e32 v7, 1.0, v14
	v_rcp_f32_e32 v9, v7
	v_lshlrev_b32_e32 v14, 16, v3
	v_and_b32_e32 v15, 0xffff0000, v3
	v_pk_mul_f32 v[12:13], v[12:13], v[14:15]
	v_pk_mul_f32 v[8:9], v[8:9], v[10:11]
	s_nop 0
	v_pk_mul_f32 v[8:9], v[8:9], v[12:13]
	s_nop 0
	v_cvt_pk_bf16_f32 v7, v8, v9
	global_store_dwordx4 v[44:45], v[4:7], off offset:48

; #define LBAR() do { asm volatile("s_waitcnt lgkmcnt(0)" ::: "memory"); __builtin_amdgcn_s_barrier(); asm volatile("" ::: "memory"); } while (0)
; #define GZLOAD(ZR, chunk) do { const bf16_t* zp_ = proj + (size_t)(b * SEQ + (chunk) * 64 + lane) * NINP + C_GZ + h * 64 + 32 * hc; \
;         _Pragma("unroll") for (int k = 0; k < 4; ++k) ZR[k] = *(const u32x4*)(zp_ + 8 * k); } while (0)
; DI void gdn_scan(const Ctx& c, int bh, const unsigned char* gbase, const float* GL, bf16_t* proj, const float* normw) {
;     ...
;     if (wid >= 6) {
;         const int hc = wid - 6;
;         u32x4 zA[4], zB[4];
;         GZLOAD(zA, 0);
;         for (int n = 0; n < 64; n += 2) {
;             LBAR(); if (n > 0) GHELP(n - 1, zB); GZLOAD(zB, n + 1);
;             LBAR(); GHELP(n, zA); { const int nx = n + 2 < 64 ? n + 2 : 63; GZLOAD(zA, nx); }
.LBB0_884:
	s_nop 0
	v_add_u32_e32 v4, s33, v64
	v_mov_b64_e32 v[60:61], s[8:9]
	v_mad_i64_i32 v[20:21], s[52:53], v4, s73, v[60:61]
	global_load_dwordx4 v[4:7], v[20:21], off offset:3120
	global_load_dwordx4 v[8:11], v[20:21], off offset:3104
	global_load_dwordx4 v[12:15], v[20:21], off offset:3088
	s_nop 0
	global_load_dwordx4 v[20:23], v[20:21], off offset:3072
	s_waitcnt lgkmcnt(0)
	s_barrier
	v_add_u32_e32 v40, 0x1e200, v135
	ds_read_b128 v[66:69], v40
	ds_read_b128 v[52:55], v40 offset:16
	ds_read_b128 v[44:47], v40 offset:32
	ds_read_b128 v[36:39], v40 offset:48
	ds_read_b128 v[70:73], v40 offset:64
	ds_read_b128 v[56:59], v40 offset:80
	ds_read_b128 v[48:51], v40 offset:96
	ds_read_b128 v[40:43], v40 offset:112
	s_waitcnt lgkmcnt(0)
	v_and_b32_e32 v77, 0xffff0000, v52
	v_and_b32_e32 v76, 0xffff0000, v66
	v_lshlrev_b32_e32 v75, 16, v52
	v_lshlrev_b32_e32 v74, 16, v66
	v_pk_mul_f32 v[76:77], v[76:77], v[76:77]
	v_and_b32_e32 v79, 0xffff0000, v36
	v_pk_fma_f32 v[74:75], v[74:75], v[74:75], v[76:77]
	v_lshlrev_b32_e32 v77, 16, v53
	v_lshlrev_b32_e32 v76, 16, v67
	v_pk_fma_f32 v[74:75], v[76:77], v[76:77], v[74:75]
	v_and_b32_e32 v77, 0xffff0000, v53
	v_and_b32_e32 v76, 0xffff0000, v67
	v_pk_fma_f32 v[74:75], v[76:77], v[76:77], v[74:75]
	v_lshlrev_b32_e32 v77, 16, v54
	v_lshlrev_b32_e32 v76, 16, v68
	v_pk_fma_f32 v[74:75], v[76:77], v[76:77], v[74:75]
	v_and_b32_e32 v77, 0xffff0000, v54
	v_and_b32_e32 v76, 0xffff0000, v68
	v_pk_fma_f32 v[74:75], v[76:77], v[76:77], v[74:75]
	v_lshlrev_b32_e32 v77, 16, v55
	v_lshlrev_b32_e32 v76, 16, v69
	v_pk_fma_f32 v[74:75], v[76:77], v[76:77], v[74:75]
	v_and_b32_e32 v77, 0xffff0000, v55
	v_and_b32_e32 v76, 0xffff0000, v69
	v_and_b32_e32 v78, 0xffff0000, v44
	v_pk_fma_f32 v[74:75], v[76:77], v[76:77], v[74:75]
	v_lshlrev_b32_e32 v77, 16, v36
	v_lshlrev_b32_e32 v76, 16, v44
	v_pk_mul_f32 v[78:79], v[78:79], v[78:79]
	v_and_b32_e32 v81, 0xffff0000, v56
	v_pk_fma_f32 v[76:77], v[76:77], v[76:77], v[78:79]
	v_lshlrev_b32_e32 v79, 16, v37
	v_lshlrev_b32_e32 v78, 16, v45
	v_pk_fma_f32 v[76:77], v[78:79], v[78:79], v[76:77]
	v_and_b32_e32 v79, 0xffff0000, v37
	v_and_b32_e32 v78, 0xffff0000, v45
	v_pk_fma_f32 v[76:77], v[78:79], v[78:79], v[76:77]
	v_lshlrev_b32_e32 v79, 16, v38
	v_lshlrev_b32_e32 v78, 16, v46
	v_pk_fma_f32 v[76:77], v[78:79], v[78:79], v[76:77]
	v_and_b32_e32 v79, 0xffff0000, v38
	v_and_b32_e32 v78, 0xffff0000, v46
	v_pk_fma_f32 v[76:77], v[78:79], v[78:79], v[76:77]
	v_lshlrev_b32_e32 v79, 16, v39
	v_lshlrev_b32_e32 v78, 16, v47
	v_pk_fma_f32 v[76:77], v[78:79], v[78:79], v[76:77]
	v_and_b32_e32 v79, 0xffff0000, v39
	v_and_b32_e32 v78, 0xffff0000, v47
	v_and_b32_e32 v80, 0xffff0000, v70
	v_pk_fma_f32 v[76:77], v[78:79], v[78:79], v[76:77]
	v_lshlrev_b32_e32 v79, 16, v56
	v_lshlrev_b32_e32 v78, 16, v70
	v_pk_mul_f32 v[80:81], v[80:81], v[80:81]
	v_and_b32_e32 v83, 0xffff0000, v40
	v_pk_fma_f32 v[78:79], v[78:79], v[78:79], v[80:81]
	v_lshlrev_b32_e32 v81, 16, v57
	v_lshlrev_b32_e32 v80, 16, v71
	v_pk_fma_f32 v[78:79], v[80:81], v[80:81], v[78:79]
	v_and_b32_e32 v81, 0xffff0000, v57
	v_and_b32_e32 v80, 0xffff0000, v71
	v_pk_fma_f32 v[78:79], v[80:81], v[80:81], v[78:79]
	v_lshlrev_b32_e32 v81, 16, v58
	v_lshlrev_b32_e32 v80, 16, v72
	v_pk_fma_f32 v[78:79], v[80:81], v[80:81], v[78:79]
	v_and_b32_e32 v81, 0xffff0000, v58
	v_and_b32_e32 v80, 0xffff0000, v72
	v_pk_fma_f32 v[78:79], v[80:81], v[80:81], v[78:79]
	v_lshlrev_b32_e32 v81, 16, v59
	v_lshlrev_b32_e32 v80, 16, v73
	v_pk_fma_f32 v[78:79], v[80:81], v[80:81], v[78:79]
	v_and_b32_e32 v81, 0xffff0000, v59
	v_and_b32_e32 v80, 0xffff0000, v73
	v_and_b32_e32 v82, 0xffff0000, v48
	v_pk_fma_f32 v[78:79], v[80:81], v[80:81], v[78:79]
	v_lshlrev_b32_e32 v81, 16, v40
	v_lshlrev_b32_e32 v80, 16, v48
	v_pk_mul_f32 v[82:83], v[82:83], v[82:83]
	v_add_u32_e32 v65, s33, v63
	v_pk_fma_f32 v[80:81], v[80:81], v[80:81], v[82:83]
	v_lshlrev_b32_e32 v83, 16, v41
	v_lshlrev_b32_e32 v82, 16, v49
	v_pk_fma_f32 v[80:81], v[82:83], v[82:83], v[80:81]
	v_and_b32_e32 v83, 0xffff0000, v41
	v_and_b32_e32 v82, 0xffff0000, v49
	v_cndmask_b32_e64 v72, v72, v68, s[6:7]
	s_waitcnt vmcnt(4)
	v_lshlrev_b32_e32 v68, 16, v32
	v_pk_fma_f32 v[80:81], v[82:83], v[82:83], v[80:81]
	v_lshlrev_b32_e32 v83, 16, v42
	v_lshlrev_b32_e32 v82, 16, v50
	v_add_f32_e32 v62, v74, v75
	v_mad_i64_i32 v[60:61], s[52:53], v65, s73, v[60:61]
	v_cndmask_b32_e64 v65, v73, v69, s[6:7]
	v_and_b32_e32 v69, 0xffff0000, v32
	v_mul_f32_e32 v32, 0xbfb8aa3b, v68
	v_pk_fma_f32 v[80:81], v[82:83], v[82:83], v[80:81]
	v_and_b32_e32 v83, 0xffff0000, v42
	v_and_b32_e32 v82, 0xffff0000, v50
	v_add_f32_e32 v62, v62, v76
	v_cndmask_b32_e64 v73, v71, v67, s[6:7]
	v_exp_f32_e32 v32, v32
	v_mul_f32_e32 v67, 0xbfb8aa3b, v69
	v_pk_fma_f32 v[80:81], v[82:83], v[82:83], v[80:81]
	v_lshlrev_b32_e32 v83, 16, v43
	v_lshlrev_b32_e32 v82, 16, v51
	v_add_f32_e32 v62, v62, v77
	v_exp_f32_e32 v67, v67
	v_pk_fma_f32 v[80:81], v[82:83], v[82:83], v[80:81]
	v_and_b32_e32 v83, 0xffff0000, v43
	v_and_b32_e32 v82, 0xffff0000, v51
	v_add_f32_e32 v62, v62, v78
	v_pk_fma_f32 v[80:81], v[82:83], v[82:83], v[80:81]
	v_add_f32_e32 v62, v62, v79
	v_add_f32_e32 v62, v62, v80
	v_add_f32_e32 v32, 1.0, v32
	v_add_f32_e32 v62, v62, v81
	v_mov_b32_e32 v90, s68
	v_cndmask_b32_e64 v71, v70, v66, s[6:7]
	v_rcp_f32_e32 v66, v32
	v_add_f32_e32 v32, 1.0, v67
	v_fmamk_f32 v62, v62, 0x3c800000, v134
	ds_read_b128 v[74:77], v90
	v_rcp_f32_e32 v67, v32
	v_rsq_f32_e32 v62, v62
	v_lshlrev_b32_e32 v70, 16, v71
	v_and_b32_e32 v71, 0xffff0000, v71
	v_pk_mul_f32 v[66:67], v[66:67], v[68:69]
	v_lshlrev_b32_e32 v68, 16, v33
	s_waitcnt lgkmcnt(0)
	v_pk_mul_f32 v[74:75], v[74:75], v[62:63] op_sel_hi:[1,0]
	v_and_b32_e32 v69, 0xffff0000, v33
	v_mul_f32_e32 v32, 0xbfb8aa3b, v68
	v_pk_mul_f32 v[70:71], v[74:75], v[70:71]
	v_exp_f32_e32 v33, v32
	v_mul_f32_e32 v32, 0xbfb8aa3b, v69
	v_pk_mul_f32 v[66:67], v[66:67], v[70:71]
	v_exp_f32_e32 v70, v32
	v_add_f32_e32 v33, 1.0, v33
	v_cvt_pk_bf16_f32 v32, v66, v67
	v_rcp_f32_e32 v66, v33
	v_add_f32_e32 v33, 1.0, v70
	v_rcp_f32_e32 v67, v33
	v_pk_mul_f32 v[76:77], v[76:77], v[62:63] op_sel_hi:[1,0]
	v_lshlrev_b32_e32 v70, 16, v73
	v_and_b32_e32 v71, 0xffff0000, v73
	v_pk_mul_f32 v[66:67], v[66:67], v[68:69]
	v_lshlrev_b32_e32 v68, 16, v34
	v_and_b32_e32 v69, 0xffff0000, v34
	v_mul_f32_e32 v33, 0xbfb8aa3b, v68
	v_pk_mul_f32 v[70:71], v[76:77], v[70:71]
	v_exp_f32_e32 v34, v33
	v_mul_f32_e32 v33, 0xbfb8aa3b, v69
	v_pk_mul_f32 v[66:67], v[66:67], v[70:71]
	v_exp_f32_e32 v70, v33
	v_add_f32_e32 v34, 1.0, v34
	v_cvt_pk_bf16_f32 v33, v66, v67
	v_rcp_f32_e32 v66, v34
	v_add_f32_e32 v34, 1.0, v70
	v_rcp_f32_e32 v67, v34
	ds_read_b128 v[78:81], v90 offset:16
	ds_read_b128 v[82:85], v90 offset:32
	ds_read_b128 v[86:89], v90 offset:48
	v_lshlrev_b32_e32 v70, 16, v72
	v_and_b32_e32 v71, 0xffff0000, v72
	v_pk_mul_f32 v[66:67], v[66:67], v[68:69]
	v_lshlrev_b32_e32 v68, 16, v35
	s_waitcnt lgkmcnt(2)
	v_pk_mul_f32 v[78:79], v[78:79], v[62:63] op_sel_hi:[1,0]
	v_and_b32_e32 v69, 0xffff0000, v35
	v_mul_f32_e32 v34, 0xbfb8aa3b, v68
	v_pk_mul_f32 v[70:71], v[78:79], v[70:71]
	v_exp_f32_e32 v35, v34
	v_mul_f32_e32 v34, 0xbfb8aa3b, v69
	v_pk_mul_f32 v[66:67], v[66:67], v[70:71]
	v_exp_f32_e32 v70, v34
	v_cndmask_b32_e64 v58, v58, v54, s[6:7]
	v_lshlrev_b32_e32 v54, 16, v28
	v_add_f32_e32 v35, 1.0, v35
	v_cndmask_b32_e64 v59, v59, v55, s[6:7]
	v_and_b32_e32 v55, 0xffff0000, v28
	v_mul_f32_e32 v28, 0xbfb8aa3b, v54
	v_cvt_pk_bf16_f32 v34, v66, v67
	v_rcp_f32_e32 v66, v35
	v_add_f32_e32 v35, 1.0, v70
	v_lshlrev_b32_e32 v70, 16, v65
	v_and_b32_e32 v71, 0xffff0000, v65
	v_cndmask_b32_e64 v65, v57, v53, s[6:7]
	v_exp_f32_e32 v28, v28
	v_mul_f32_e32 v53, 0xbfb8aa3b, v55
	v_exp_f32_e32 v53, v53
	v_rcp_f32_e32 v67, v35
	v_add_f32_e32 v28, 1.0, v28
	v_pk_mul_f32 v[80:81], v[80:81], v[62:63] op_sel_hi:[1,0]
	v_cndmask_b32_e64 v57, v56, v52, s[6:7]
	v_rcp_f32_e32 v52, v28
	v_add_f32_e32 v28, 1.0, v53
	v_pk_mul_f32 v[70:71], v[80:81], v[70:71]
	v_pk_mul_f32 v[66:67], v[66:67], v[68:69]
	v_rcp_f32_e32 v53, v28
	v_pk_mul_f32 v[66:67], v[66:67], v[70:71]
	v_lshlrev_b32_e32 v56, 16, v57
	v_cvt_pk_bf16_f32 v35, v66, v67
	global_store_dwordx4 v[60:61], v[32:35], off
	v_and_b32_e32 v57, 0xffff0000, v57
	v_pk_mul_f32 v[52:53], v[52:53], v[54:55]
	s_waitcnt lgkmcnt(1)
	v_pk_mul_f32 v[34:35], v[82:83], v[62:63] op_sel_hi:[1,0]
	v_pk_mul_f32 v[32:33], v[84:85], v[62:63] op_sel_hi:[1,0]
	v_pk_mul_f32 v[34:35], v[34:35], v[56:57]
	v_and_b32_e32 v55, 0xffff0000, v65
	v_pk_mul_f32 v[34:35], v[52:53], v[34:35]
	v_lshlrev_b32_e32 v52, 16, v29
	v_and_b32_e32 v53, 0xffff0000, v29
	v_mul_f32_e32 v28, 0xbfb8aa3b, v52
	v_exp_f32_e32 v29, v28
	v_mul_f32_e32 v28, 0xbfb8aa3b, v53
	v_exp_f32_e32 v54, v28
	v_cvt_pk_bf16_f32 v28, v34, v35
	v_add_f32_e32 v29, 1.0, v29
	v_rcp_f32_e32 v34, v29
	v_add_f32_e32 v29, 1.0, v54
	v_rcp_f32_e32 v35, v29
	v_lshlrev_b32_e32 v54, 16, v65
	v_pk_mul_f32 v[32:33], v[32:33], v[54:55]
	s_waitcnt lgkmcnt(0)
	v_pk_mul_f32 v[68:69], v[86:87], v[62:63] op_sel_hi:[1,0]
	v_pk_mul_f32 v[34:35], v[34:35], v[52:53]
	v_and_b32_e32 v53, 0xffff0000, v58
	v_pk_mul_f32 v[32:33], v[34:35], v[32:33]
	v_lshlrev_b32_e32 v34, 16, v30
	v_and_b32_e32 v35, 0xffff0000, v30
	v_mul_f32_e32 v29, 0xbfb8aa3b, v34
	v_exp_f32_e32 v30, v29
	v_mul_f32_e32 v29, 0xbfb8aa3b, v35
	v_exp_f32_e32 v52, v29
	v_cvt_pk_bf16_f32 v29, v32, v33
	v_add_f32_e32 v30, 1.0, v30
	v_rcp_f32_e32 v32, v30
	v_add_f32_e32 v30, 1.0, v52
	v_rcp_f32_e32 v33, v30
	v_lshlrev_b32_e32 v52, 16, v58
	v_pk_mul_f32 v[52:53], v[68:69], v[52:53]
	v_pk_mul_f32 v[66:67], v[88:89], v[62:63] op_sel_hi:[1,0]
	v_pk_mul_f32 v[32:33], v[32:33], v[34:35]
	v_lshlrev_b32_e32 v34, 16, v31
	v_and_b32_e32 v35, 0xffff0000, v31
	v_mul_f32_e32 v30, 0xbfb8aa3b, v34
	v_exp_f32_e32 v31, v30
	v_mul_f32_e32 v30, 0xbfb8aa3b, v35
	v_pk_mul_f32 v[32:33], v[32:33], v[52:53]
	v_exp_f32_e32 v52, v30
	v_add_f32_e32 v31, 1.0, v31
	v_cvt_pk_bf16_f32 v30, v32, v33
	v_rcp_f32_e32 v32, v31
	v_add_f32_e32 v31, 1.0, v52
	v_rcp_f32_e32 v33, v31
	v_lshlrev_b32_e32 v52, 16, v59
	v_and_b32_e32 v53, 0xffff0000, v59
	v_pk_mul_f32 v[52:53], v[66:67], v[52:53]
	v_pk_mul_f32 v[54:55], v[32:33], v[34:35]
	ds_read_b128 v[32:35], v90 offset:64
	v_pk_mul_f32 v[56:57], v[54:55], v[52:53]
	ds_read_b128 v[52:55], v90 offset:80
	v_cndmask_b32_e64 v50, v50, v46, s[6:7]
	v_lshlrev_b32_e32 v46, 16, v24
	v_cvt_pk_bf16_f32 v31, v56, v57
	v_cndmask_b32_e64 v51, v51, v47, s[6:7]
	v_and_b32_e32 v47, 0xffff0000, v24
	v_mul_f32_e32 v24, 0xbfb8aa3b, v46
	global_store_dwordx4 v[60:61], v[28:31], off offset:16
	v_exp_f32_e32 v24, v24
	v_cndmask_b32_e64 v41, v41, v37, s[6:7]
	s_waitcnt lgkmcnt(1)
	v_pk_mul_f32 v[28:29], v[34:35], v[62:63] op_sel_hi:[1,0]
	s_waitcnt lgkmcnt(0)
; #define LBAR() do { asm volatile("s_waitcnt lgkmcnt(0)" ::: "memory"); __builtin_amdgcn_s_barrier(); asm volatile("" ::: "memory"); } while (0)
; #define GZLOAD(ZR, chunk) do { const bf16_t* zp_ = proj + (size_t)(b * SEQ + (chunk) * 64 + lane) * NINP + C_GZ + h * 64 + 32 * hc; \
;         _Pragma("unroll") for (int k = 0; k < 4; ++k) ZR[k] = *(const u32x4*)(zp_ + 8 * k); } while (0)
; DI void gdn_scan(const Ctx& c, int bh, const unsigned char* gbase, const float* GL, bf16_t* proj, const float* normw) {
;     ...
;     if (wid >= 6) {
;         const int hc = wid - 6;
;         u32x4 zA[4], zB[4];
;         GZLOAD(zA, 0);
;         for (int n = 0; n < 64; n += 2) {
;             LBAR(); if (n > 0) GHELP(n - 1, zB); GZLOAD(zB, n + 1);
;             LBAR(); GHELP(n, zA); { const int nx = n + 2 < 64 ? n + 2 : 63; GZLOAD(zA, nx); }
	v_pk_mul_f32 v[34:35], v[52:53], v[62:63] op_sel_hi:[1,0]
	v_cndmask_b32_e64 v52, v49, v45, s[6:7]
	v_mul_f32_e32 v45, 0xbfb8aa3b, v47
	v_exp_f32_e32 v45, v45
	v_add_f32_e32 v24, 1.0, v24
	v_cndmask_b32_e64 v49, v48, v44, s[6:7]
	v_rcp_f32_e32 v44, v24
	v_add_f32_e32 v24, 1.0, v45
	v_rcp_f32_e32 v45, v24
	v_pk_mul_f32 v[30:31], v[32:33], v[62:63] op_sel_hi:[1,0]
	v_lshlrev_b32_e32 v48, 16, v49
	v_and_b32_e32 v49, 0xffff0000, v49
	v_pk_mul_f32 v[30:31], v[30:31], v[48:49]
	v_pk_mul_f32 v[44:45], v[44:45], v[46:47]
	v_and_b32_e32 v47, 0xffff0000, v52
	v_pk_mul_f32 v[30:31], v[44:45], v[30:31]
	v_lshlrev_b32_e32 v44, 16, v25
	v_and_b32_e32 v45, 0xffff0000, v25
	v_mul_f32_e32 v24, 0xbfb8aa3b, v44
	v_exp_f32_e32 v25, v24
	v_mul_f32_e32 v24, 0xbfb8aa3b, v45
	v_exp_f32_e32 v46, v24
	v_cvt_pk_bf16_f32 v24, v30, v31
	v_add_f32_e32 v25, 1.0, v25
	v_rcp_f32_e32 v30, v25
	v_add_f32_e32 v25, 1.0, v46
	v_rcp_f32_e32 v31, v25
	v_lshlrev_b32_e32 v46, 16, v52
	v_pk_mul_f32 v[28:29], v[28:29], v[46:47]
	v_pk_mul_f32 v[32:33], v[54:55], v[62:63] op_sel_hi:[1,0]
	v_pk_mul_f32 v[30:31], v[30:31], v[44:45]
	v_and_b32_e32 v45, 0xffff0000, v50
	v_pk_mul_f32 v[28:29], v[30:31], v[28:29]
	v_lshlrev_b32_e32 v30, 16, v26
	v_and_b32_e32 v31, 0xffff0000, v26
	v_mul_f32_e32 v25, 0xbfb8aa3b, v30
	v_exp_f32_e32 v26, v25
	v_mul_f32_e32 v25, 0xbfb8aa3b, v31
	v_exp_f32_e32 v44, v25
	v_cvt_pk_bf16_f32 v25, v28, v29
	v_add_f32_e32 v26, 1.0, v26
	v_rcp_f32_e32 v28, v26
	v_add_f32_e32 v26, 1.0, v44
	v_rcp_f32_e32 v29, v26
	v_lshlrev_b32_e32 v44, 16, v50
	v_pk_mul_f32 v[34:35], v[34:35], v[44:45]
	v_cndmask_b32_e64 v37, v40, v36, s[6:7]
	v_pk_mul_f32 v[28:29], v[28:29], v[30:31]
	v_lshlrev_b32_e32 v30, 16, v27
	v_and_b32_e32 v31, 0xffff0000, v27
	v_mul_f32_e32 v26, 0xbfb8aa3b, v30
	v_exp_f32_e32 v27, v26
	v_mul_f32_e32 v26, 0xbfb8aa3b, v31
	v_pk_mul_f32 v[28:29], v[28:29], v[34:35]
	v_exp_f32_e32 v34, v26
	v_add_f32_e32 v27, 1.0, v27
	v_cvt_pk_bf16_f32 v26, v28, v29
	v_rcp_f32_e32 v28, v27
	v_add_f32_e32 v27, 1.0, v34
	v_rcp_f32_e32 v29, v27
	v_lshlrev_b32_e32 v34, 16, v51
	v_and_b32_e32 v35, 0xffff0000, v51
	v_pk_mul_f32 v[32:33], v[32:33], v[34:35]
	v_pk_mul_f32 v[34:35], v[28:29], v[30:31]
	ds_read_b128 v[28:31], v90 offset:96
	v_pk_mul_f32 v[44:45], v[34:35], v[32:33]
	ds_read_b128 v[32:35], v90 offset:112
	v_cvt_pk_bf16_f32 v27, v44, v45
	global_store_dwordx4 v[60:61], v[24:27], off offset:32
	v_lshlrev_b32_e32 v36, 16, v37
	v_and_b32_e32 v37, 0xffff0000, v37
	s_waitcnt lgkmcnt(1)
	v_pk_mul_f32 v[24:25], v[30:31], v[62:63] op_sel_hi:[1,0]
	s_waitcnt lgkmcnt(0)
	v_pk_mul_f32 v[30:31], v[32:33], v[62:63] op_sel_hi:[1,0]
	v_lshlrev_b32_e32 v32, 16, v16
	v_and_b32_e32 v33, 0xffff0000, v16
	v_mul_f32_e32 v16, 0xbfb8aa3b, v32
	v_pk_mul_f32 v[26:27], v[28:29], v[62:63] op_sel_hi:[1,0]
	v_pk_mul_f32 v[28:29], v[34:35], v[62:63] op_sel_hi:[1,0]
	v_exp_f32_e32 v16, v16
	v_mul_f32_e32 v34, 0xbfb8aa3b, v33
	v_exp_f32_e32 v35, v34
	v_pk_mul_f32 v[26:27], v[26:27], v[36:37]
	v_add_f32_e32 v16, 1.0, v16
	v_rcp_f32_e32 v34, v16
	v_add_f32_e32 v16, 1.0, v35
	v_rcp_f32_e32 v35, v16
	v_cndmask_b32_e64 v38, v42, v38, s[6:7]
	v_cndmask_b32_e64 v39, v43, v39, s[6:7]
	s_add_i32 s33, s36, 2
	v_pk_mul_f32 v[32:33], v[34:35], v[32:33]
	v_and_b32_e32 v35, 0xffff0000, v41
	v_pk_mul_f32 v[26:27], v[32:33], v[26:27]
	v_lshlrev_b32_e32 v32, 16, v17
	v_and_b32_e32 v33, 0xffff0000, v17
	v_mul_f32_e32 v16, 0xbfb8aa3b, v32
	v_exp_f32_e32 v17, v16
	v_mul_f32_e32 v16, 0xbfb8aa3b, v33
	v_exp_f32_e32 v34, v16
	v_cvt_pk_bf16_f32 v16, v26, v27
	v_add_f32_e32 v17, 1.0, v17
	v_rcp_f32_e32 v26, v17
	v_add_f32_e32 v17, 1.0, v34
	v_rcp_f32_e32 v27, v17
	v_lshlrev_b32_e32 v34, 16, v41
	v_pk_mul_f32 v[24:25], v[24:25], v[34:35]
	s_addk_i32 s29, 0x80
	v_pk_mul_f32 v[26:27], v[26:27], v[32:33]
	v_and_b32_e32 v33, 0xffff0000, v38
	v_pk_mul_f32 v[24:25], v[26:27], v[24:25]
	v_lshlrev_b32_e32 v26, 16, v18
	v_and_b32_e32 v27, 0xffff0000, v18
	v_mul_f32_e32 v17, 0xbfb8aa3b, v26
	v_exp_f32_e32 v18, v17
	v_mul_f32_e32 v17, 0xbfb8aa3b, v27
	v_exp_f32_e32 v32, v17
	v_cvt_pk_bf16_f32 v17, v24, v25
	v_add_f32_e32 v18, 1.0, v18
	v_rcp_f32_e32 v24, v18
	v_add_f32_e32 v18, 1.0, v32
	v_rcp_f32_e32 v25, v18
	v_lshlrev_b32_e32 v32, 16, v38
	v_pk_mul_f32 v[30:31], v[30:31], v[32:33]
	s_cmp_lt_u32 s36, 62
	v_pk_mul_f32 v[24:25], v[24:25], v[26:27]
	v_lshlrev_b32_e32 v26, 16, v19
	v_and_b32_e32 v27, 0xffff0000, v19
	v_mul_f32_e32 v18, 0xbfb8aa3b, v26
	v_exp_f32_e32 v19, v18
	v_mul_f32_e32 v18, 0xbfb8aa3b, v27
	v_pk_mul_f32 v[24:25], v[24:25], v[30:31]
	v_exp_f32_e32 v30, v18
	v_add_f32_e32 v19, 1.0, v19
	v_cvt_pk_bf16_f32 v18, v24, v25
	v_rcp_f32_e32 v24, v19
	v_add_f32_e32 v19, 1.0, v30
	v_rcp_f32_e32 v25, v19
	v_lshlrev_b32_e32 v30, 16, v39
	v_and_b32_e32 v31, 0xffff0000, v39
	v_pk_mul_f32 v[28:29], v[28:29], v[30:31]
	v_pk_mul_f32 v[24:25], v[24:25], v[26:27]
	s_cselect_b32 s37, s29, 0xfc0
	v_pk_mul_f32 v[24:25], v[24:25], v[28:29]
	s_cmp_gt_u32 s36, 61
	v_cvt_pk_bf16_f32 v19, v24, v25
	global_store_dwordx4 v[60:61], v[16:19], off offset:48
	s_mov_b32 s36, s33
	s_nop 0
	v_add_u32_e32 v16, s37, v63
	s_cbranch_scc1 .LBB0_861
; #define LBAR() do { asm volatile("s_waitcnt lgkmcnt(0)" ::: "memory"); __builtin_amdgcn_s_barrier(); asm volatile("" ::: "memory"); } while (0)
; #define GZLOAD(ZR, chunk) do { const bf16_t* zp_ = proj + (size_t)(b * SEQ + (chunk) * 64 + lane) * NINP + C_GZ + h * 64 + 32 * hc; \
;         _Pragma("unroll") for (int k = 0; k < 4; ++k) ZR[k] = *(const u32x4*)(zp_ + 8 * k); } while (0)
; DI void gdn_scan(const Ctx& c, int bh, const unsigned char* gbase, const float* GL, bf16_t* proj, const float* normw) {
;     ...
;     if (wid >= 6) {
;         const int hc = wid - 6;
;         u32x4 zA[4], zB[4];
;         GZLOAD(zA, 0);
;         for (int n = 0; n < 64; n += 2) {
;             LBAR(); if (n > 0) GHELP(n - 1, zB); GZLOAD(zB, n + 1);
;             LBAR(); GHELP(n, zA); { const int nx = n + 2 < 64 ? n + 2 : 63; GZLOAD(zA, nx); }
.LBB0_885:
	v_mov_b64_e32 v[18:19], s[8:9]
	v_mad_i64_i32 v[32:33], s[52:53], v16, s73, v[18:19]
	global_load_dwordx4 v[16:19], v[32:33], off offset:3120
	global_load_dwordx4 v[24:27], v[32:33], off offset:3104
	global_load_dwordx4 v[28:31], v[32:33], off offset:3088
	s_nop 0
	global_load_dwordx4 v[32:35], v[32:33], off offset:3072
	s_waitcnt lgkmcnt(0)
	s_barrier
	s_cmp_eq_u32 s29, 0
	s_mov_b32 s33, 0
	s_cbranch_scc1 .LBB0_884
	v_add_u32_e32 v40, 0x20600, v135
	ds_read_b128 v[66:69], v40
	ds_read_b128 v[52:55], v40 offset:16
	ds_read_b128 v[44:47], v40 offset:32
	ds_read_b128 v[36:39], v40 offset:48
	ds_read_b128 v[70:73], v40 offset:64
	ds_read_b128 v[56:59], v40 offset:80
	ds_read_b128 v[48:51], v40 offset:96
	ds_read_b128 v[40:43], v40 offset:112
	s_waitcnt lgkmcnt(0)
	s_waitcnt vmcnt(4)
	v_and_b32_e32 v75, 0xffff0000, v52
	v_and_b32_e32 v74, 0xffff0000, v66
	v_lshlrev_b32_e32 v61, 16, v52
	v_lshlrev_b32_e32 v60, 16, v66
	v_pk_mul_f32 v[74:75], v[74:75], v[74:75]
	v_and_b32_e32 v77, 0xffff0000, v36
	v_pk_fma_f32 v[60:61], v[60:61], v[60:61], v[74:75]
	v_lshlrev_b32_e32 v75, 16, v53
	v_lshlrev_b32_e32 v74, 16, v67
	v_pk_fma_f32 v[60:61], v[74:75], v[74:75], v[60:61]
	v_and_b32_e32 v75, 0xffff0000, v53
	v_and_b32_e32 v74, 0xffff0000, v67
	v_pk_fma_f32 v[60:61], v[74:75], v[74:75], v[60:61]
	v_lshlrev_b32_e32 v75, 16, v54
	v_lshlrev_b32_e32 v74, 16, v68
	v_pk_fma_f32 v[60:61], v[74:75], v[74:75], v[60:61]
	v_and_b32_e32 v75, 0xffff0000, v54
	v_and_b32_e32 v74, 0xffff0000, v68
	v_pk_fma_f32 v[60:61], v[74:75], v[74:75], v[60:61]
	v_lshlrev_b32_e32 v75, 16, v55
	v_lshlrev_b32_e32 v74, 16, v69
	v_pk_fma_f32 v[60:61], v[74:75], v[74:75], v[60:61]
	v_and_b32_e32 v75, 0xffff0000, v55
	v_and_b32_e32 v74, 0xffff0000, v69
	v_and_b32_e32 v76, 0xffff0000, v44
	v_pk_fma_f32 v[60:61], v[74:75], v[74:75], v[60:61]
	v_lshlrev_b32_e32 v75, 16, v36
	v_lshlrev_b32_e32 v74, 16, v44
	v_pk_mul_f32 v[76:77], v[76:77], v[76:77]
	v_and_b32_e32 v79, 0xffff0000, v56
	v_pk_fma_f32 v[74:75], v[74:75], v[74:75], v[76:77]
	v_lshlrev_b32_e32 v77, 16, v37
	v_lshlrev_b32_e32 v76, 16, v45
	v_pk_fma_f32 v[74:75], v[76:77], v[76:77], v[74:75]
	v_and_b32_e32 v77, 0xffff0000, v37
	v_and_b32_e32 v76, 0xffff0000, v45
	v_pk_fma_f32 v[74:75], v[76:77], v[76:77], v[74:75]
	v_lshlrev_b32_e32 v77, 16, v38
	v_lshlrev_b32_e32 v76, 16, v46
	v_pk_fma_f32 v[74:75], v[76:77], v[76:77], v[74:75]
	v_and_b32_e32 v77, 0xffff0000, v38
	v_and_b32_e32 v76, 0xffff0000, v46
	v_pk_fma_f32 v[74:75], v[76:77], v[76:77], v[74:75]
	v_lshlrev_b32_e32 v77, 16, v39
	v_lshlrev_b32_e32 v76, 16, v47
	v_pk_fma_f32 v[74:75], v[76:77], v[76:77], v[74:75]
	v_and_b32_e32 v77, 0xffff0000, v39
	v_and_b32_e32 v76, 0xffff0000, v47
	v_and_b32_e32 v78, 0xffff0000, v70
	v_pk_fma_f32 v[74:75], v[76:77], v[76:77], v[74:75]
	v_lshlrev_b32_e32 v77, 16, v56
	v_lshlrev_b32_e32 v76, 16, v70
	v_pk_mul_f32 v[78:79], v[78:79], v[78:79]
	v_and_b32_e32 v81, 0xffff0000, v40
	v_pk_fma_f32 v[76:77], v[76:77], v[76:77], v[78:79]
	v_lshlrev_b32_e32 v79, 16, v57
	v_lshlrev_b32_e32 v78, 16, v71
	v_pk_fma_f32 v[76:77], v[78:79], v[78:79], v[76:77]
	v_and_b32_e32 v79, 0xffff0000, v57
	v_and_b32_e32 v78, 0xffff0000, v71
	v_pk_fma_f32 v[76:77], v[78:79], v[78:79], v[76:77]
	v_lshlrev_b32_e32 v79, 16, v58
	v_lshlrev_b32_e32 v78, 16, v72
	v_pk_fma_f32 v[76:77], v[78:79], v[78:79], v[76:77]
	v_and_b32_e32 v79, 0xffff0000, v58
	v_and_b32_e32 v78, 0xffff0000, v72
	v_pk_fma_f32 v[76:77], v[78:79], v[78:79], v[76:77]
	v_lshlrev_b32_e32 v79, 16, v59
	v_lshlrev_b32_e32 v78, 16, v73
	v_pk_fma_f32 v[76:77], v[78:79], v[78:79], v[76:77]
	v_and_b32_e32 v79, 0xffff0000, v59
	v_and_b32_e32 v78, 0xffff0000, v73
	v_and_b32_e32 v80, 0xffff0000, v48
	v_pk_fma_f32 v[76:77], v[78:79], v[78:79], v[76:77]
	v_lshlrev_b32_e32 v79, 16, v40
	v_lshlrev_b32_e32 v78, 16, v48
	v_pk_mul_f32 v[80:81], v[80:81], v[80:81]
	v_add_f32_e32 v60, v60, v61
	v_pk_fma_f32 v[78:79], v[78:79], v[78:79], v[80:81]
	v_lshlrev_b32_e32 v81, 16, v41
	v_lshlrev_b32_e32 v80, 16, v49
	v_pk_fma_f32 v[78:79], v[80:81], v[80:81], v[78:79]
	v_and_b32_e32 v81, 0xffff0000, v41
	v_and_b32_e32 v80, 0xffff0000, v49
	v_pk_fma_f32 v[78:79], v[80:81], v[80:81], v[78:79]
	v_lshlrev_b32_e32 v81, 16, v42
	v_lshlrev_b32_e32 v80, 16, v50
	v_pk_fma_f32 v[78:79], v[80:81], v[80:81], v[78:79]
	v_and_b32_e32 v81, 0xffff0000, v42
	v_and_b32_e32 v80, 0xffff0000, v50
	v_add_f32_e32 v60, v60, v74
	v_pk_fma_f32 v[78:79], v[80:81], v[80:81], v[78:79]
	v_lshlrev_b32_e32 v81, 16, v43
	v_lshlrev_b32_e32 v80, 16, v51
	v_add_f32_e32 v60, v60, v75
	v_pk_fma_f32 v[78:79], v[80:81], v[80:81], v[78:79]
	v_and_b32_e32 v81, 0xffff0000, v43
	v_and_b32_e32 v80, 0xffff0000, v51
	v_add_f32_e32 v60, v60, v76
	v_pk_fma_f32 v[78:79], v[80:81], v[80:81], v[78:79]
	v_add_f32_e32 v60, v60, v77
	v_add_f32_e32 v60, v60, v78
	v_add_f32_e32 v60, v60, v79
	v_fmamk_f32 v60, v60, 0x3c800000, v134
	v_rsq_f32_e32 v62, v60
	v_add_u32_e32 v65, s29, v3
	v_mov_b64_e32 v[60:61], s[8:9]
	v_cndmask_b32_e64 v72, v72, v68, s[6:7]
	v_lshlrev_b32_e32 v68, 16, v20
	v_mad_i64_i32 v[60:61], s[52:53], v65, s73, v[60:61]
	v_cndmask_b32_e64 v65, v73, v69, s[6:7]
	v_and_b32_e32 v69, 0xffff0000, v20
	v_mul_f32_e32 v20, 0xbfb8aa3b, v68
	v_cndmask_b32_e64 v73, v71, v67, s[6:7]
	v_exp_f32_e32 v20, v20
	v_mul_f32_e32 v67, 0xbfb8aa3b, v69
	v_exp_f32_e32 v67, v67
	v_mov_b32_e32 v90, s68
	v_add_f32_e32 v20, 1.0, v20
	v_cndmask_b32_e64 v71, v70, v66, s[6:7]
	v_rcp_f32_e32 v66, v20
	v_add_f32_e32 v20, 1.0, v67
	ds_read_b128 v[74:77], v90
	v_rcp_f32_e32 v67, v20
	v_lshlrev_b32_e32 v70, 16, v71
	v_and_b32_e32 v71, 0xffff0000, v71
	ds_read_b128 v[78:81], v90 offset:16
	ds_read_b128 v[82:85], v90 offset:32
	ds_read_b128 v[86:89], v90 offset:48
	v_pk_mul_f32 v[66:67], v[66:67], v[68:69]
	v_lshlrev_b32_e32 v68, 16, v21
	s_waitcnt lgkmcnt(0)
	v_pk_mul_f32 v[74:75], v[74:75], v[62:63] op_sel_hi:[1,0]
	v_and_b32_e32 v69, 0xffff0000, v21
	v_mul_f32_e32 v20, 0xbfb8aa3b, v68
	v_pk_mul_f32 v[70:71], v[74:75], v[70:71]
	v_exp_f32_e32 v21, v20
	v_mul_f32_e32 v20, 0xbfb8aa3b, v69
	v_pk_mul_f32 v[66:67], v[66:67], v[70:71]
	v_exp_f32_e32 v70, v20
	v_add_f32_e32 v21, 1.0, v21
	v_cvt_pk_bf16_f32 v20, v66, v67
	v_rcp_f32_e32 v66, v21
	v_add_f32_e32 v21, 1.0, v70
	v_rcp_f32_e32 v67, v21
	v_pk_mul_f32 v[76:77], v[76:77], v[62:63] op_sel_hi:[1,0]
	v_lshlrev_b32_e32 v70, 16, v73
	v_and_b32_e32 v71, 0xffff0000, v73
	v_pk_mul_f32 v[66:67], v[66:67], v[68:69]
	v_lshlrev_b32_e32 v68, 16, v22
	v_and_b32_e32 v69, 0xffff0000, v22
	v_mul_f32_e32 v21, 0xbfb8aa3b, v68
	v_pk_mul_f32 v[70:71], v[76:77], v[70:71]
	v_exp_f32_e32 v22, v21
	v_mul_f32_e32 v21, 0xbfb8aa3b, v69
	v_pk_mul_f32 v[66:67], v[66:67], v[70:71]
	v_exp_f32_e32 v70, v21
	v_add_f32_e32 v22, 1.0, v22
	v_cvt_pk_bf16_f32 v21, v66, v67
	v_rcp_f32_e32 v66, v22
	v_add_f32_e32 v22, 1.0, v70
	v_rcp_f32_e32 v67, v22
	v_pk_mul_f32 v[78:79], v[78:79], v[62:63] op_sel_hi:[1,0]
	v_lshlrev_b32_e32 v70, 16, v72
	v_and_b32_e32 v71, 0xffff0000, v72
	v_pk_mul_f32 v[66:67], v[66:67], v[68:69]
	v_lshlrev_b32_e32 v68, 16, v23
	v_and_b32_e32 v69, 0xffff0000, v23
	v_mul_f32_e32 v22, 0xbfb8aa3b, v68
	v_pk_mul_f32 v[70:71], v[78:79], v[70:71]
	v_exp_f32_e32 v23, v22
	v_mul_f32_e32 v22, 0xbfb8aa3b, v69
	v_pk_mul_f32 v[66:67], v[66:67], v[70:71]
	v_exp_f32_e32 v70, v22
	v_cndmask_b32_e64 v58, v58, v54, s[6:7]
	v_lshlrev_b32_e32 v54, 16, v12
	v_add_f32_e32 v23, 1.0, v23
	v_cndmask_b32_e64 v59, v59, v55, s[6:7]
	v_and_b32_e32 v55, 0xffff0000, v12
	v_mul_f32_e32 v12, 0xbfb8aa3b, v54
	v_cvt_pk_bf16_f32 v22, v66, v67
	v_rcp_f32_e32 v66, v23
	v_add_f32_e32 v23, 1.0, v70
	v_lshlrev_b32_e32 v70, 16, v65
	v_and_b32_e32 v71, 0xffff0000, v65
	v_cndmask_b32_e64 v65, v57, v53, s[6:7]
	v_exp_f32_e32 v12, v12
	v_mul_f32_e32 v53, 0xbfb8aa3b, v55
	v_exp_f32_e32 v53, v53
	v_rcp_f32_e32 v67, v23
	v_add_f32_e32 v12, 1.0, v12
	v_pk_mul_f32 v[80:81], v[80:81], v[62:63] op_sel_hi:[1,0]
	v_cndmask_b32_e64 v57, v56, v52, s[6:7]
	v_rcp_f32_e32 v52, v12
	v_add_f32_e32 v12, 1.0, v53
	v_pk_mul_f32 v[70:71], v[80:81], v[70:71]
	v_pk_mul_f32 v[66:67], v[66:67], v[68:69]
	v_rcp_f32_e32 v53, v12
	v_pk_mul_f32 v[66:67], v[66:67], v[70:71]
	v_lshlrev_b32_e32 v56, 16, v57
	v_cvt_pk_bf16_f32 v23, v66, v67
	global_store_dwordx4 v[60:61], v[20:23], off
	v_and_b32_e32 v57, 0xffff0000, v57
	v_pk_mul_f32 v[52:53], v[52:53], v[54:55]
	v_pk_mul_f32 v[22:23], v[82:83], v[62:63] op_sel_hi:[1,0]
	v_pk_mul_f32 v[20:21], v[84:85], v[62:63] op_sel_hi:[1,0]
	v_pk_mul_f32 v[22:23], v[22:23], v[56:57]
	v_and_b32_e32 v55, 0xffff0000, v65
	v_pk_mul_f32 v[22:23], v[52:53], v[22:23]
	v_lshlrev_b32_e32 v52, 16, v13
	v_and_b32_e32 v53, 0xffff0000, v13
	v_mul_f32_e32 v12, 0xbfb8aa3b, v52
	v_exp_f32_e32 v13, v12
	v_mul_f32_e32 v12, 0xbfb8aa3b, v53
	v_exp_f32_e32 v54, v12
	v_cvt_pk_bf16_f32 v12, v22, v23
	v_add_f32_e32 v13, 1.0, v13
	v_rcp_f32_e32 v22, v13
	v_add_f32_e32 v13, 1.0, v54
	v_rcp_f32_e32 v23, v13
	v_lshlrev_b32_e32 v54, 16, v65
	v_pk_mul_f32 v[20:21], v[20:21], v[54:55]
	v_pk_mul_f32 v[68:69], v[86:87], v[62:63] op_sel_hi:[1,0]
	v_pk_mul_f32 v[22:23], v[22:23], v[52:53]
	v_and_b32_e32 v53, 0xffff0000, v58
	v_pk_mul_f32 v[20:21], v[22:23], v[20:21]
	v_lshlrev_b32_e32 v22, 16, v14
	v_and_b32_e32 v23, 0xffff0000, v14
	v_mul_f32_e32 v13, 0xbfb8aa3b, v22
	v_exp_f32_e32 v14, v13
	v_mul_f32_e32 v13, 0xbfb8aa3b, v23
	v_exp_f32_e32 v52, v13
	v_cvt_pk_bf16_f32 v13, v20, v21
	v_add_f32_e32 v14, 1.0, v14
	v_rcp_f32_e32 v20, v14
	v_add_f32_e32 v14, 1.0, v52
	v_rcp_f32_e32 v21, v14
	v_lshlrev_b32_e32 v52, 16, v58
	v_pk_mul_f32 v[52:53], v[68:69], v[52:53]
	v_pk_mul_f32 v[66:67], v[88:89], v[62:63] op_sel_hi:[1,0]
	v_pk_mul_f32 v[20:21], v[20:21], v[22:23]
	v_lshlrev_b32_e32 v22, 16, v15
	v_and_b32_e32 v23, 0xffff0000, v15
	v_mul_f32_e32 v14, 0xbfb8aa3b, v22
	v_exp_f32_e32 v15, v14
	v_mul_f32_e32 v14, 0xbfb8aa3b, v23
	v_pk_mul_f32 v[20:21], v[20:21], v[52:53]
	v_exp_f32_e32 v52, v14
	v_add_f32_e32 v15, 1.0, v15
	v_cvt_pk_bf16_f32 v14, v20, v21
	v_rcp_f32_e32 v20, v15
	v_add_f32_e32 v15, 1.0, v52
	v_rcp_f32_e32 v21, v15
	v_lshlrev_b32_e32 v52, 16, v59
	v_and_b32_e32 v53, 0xffff0000, v59
	v_pk_mul_f32 v[52:53], v[66:67], v[52:53]
	v_pk_mul_f32 v[54:55], v[20:21], v[22:23]
	ds_read_b128 v[20:23], v90 offset:64
	v_pk_mul_f32 v[56:57], v[54:55], v[52:53]
	ds_read_b128 v[52:55], v90 offset:80
	v_cndmask_b32_e64 v50, v50, v46, s[6:7]
	v_lshlrev_b32_e32 v46, 16, v8
	v_cvt_pk_bf16_f32 v15, v56, v57
	v_cndmask_b32_e64 v51, v51, v47, s[6:7]
	v_and_b32_e32 v47, 0xffff0000, v8
	v_mul_f32_e32 v8, 0xbfb8aa3b, v46
	global_store_dwordx4 v[60:61], v[12:15], off offset:16
	v_exp_f32_e32 v8, v8
	v_cndmask_b32_e64 v41, v41, v37, s[6:7]
	s_waitcnt lgkmcnt(0)
	v_pk_mul_f32 v[12:13], v[22:23], v[62:63] op_sel_hi:[1,0]
	v_pk_mul_f32 v[22:23], v[52:53], v[62:63] op_sel_hi:[1,0]
	v_cndmask_b32_e64 v52, v49, v45, s[6:7]
	v_mul_f32_e32 v45, 0xbfb8aa3b, v47
	v_exp_f32_e32 v45, v45
	v_add_f32_e32 v8, 1.0, v8
	v_cndmask_b32_e64 v49, v48, v44, s[6:7]
	v_rcp_f32_e32 v44, v8
	v_add_f32_e32 v8, 1.0, v45
	v_rcp_f32_e32 v45, v8
	v_pk_mul_f32 v[14:15], v[20:21], v[62:63] op_sel_hi:[1,0]
	v_lshlrev_b32_e32 v48, 16, v49
	v_and_b32_e32 v49, 0xffff0000, v49
	v_pk_mul_f32 v[14:15], v[14:15], v[48:49]
	v_pk_mul_f32 v[44:45], v[44:45], v[46:47]
	v_and_b32_e32 v47, 0xffff0000, v52
	v_pk_mul_f32 v[14:15], v[44:45], v[14:15]
	v_lshlrev_b32_e32 v44, 16, v9
	v_and_b32_e32 v45, 0xffff0000, v9
	v_mul_f32_e32 v8, 0xbfb8aa3b, v44
	v_exp_f32_e32 v9, v8
	v_mul_f32_e32 v8, 0xbfb8aa3b, v45
	v_exp_f32_e32 v46, v8
	v_cvt_pk_bf16_f32 v8, v14, v15
	v_add_f32_e32 v9, 1.0, v9
	v_rcp_f32_e32 v14, v9
	v_add_f32_e32 v9, 1.0, v46
	v_rcp_f32_e32 v15, v9
	v_lshlrev_b32_e32 v46, 16, v52
	v_pk_mul_f32 v[12:13], v[12:13], v[46:47]
	v_pk_mul_f32 v[20:21], v[54:55], v[62:63] op_sel_hi:[1,0]
	v_pk_mul_f32 v[14:15], v[14:15], v[44:45]
	v_and_b32_e32 v45, 0xffff0000, v50
	v_pk_mul_f32 v[12:13], v[14:15], v[12:13]
	v_lshlrev_b32_e32 v14, 16, v10
	v_and_b32_e32 v15, 0xffff0000, v10
	v_mul_f32_e32 v9, 0xbfb8aa3b, v14
	v_exp_f32_e32 v10, v9
	v_mul_f32_e32 v9, 0xbfb8aa3b, v15
	v_exp_f32_e32 v44, v9
	v_cvt_pk_bf16_f32 v9, v12, v13
	v_add_f32_e32 v10, 1.0, v10
	v_rcp_f32_e32 v12, v10
	v_add_f32_e32 v10, 1.0, v44
	v_rcp_f32_e32 v13, v10
	v_lshlrev_b32_e32 v44, 16, v50
	v_pk_mul_f32 v[22:23], v[22:23], v[44:45]
	v_cndmask_b32_e64 v37, v40, v36, s[6:7]
	v_pk_mul_f32 v[12:13], v[12:13], v[14:15]
	v_lshlrev_b32_e32 v14, 16, v11
	v_and_b32_e32 v15, 0xffff0000, v11
	v_mul_f32_e32 v10, 0xbfb8aa3b, v14
	v_exp_f32_e32 v11, v10
	v_mul_f32_e32 v10, 0xbfb8aa3b, v15
	v_pk_mul_f32 v[12:13], v[12:13], v[22:23]
	v_exp_f32_e32 v22, v10
	v_add_f32_e32 v11, 1.0, v11
	v_cvt_pk_bf16_f32 v10, v12, v13
	v_rcp_f32_e32 v12, v11
	v_add_f32_e32 v11, 1.0, v22
	v_rcp_f32_e32 v13, v11
	v_lshlrev_b32_e32 v22, 16, v51
	v_and_b32_e32 v23, 0xffff0000, v51
	v_pk_mul_f32 v[20:21], v[20:21], v[22:23]
	v_pk_mul_f32 v[22:23], v[12:13], v[14:15]
	ds_read_b128 v[12:15], v90 offset:96
	v_pk_mul_f32 v[44:45], v[22:23], v[20:21]
	ds_read_b128 v[20:23], v90 offset:112
	v_cvt_pk_bf16_f32 v11, v44, v45
	global_store_dwordx4 v[60:61], v[8:11], off offset:32
	v_lshlrev_b32_e32 v36, 16, v37
	v_and_b32_e32 v37, 0xffff0000, v37
	s_waitcnt lgkmcnt(0)
	v_pk_mul_f32 v[8:9], v[14:15], v[62:63] op_sel_hi:[1,0]
	v_pk_mul_f32 v[14:15], v[20:21], v[62:63] op_sel_hi:[1,0]
	v_lshlrev_b32_e32 v20, 16, v4
	v_and_b32_e32 v21, 0xffff0000, v4
	v_mul_f32_e32 v4, 0xbfb8aa3b, v20
	v_pk_mul_f32 v[10:11], v[12:13], v[62:63] op_sel_hi:[1,0]
	v_pk_mul_f32 v[12:13], v[22:23], v[62:63] op_sel_hi:[1,0]
	v_exp_f32_e32 v4, v4
	v_mul_f32_e32 v22, 0xbfb8aa3b, v21
	v_exp_f32_e32 v23, v22
	v_pk_mul_f32 v[10:11], v[10:11], v[36:37]
	v_add_f32_e32 v4, 1.0, v4
	v_rcp_f32_e32 v22, v4
	v_add_f32_e32 v4, 1.0, v23
	v_rcp_f32_e32 v23, v4
	v_cndmask_b32_e64 v38, v42, v38, s[6:7]
	v_cndmask_b32_e64 v39, v43, v39, s[6:7]
	s_mov_b32 s33, s29
	v_pk_mul_f32 v[20:21], v[22:23], v[20:21]
	v_and_b32_e32 v23, 0xffff0000, v41
	v_pk_mul_f32 v[10:11], v[20:21], v[10:11]
	v_lshlrev_b32_e32 v20, 16, v5
	v_and_b32_e32 v21, 0xffff0000, v5
	v_mul_f32_e32 v4, 0xbfb8aa3b, v20
	v_exp_f32_e32 v5, v4
	v_mul_f32_e32 v4, 0xbfb8aa3b, v21
	v_exp_f32_e32 v22, v4
	v_cvt_pk_bf16_f32 v4, v10, v11
	v_add_f32_e32 v5, 1.0, v5
	v_rcp_f32_e32 v10, v5
	v_add_f32_e32 v5, 1.0, v22
	v_rcp_f32_e32 v11, v5
	v_lshlrev_b32_e32 v22, 16, v41
	v_pk_mul_f32 v[8:9], v[8:9], v[22:23]
	v_pk_mul_f32 v[10:11], v[10:11], v[20:21]
	s_nop 0
	v_pk_mul_f32 v[8:9], v[10:11], v[8:9]
	v_lshlrev_b32_e32 v10, 16, v6
	v_and_b32_e32 v11, 0xffff0000, v6
	v_mul_f32_e32 v5, 0xbfb8aa3b, v10
	v_exp_f32_e32 v6, v5
	v_mul_f32_e32 v5, 0xbfb8aa3b, v11
	v_exp_f32_e32 v20, v5
	v_cvt_pk_bf16_f32 v5, v8, v9
	v_add_f32_e32 v6, 1.0, v6
	v_rcp_f32_e32 v8, v6
	v_add_f32_e32 v6, 1.0, v20
	v_rcp_f32_e32 v9, v6
	v_lshlrev_b32_e32 v20, 16, v38
	v_and_b32_e32 v21, 0xffff0000, v38
	v_pk_mul_f32 v[14:15], v[14:15], v[20:21]
	v_pk_mul_f32 v[8:9], v[8:9], v[10:11]
	v_lshlrev_b32_e32 v10, 16, v7
	v_and_b32_e32 v11, 0xffff0000, v7
	v_mul_f32_e32 v6, 0xbfb8aa3b, v10
	v_exp_f32_e32 v7, v6
	v_mul_f32_e32 v6, 0xbfb8aa3b, v11
	v_pk_mul_f32 v[8:9], v[8:9], v[14:15]
	v_exp_f32_e32 v14, v6
	v_add_f32_e32 v7, 1.0, v7
	v_cvt_pk_bf16_f32 v6, v8, v9
	v_rcp_f32_e32 v8, v7
	v_add_f32_e32 v7, 1.0, v14
	v_rcp_f32_e32 v9, v7
	v_lshlrev_b32_e32 v14, 16, v39
	v_and_b32_e32 v15, 0xffff0000, v39
	v_pk_mul_f32 v[12:13], v[12:13], v[14:15]
	v_pk_mul_f32 v[8:9], v[8:9], v[10:11]
	s_nop 0
	v_pk_mul_f32 v[8:9], v[8:9], v[12:13]
	s_nop 0
	v_cvt_pk_bf16_f32 v7, v8, v9
	global_store_dwordx4 v[60:61], v[4:7], off offset:48
	s_branch .LBB0_884

; #define LAS __attribute__((address_space(3)))
; DI float fexp2(float x) { return __builtin_amdgcn_exp2f(x); }
; DI int crow(int r, int hi) { return (r & 3) + 8 * (r >> 2) + 4 * hi; }
; #define MFMA32(a, b, c) __builtin_amdgcn_mfma_f32_32x32x16_bf16((a), (b), (c), 0, 0, 0)
; DI void gdn_prefetch(const Ctx& c, int item, const bf16_t* proj, u32x4 (&x)[12], bf16_t& ga, bf16_t& gb) {
;     const int tid = c.tid; const int b = item >> 9, h = (item >> 6) & 7, n = item & 63; const int t = tid >> 3, cg8 = tid & 7;
; #pragma unroll
;     for (int which = 0; which < 3; ++which)
; #pragma unroll
;         for (int j = 0; j < 4; ++j) { const int sp = n * 64 + t - 3 + j; const int spc = sp >= 0 ? sp : 0;
;             x[which * 4 + j] = *(const u32x4*)(proj + (size_t)(b * SEQ + spc) * NINP + which * 512 + h * 64 + cg8 * 8); }
;     const size_t ro = (size_t)(b * SEQ + n * 64 + (tid & 63)) * NINP; ga = proj[ro + C_GA + h]; gb = proj[ro + C_GB + h];
;     ...
;     { const int l31 = lane & 31, hi = lane >> 5; const int isqk = wid >> 2, jt = (wid >> 1) & 1, it = wid & 1;
;         if (jt <= it) {
;             const LAS bf16_t* BH = isqk ? QH : KH; const LAS bf16_t* BL = isqk ? QL : KL;
;             bf16x8 aH[4], aLo[4], bH[4], bLo[4];
; #pragma unroll
;             for (int ks = 0; ks < 4; ++ks) { const int ao = (32 * jt + l31) * 72 + 16 * ks + 8 * hi, bo = (32 * it + l31) * 72 + 16 * ks + 8 * hi;
;                 aH[ks] = *(const LAS bf16x8*)(KH + ao); aLo[ks] = *(const LAS bf16x8*)(KL + ao); bH[ks] = *(const LAS bf16x8*)(BH + bo); bLo[ks] = *(const LAS bf16x8*)(BL + bo); }
;             __builtin_amdgcn_sched_barrier(0);
;             f32x16 acc;
; #pragma unroll
;             for (int r = 0; r < 16; ++r) acc[r] = 0.f;
; #pragma unroll
;             for (int ks = 0; ks < 4; ++ks) { acc = MFMA32(aH[ks], bH[ks], acc); acc = MFMA32(aH[ks], bLo[ks], acc); acc = MFMA32(aLo[ks], bH[ks], acc); }
;             const int i = 32 * it + l31; const float gi = gcs[i], bi = bet[i];
; #pragma unroll
;             for (int r = 0; r < 16; ++r) { const int j = 32 * jt + crow(r, hi); const float d = fexp2((gi - gcs[j]) * 1.4426950408889634f);
;                 if (isqk) acc[r] = (j <= i) ? acc[r] * d : 0.f; else Lm[j * 68 + i] = (j < i) ? bi * acc[r] * d : 0.f; }
.LBB0_1747:
	s_add_i32 s73, s68, s30
	s_cmpk_lt_i32 s73, 0x800
	s_waitcnt lgkmcnt(0)
	s_barrier
	s_cselect_b64 s[16:17], -1, 0
	s_cmpk_gt_i32 s73, 0x7ff
	s_cselect_b64 s[66:67], -1, 0
	s_andn2_b64 vcc, exec, s[0:1]
	s_cbranch_vccnz .LBB0_1744
	s_and_b64 s[16:17], s[16:17], exec
	s_mul_i32 s16, s68, 0xa000
	s_cselect_b32 s24, s73, s68
	s_mul_hi_i32 s17, s68, 0xa000
	s_add_u32 s16, s71, s16
	s_addc_u32 s17, s95, s17
	s_lshl_b32 s26, s24, 6
	s_and_b32 s52, s26, 0xfc0
	v_add_u32_e32 v1, s52, v110
	s_bfe_u32 s33, s24, 0x30006
	v_add_u32_e32 v8, -3, v1
	s_lshl_b32 s24, s24, 3
	s_and_b32 s53, s24, 0xfffff000
	s_lshl_b32 s24, s33, 7
	v_max_i32_e32 v4, 0, v8
	v_lshl_add_u64 v[2:3], v[84:85], 0, s[24:25]
	v_add_u32_e32 v4, s53, v4
	v_max_i32_e32 v6, -1, v8
	v_max_i32_e32 v8, -2, v8
	v_mad_i64_i32 v[4:5], s[26:27], v4, s72, v[2:3]
	v_add3_u32 v6, v6, s53, 1
	v_add3_u32 v8, v8, s53, 2
	v_add_u32_e32 v1, s53, v1
	v_mad_i64_i32 v[6:7], s[26:27], v6, s72, v[2:3]
	v_mad_i64_i32 v[8:9], s[26:27], v8, s72, v[2:3]
	v_mad_i64_i32 v[2:3], s[26:27], v1, s72, v[2:3]
	global_load_dwordx4 v[70:73], v[4:5], off
	global_load_dwordx4 v[54:57], v[4:5], off offset:1024
	global_load_dwordx4 v[58:61], v[8:9], off
	global_load_dwordx4 v[50:53], v[8:9], off offset:1024
	global_load_dwordx4 v[74:77], v[6:7], off
	global_load_dwordx4 v[34:37], v[4:5], off offset:2048
	global_load_dwordx4 v[62:65], v[6:7], off offset:1024
	global_load_dwordx4 v[38:41], v[6:7], off offset:2048
	global_load_dwordx4 v[78:81], v[2:3], off
	global_load_dwordx4 v[42:45], v[8:9], off offset:2048
	global_load_dwordx4 v[66:69], v[2:3], off offset:1024
	global_load_dwordx4 v[46:49], v[2:3], off offset:2048
	v_or_b32_e32 v1, s52, v202
	v_or_b32_e32 v1, s53, v1
	v_mov_b64_e32 v[2:3], s[36:37]
	v_mad_i64_i32 v[2:3], s[26:27], v1, s72, v[2:3]
	s_lshl_b32 s24, s33, 1
	v_lshl_add_u64 v[2:3], v[2:3], 0, s[24:25]
	v_add_co_u32_e32 v2, vcc, 0x1000, v2
	s_mov_b64 s[26:27], -1
	s_nop 0
	v_addc_co_u32_e32 v3, vcc, 0, v3, vcc
	global_load_ushort v1, v[2:3], off
	global_load_ushort v100, v[2:3], off offset:16
	v_mov_b32_e32 v2, s65
	ds_read_b32 v82, v2
	s_andn2_b64 vcc, exec, s[48:49]
	s_cbranch_vccnz .LBB0_1819
	ds_read_b128 v[18:21], v119
	ds_read_b128 v[22:25], v120
	ds_read_b128 v[26:29], v123
	ds_read_b128 v[30:33], v124
	ds_read_b128 v[94:97], v121
	ds_read_b128 v[196:199], v121 offset:32
	ds_read_b128 v[204:207], v122
	ds_read_b128 v[208:211], v122 offset:32
	ds_read_b128 v[212:215], v125
	ds_read_b128 v[216:219], v126
	ds_read_b128 v[220:223], v127
	ds_read_b128 v[224:227], v128
	ds_read_b128 v[228:231], v121 offset:64
	ds_read_b128 v[232:235], v121 offset:96
	ds_read_b128 v[236:239], v122 offset:64
	ds_read_b128 v[240:243], v122 offset:96
	s_waitcnt lgkmcnt(11)
	v_mfma_f32_32x32x16_bf16 v[2:17], v[18:21], v[94:97], 0
	s_and_b64 vcc, exec, s[88:89]
	s_waitcnt lgkmcnt(9)
	v_mfma_f32_32x32x16_bf16 v[2:17], v[18:21], v[204:207], v[2:17]
	v_mfma_f32_32x32x16_bf16 v[2:17], v[22:25], v[94:97], v[2:17]
	ds_read_b32 v95, v129
	ds_read_b32 v18, v131
	ds_read_b32 v94, v130
	s_waitcnt lgkmcnt(1)
	v_sub_f32_e32 v18, v95, v18
	v_mul_f32_e32 v18, 0x3fb8aa3b, v18
	v_exp_f32_e32 v96, v18
	v_mfma_f32_32x32x16_bf16 v[2:17], v[26:29], v[196:199], v[2:17]
	v_mfma_f32_32x32x16_bf16 v[2:17], v[26:29], v[208:211], v[2:17]
	v_mfma_f32_32x32x16_bf16 v[2:17], v[30:33], v[196:199], v[2:17]
	v_mfma_f32_32x32x16_bf16 v[2:17], v[212:215], v[228:231], v[2:17]
	v_mfma_f32_32x32x16_bf16 v[2:17], v[212:215], v[236:239], v[2:17]
	v_mfma_f32_32x32x16_bf16 v[2:17], v[216:219], v[228:231], v[2:17]
	v_mfma_f32_32x32x16_bf16 v[2:17], v[220:223], v[232:235], v[2:17]
	v_mfma_f32_32x32x16_bf16 v[2:17], v[220:223], v[240:243], v[2:17]
	v_mfma_f32_32x32x16_bf16 v[2:17], v[224:227], v[232:235], v[2:17]
	ds_read_b32 v19, v132
	ds_read_b32 v20, v133
	ds_read_b32 v21, v134
	ds_read_b32 v22, v135
	ds_read_b32 v23, v136
	ds_read_b32 v24, v137
	ds_read_b32 v25, v138
	ds_read_b32 v26, v139
	ds_read_b32 v27, v140
	ds_read_b32 v28, v141
	ds_read_b32 v29, v142
	ds_read_b32 v30, v143
	ds_read_b32 v31, v144
	ds_read_b32 v32, v145
	ds_read_b32 v33, v146
	v_mov_b32_e32 v18, v96
	s_waitcnt lgkmcnt(0)
	v_sub_f32_e32 v19, v95, v19
	v_sub_f32_e32 v20, v95, v20
	v_sub_f32_e32 v21, v95, v21
	v_sub_f32_e32 v22, v95, v22
	v_sub_f32_e32 v23, v95, v23
	v_sub_f32_e32 v24, v95, v24
	v_sub_f32_e32 v25, v95, v25
	v_sub_f32_e32 v26, v95, v26
	v_sub_f32_e32 v27, v95, v27
	v_sub_f32_e32 v28, v95, v28
	v_sub_f32_e32 v29, v95, v29
	v_sub_f32_e32 v30, v95, v30
	v_sub_f32_e32 v31, v95, v31
	v_sub_f32_e32 v32, v95, v32
	v_sub_f32_e32 v33, v95, v33
	v_mul_f32_e32 v19, 0x3fb8aa3b, v19
	v_mul_f32_e32 v20, 0x3fb8aa3b, v20
	v_mul_f32_e32 v21, 0x3fb8aa3b, v21
	v_mul_f32_e32 v22, 0x3fb8aa3b, v22
	v_mul_f32_e32 v23, 0x3fb8aa3b, v23
	v_mul_f32_e32 v24, 0x3fb8aa3b, v24
	v_mul_f32_e32 v25, 0x3fb8aa3b, v25
	v_mul_f32_e32 v26, 0x3fb8aa3b, v26
	v_mul_f32_e32 v27, 0x3fb8aa3b, v27
	v_mul_f32_e32 v28, 0x3fb8aa3b, v28
	v_mul_f32_e32 v29, 0x3fb8aa3b, v29
	v_mul_f32_e32 v30, 0x3fb8aa3b, v30
	v_mul_f32_e32 v31, 0x3fb8aa3b, v31
	v_mul_f32_e32 v32, 0x3fb8aa3b, v32
	v_mul_f32_e32 v33, 0x3fb8aa3b, v33
	v_exp_f32_e32 v19, v19
	v_exp_f32_e32 v20, v20
	v_exp_f32_e32 v21, v21
	v_exp_f32_e32 v22, v22
	v_exp_f32_e32 v23, v23
	v_exp_f32_e32 v24, v24
	v_exp_f32_e32 v25, v25
	v_exp_f32_e32 v26, v26
	v_exp_f32_e32 v27, v27
	v_exp_f32_e32 v28, v28
	v_exp_f32_e32 v29, v29
	v_exp_f32_e32 v30, v30
	v_exp_f32_e32 v31, v31
	v_exp_f32_e32 v32, v32
	v_exp_f32_e32 v33, v33
	s_andn2_b64 vcc, exec, s[88:89]
	s_cbranch_vccnz .Ldecay_l_1
; DI float fexp2(float x) { return __builtin_amdgcn_exp2f(x); }
; DI int crow(int r, int hi) { return (r & 3) + 8 * (r >> 2) + 4 * hi; }
;     ...
;             const int i = 32 * it + l31; const float gi = gcs[i], bi = bet[i];
; #pragma unroll
;             for (int r = 0; r < 16; ++r) { const int j = 32 * jt + crow(r, hi); const float d = fexp2((gi - gcs[j]) * 1.4426950408889634f);
;                 if (isqk) acc[r] = (j <= i) ? acc[r] * d : 0.f; else Lm[j * 68 + i] = (j < i) ? bi * acc[r] * d : 0.f; }
	v_readlane_b32 s4, v247, 39
	v_readlane_b32 s5, v247, 40
	v_mul_f32_e32 v2, v2, v18
	s_nop 1
	v_cndmask_b32_e64 v2, v2, 0, s[4:5]
	v_mul_f32_e32 v3, v3, v19
	s_nop 1
	v_cndmask_b32_e64 v3, 0, v3, s[42:43]
	v_readlane_b32 s4, v247, 41
	v_readlane_b32 s5, v247, 42
	v_mul_f32_e32 v4, v4, v20
	s_nop 1
	v_cndmask_b32_e64 v4, v4, 0, s[4:5]
	v_readlane_b32 s4, v247, 45
	v_readlane_b32 s5, v247, 46
	v_mul_f32_e32 v5, v5, v21
	s_nop 1
	v_cndmask_b32_e64 v5, v5, 0, s[4:5]
	v_readlane_b32 s4, v247, 49
	v_readlane_b32 s5, v247, 50
	v_mul_f32_e32 v6, v6, v22
	s_nop 1
	v_cndmask_b32_e64 v6, v6, 0, s[4:5]
	v_readlane_b32 s4, v247, 53
	v_readlane_b32 s5, v247, 54
	v_mul_f32_e32 v7, v7, v23
	s_nop 1
	v_cndmask_b32_e64 v7, v7, 0, s[4:5]
	v_readlane_b32 s4, v247, 57
	v_readlane_b32 s5, v247, 58
	v_mul_f32_e32 v8, v8, v24
	s_nop 1
	v_cndmask_b32_e64 v8, v8, 0, s[4:5]
	v_readlane_b32 s4, v247, 61
	v_readlane_b32 s5, v247, 62
	v_mul_f32_e32 v9, v9, v25
	s_nop 1
	v_cndmask_b32_e64 v9, v9, 0, s[4:5]
	v_readlane_b32 s4, v246, 1
	v_readlane_b32 s5, v246, 2
	v_mul_f32_e32 v10, v10, v26
	s_nop 1
	v_cndmask_b32_e64 v10, v10, 0, s[4:5]
	v_readlane_b32 s4, v246, 5
	v_readlane_b32 s5, v246, 6
	v_mul_f32_e32 v11, v11, v27
	s_nop 1
	v_cndmask_b32_e64 v11, v11, 0, s[4:5]
	v_readlane_b32 s4, v246, 9
	v_readlane_b32 s5, v246, 10
	v_mul_f32_e32 v12, v12, v28
	s_nop 1
	v_cndmask_b32_e64 v12, v12, 0, s[4:5]
	v_readlane_b32 s4, v246, 13
	v_readlane_b32 s5, v246, 14
	v_mul_f32_e32 v13, v13, v29
	s_nop 1
	v_cndmask_b32_e64 v13, v13, 0, s[4:5]
	v_readlane_b32 s4, v246, 17
	v_readlane_b32 s5, v246, 18
	v_mul_f32_e32 v14, v14, v30
	s_nop 1
	v_cndmask_b32_e64 v14, v14, 0, s[4:5]
	v_readlane_b32 s4, v246, 21
	v_readlane_b32 s5, v246, 22
	v_mul_f32_e32 v15, v15, v31
	s_nop 1
	v_cndmask_b32_e64 v15, v15, 0, s[4:5]
	v_readlane_b32 s4, v246, 25
	v_readlane_b32 s5, v246, 26
	v_mul_f32_e32 v16, v16, v32
	s_nop 1
	v_cndmask_b32_e64 v16, v16, 0, s[4:5]
	v_readlane_b32 s4, v246, 29
	v_readlane_b32 s5, v246, 30
	v_mul_f32_e32 v17, v17, v33
	s_nop 1
	v_cndmask_b32_e64 v17, v17, 0, s[4:5]
	s_mov_b64 s[26:27], -1
	s_branch .LBB0_1815
.Ldecay_l_1:
	v_mul_f32_e32 v96, v94, v2
	v_mul_f32_e32 v96, v96, v18
	s_nop 1
	v_cndmask_b32_e64 v96, 0, v96, s[42:43]
	ds_write_b32 v194, v96 offset:52224
	v_mul_f32_e32 v97, v94, v3
	v_readlane_b32 s4, v247, 37
	v_readlane_b32 s5, v247, 38
	v_mul_f32_e32 v97, v97, v19
	s_nop 1
	v_cndmask_b32_e64 v97, 0, v97, s[4:5]
	ds_write_b32 v194, v97 offset:52496
	v_mul_f32_e32 v96, v94, v4
	v_readlane_b32 s4, v247, 43
	v_readlane_b32 s5, v247, 44
	v_mul_f32_e32 v96, v96, v20
	s_nop 1
	v_cndmask_b32_e64 v96, 0, v96, s[4:5]
	ds_write_b32 v194, v96 offset:52768
	v_mul_f32_e32 v97, v94, v5
	v_readlane_b32 s4, v247, 47
	v_readlane_b32 s5, v247, 48
	v_mul_f32_e32 v97, v97, v21
	s_nop 1
	v_cndmask_b32_e64 v97, 0, v97, s[4:5]
	ds_write_b32 v194, v97 offset:53040
	v_mul_f32_e32 v96, v94, v6
	v_readlane_b32 s4, v247, 51
	v_readlane_b32 s5, v247, 52
	v_mul_f32_e32 v96, v96, v22
	s_nop 1
	v_cndmask_b32_e64 v96, 0, v96, s[4:5]
	ds_write_b32 v194, v96 offset:54400
	v_mul_f32_e32 v97, v94, v7
	v_readlane_b32 s4, v247, 55
	v_readlane_b32 s5, v247, 56
	v_mul_f32_e32 v97, v97, v23
	s_nop 1
	v_cndmask_b32_e64 v97, 0, v97, s[4:5]
	ds_write_b32 v194, v97 offset:54672
	v_mul_f32_e32 v96, v94, v8
	v_readlane_b32 s4, v247, 59
	v_readlane_b32 s5, v247, 60
	v_mul_f32_e32 v96, v96, v24
	s_nop 1
	v_cndmask_b32_e64 v96, 0, v96, s[4:5]
	ds_write_b32 v194, v96 offset:54944
	v_mul_f32_e32 v97, v94, v9
	v_readlane_b32 s4, v247, 63
	v_readlane_b32 s5, v246, 0
	v_mul_f32_e32 v97, v97, v25
	s_nop 1
	v_cndmask_b32_e64 v97, 0, v97, s[4:5]
	ds_write_b32 v194, v97 offset:55216
	v_mul_f32_e32 v96, v94, v10
	v_readlane_b32 s4, v246, 3
	v_readlane_b32 s5, v246, 4
	v_mul_f32_e32 v96, v96, v26
	s_nop 1
	v_cndmask_b32_e64 v96, 0, v96, s[4:5]
	ds_write_b32 v194, v96 offset:56576
	v_mul_f32_e32 v97, v94, v11
	v_readlane_b32 s4, v246, 7
	v_readlane_b32 s5, v246, 8
	v_mul_f32_e32 v97, v97, v27
	s_nop 1
	v_cndmask_b32_e64 v97, 0, v97, s[4:5]
	ds_write_b32 v194, v97 offset:56848
	v_mul_f32_e32 v96, v94, v12
	v_readlane_b32 s4, v246, 11
	v_readlane_b32 s5, v246, 12
	v_mul_f32_e32 v96, v96, v28
	s_nop 1
	v_cndmask_b32_e64 v96, 0, v96, s[4:5]
	ds_write_b32 v194, v96 offset:57120
	v_mul_f32_e32 v97, v94, v13
	v_readlane_b32 s4, v246, 15
	v_readlane_b32 s5, v246, 16
	v_mul_f32_e32 v97, v97, v29
	s_nop 1
	v_cndmask_b32_e64 v97, 0, v97, s[4:5]
	ds_write_b32 v194, v97 offset:57392
	v_mul_f32_e32 v96, v94, v14
	v_readlane_b32 s4, v246, 19
	v_readlane_b32 s5, v246, 20
	v_mul_f32_e32 v96, v96, v30
	s_nop 1
	v_cndmask_b32_e64 v96, 0, v96, s[4:5]
	ds_write_b32 v194, v96 offset:58752
	v_mul_f32_e32 v97, v94, v15
	v_readlane_b32 s4, v246, 23
	v_readlane_b32 s5, v246, 24
	v_mul_f32_e32 v97, v97, v31
	s_nop 1
	v_cndmask_b32_e64 v97, 0, v97, s[4:5]
	ds_write_b32 v194, v97 offset:59024
	v_mul_f32_e32 v96, v94, v16
	v_readlane_b32 s4, v246, 27
	v_readlane_b32 s5, v246, 28
	v_mul_f32_e32 v96, v96, v32
	s_nop 1
	v_cndmask_b32_e64 v96, 0, v96, s[4:5]
	ds_write_b32 v194, v96 offset:59296
	v_mul_f32_e32 v97, v94, v17
	v_readlane_b32 s4, v246, 31
	v_readlane_b32 s5, v246, 32
	v_mul_f32_e32 v97, v97, v33
	s_nop 1
	v_cndmask_b32_e64 v97, 0, v97, s[4:5]
	ds_write_b32 v194, v97 offset:59568
	s_mov_b64 s[26:27], -1
	s_branch .LBB0_1816

; #define LAS __attribute__((address_space(3)))
;     ...
;             else if (jt == it) {
;                 const int bb = 2 * jt + ((lane >> 4) & 1), col = lane & 15;
;                 float y[16];
; #pragma unroll
;                 for (int ii = 0; ii < 16; ++ii) y[ii] = (ii == col) ? 1.f : 0.f;
; #pragma unroll
;                 for (int j = 0; j < 15; ++j) { const float yj = y[j];
; #pragma unroll
;                     for (int q4 = (j + 1) / 4; q4 < 4; ++q4) { const f32x4 l4 = *(const LAS f32x4*)(Lm + (16 * bb + j) * 68 + 16 * bb + 4 * q4);
; #pragma unroll
;                         for (int e = 0; e < 4; ++e) if (4 * q4 + e > j) y[4 * q4 + e] -= l4[e] * yj; } }
; #pragma unroll
;                 for (int ii = 0; ii < 16; ++ii) DIV[bb * 320 + ii * 20 + col] = y[ii];
.LBB0_1816:
	v_readlane_b32 s4, v246, 33
	v_readlane_b32 s5, v246, 34
	s_andn2_b64 vcc, exec, s[4:5]
	s_cbranch_vccnz .LBB0_1818
	ds_read_b128 v[196:199], v178 offset:52224
	ds_read_b128 v[204:207], v178 offset:52240
	ds_read_b128 v[208:211], v178 offset:52256
	ds_read_b128 v[212:215], v178 offset:52272
	ds_read_b128 v[216:219], v178 offset:52496
	ds_read_b128 v[220:223], v178 offset:52512
	ds_read_b128 v[224:227], v178 offset:52528
	ds_read_b128 v[228:231], v178 offset:52544
	ds_read_b128 v[232:235], v178 offset:52768
	s_waitcnt lgkmcnt(8)
	v_fma_f32 v2, -v147, v197, v148
	v_fma_f32 v3, -v147, v198, v149
	v_fma_f32 v18, -v147, v199, v150
	ds_read_b128 v[236:239], v178 offset:52784
	s_waitcnt lgkmcnt(8)
	v_fma_f32 v19, -v147, v204, v151
	v_fma_f32 v20, -v147, v205, v153
	v_fma_f32 v8, -v147, v206, v154
	v_fma_f32 v9, -v147, v207, v155
	ds_read_b128 v[240:243], v178 offset:52800
	s_waitcnt lgkmcnt(8)
	v_fma_f32 v10, -v147, v208, v156
	v_fma_f32 v11, -v147, v209, v157
	s_waitcnt lgkmcnt(6)
	v_fma_f32 v3, -v2, v218, v3
	v_fma_f32 v18, -v2, v219, v18
	v_fma_f32 v12, -v147, v210, v158
	v_fma_f32 v13, -v147, v211, v159
	ds_read_b128 v[196:199], v178 offset:52816
	ds_read_b128 v[204:207], v178 offset:53056
	v_fma_f32 v14, -v147, v212, v160
	v_fma_f32 v15, -v147, v213, v161
	ds_read_b128 v[208:211], v178 offset:53072
	s_waitcnt lgkmcnt(8)
	v_fma_f32 v19, -v2, v220, v19
	v_fma_f32 v20, -v2, v221, v20
	v_fma_f32 v21, -v2, v222, v8
	v_fma_f32 v22, -v2, v223, v9
	v_fma_f32 v16, -v147, v214, v162
	v_fma_f32 v17, -v147, v215, v163
	ds_read_b128 v[212:215], v178 offset:53088
	s_waitcnt lgkmcnt(8)
	v_fma_f32 v10, -v2, v224, v10
	v_fma_f32 v11, -v2, v225, v11
	v_fma_f32 v12, -v2, v226, v12
	v_fma_f32 v13, -v2, v227, v13
	ds_read_b128 v[216:219], v178 offset:53328
	s_waitcnt lgkmcnt(8)
	v_fma_f32 v14, -v2, v228, v14
	v_fma_f32 v15, -v2, v229, v15
	v_fma_f32 v16, -v2, v230, v16
	v_fma_f32 v17, -v2, v231, v17
	ds_read_b128 v[220:223], v178 offset:53344
	s_waitcnt lgkmcnt(8)
	v_fma_f32 v4, -v3, v235, v18
	ds_read_b128 v[224:227], v178 offset:53360
	s_waitcnt lgkmcnt(8)
	v_fma_f32 v5, -v3, v236, v19
	v_fma_f32 v18, -v3, v237, v20
	v_fma_f32 v19, -v3, v238, v21
	v_fma_f32 v20, -v3, v239, v22
	ds_read_b128 v[228:231], v178 offset:53600
	s_waitcnt lgkmcnt(8)
	v_fma_f32 v10, -v3, v240, v10
	v_fma_f32 v11, -v3, v241, v11
	v_fma_f32 v12, -v3, v242, v12
	v_fma_f32 v13, -v3, v243, v13
	ds_read_b128 v[232:235], v178 offset:53616
	s_waitcnt lgkmcnt(8)
	v_fma_f32 v14, -v3, v196, v14
	v_fma_f32 v15, -v3, v197, v15
	v_fma_f32 v16, -v3, v198, v16
	v_fma_f32 v17, -v3, v199, v17
	ds_read_b128 v[236:239], v178 offset:53632
	s_waitcnt lgkmcnt(8)
	v_fma_f32 v5, -v4, v204, v5
	v_fma_f32 v18, -v4, v205, v18
	v_fma_f32 v19, -v4, v206, v19
	v_fma_f32 v20, -v4, v207, v20
	ds_read_b128 v[240:243], v178 offset:53872
	s_waitcnt lgkmcnt(8)
	v_fma_f32 v21, -v4, v208, v10
	v_fma_f32 v22, -v4, v209, v11
	v_fma_f32 v12, -v4, v210, v12
	v_fma_f32 v13, -v4, v211, v13
	ds_read_b128 v[196:199], v178 offset:53888
	s_waitcnt lgkmcnt(8)
	v_fma_f32 v14, -v4, v212, v14
	v_fma_f32 v15, -v4, v213, v15
	v_fma_f32 v16, -v4, v214, v16
	v_fma_f32 v17, -v4, v215, v17
	ds_read_b128 v[204:207], v178 offset:53904
	s_waitcnt lgkmcnt(8)
	v_fma_f32 v6, -v5, v217, v18
	v_fma_f32 v7, -v5, v218, v19
	v_fma_f32 v18, -v5, v219, v20
	ds_read_b128 v[208:211], v178 offset:54160
	s_waitcnt lgkmcnt(8)
	v_fma_f32 v19, -v5, v220, v21
	v_fma_f32 v20, -v5, v221, v22
	v_fma_f32 v12, -v5, v222, v12
	v_fma_f32 v13, -v5, v223, v13
	ds_read_b128 v[212:215], v178 offset:54176
	s_waitcnt lgkmcnt(8)
	v_fma_f32 v14, -v5, v224, v14
	v_fma_f32 v15, -v5, v225, v15
	v_fma_f32 v16, -v5, v226, v16
	v_fma_f32 v17, -v5, v227, v17
	ds_read_b128 v[216:219], v178 offset:54432
	s_waitcnt lgkmcnt(8)
	v_fma_f32 v7, -v6, v230, v7
	v_fma_f32 v18, -v6, v231, v18
	ds_read_b128 v[220:223], v178 offset:54448
	s_waitcnt lgkmcnt(8)
	v_fma_f32 v19, -v6, v232, v19
	v_fma_f32 v20, -v6, v233, v20
	v_fma_f32 v12, -v6, v234, v12
	v_fma_f32 v13, -v6, v235, v13
	ds_read_b128 v[224:227], v178 offset:54704
	s_waitcnt lgkmcnt(8)
	v_fma_f32 v14, -v6, v236, v14
	v_fma_f32 v15, -v6, v237, v15
	v_fma_f32 v16, -v6, v238, v16
	v_fma_f32 v17, -v6, v239, v17
	ds_read_b128 v[228:231], v178 offset:54720
	s_waitcnt lgkmcnt(8)
	v_fma_f32 v18, -v7, v243, v18
	ds_read_b128 v[232:235], v178 offset:54976
	s_waitcnt lgkmcnt(8)
	v_fma_f32 v19, -v7, v196, v19
	v_fma_f32 v20, -v7, v197, v20
	v_fma_f32 v12, -v7, v198, v12
	v_fma_f32 v13, -v7, v199, v13
	ds_read_b128 v[236:239], v178 offset:54992
	s_waitcnt lgkmcnt(8)
	v_fma_f32 v14, -v7, v204, v14
	v_fma_f32 v15, -v7, v205, v15
	v_fma_f32 v16, -v7, v206, v16
	v_fma_f32 v17, -v7, v207, v17
	ds_read_b128 v[240:243], v178 offset:55264
	s_waitcnt lgkmcnt(8)
	v_fma_f32 v19, -v18, v208, v19
	v_fma_f32 v20, -v18, v209, v20
	v_fma_f32 v12, -v18, v210, v12
	v_fma_f32 v13, -v18, v211, v13
	ds_read_b128 v[196:199], v178 offset:55536
	s_waitcnt lgkmcnt(8)
	v_fma_f32 v14, -v18, v212, v14
	v_fma_f32 v15, -v18, v213, v15
	v_fma_f32 v16, -v18, v214, v16
	v_fma_f32 v17, -v18, v215, v17
	ds_read_b128 v[204:207], v178 offset:55808
	s_waitcnt lgkmcnt(8)
	v_fma_f32 v20, -v19, v217, v20
	v_fma_f32 v12, -v19, v218, v12
	v_fma_f32 v13, -v19, v219, v13
	ds_read_b128 v[208:211], v178 offset:56080
	s_waitcnt lgkmcnt(8)
	v_fma_f32 v14, -v19, v220, v14
	v_fma_f32 v15, -v19, v221, v15
	v_fma_f32 v16, -v19, v222, v16
	v_fma_f32 v17, -v19, v223, v17
	s_waitcnt lgkmcnt(7)
	v_fma_f32 v12, -v20, v226, v12
	v_fma_f32 v13, -v20, v227, v13
	s_waitcnt lgkmcnt(6)
	v_fma_f32 v14, -v20, v228, v14
	v_fma_f32 v15, -v20, v229, v15
	v_fma_f32 v16, -v20, v230, v16
	v_fma_f32 v17, -v20, v231, v17
	s_waitcnt lgkmcnt(5)
	v_fma_f32 v13, -v12, v235, v13
	s_waitcnt lgkmcnt(4)
	v_fma_f32 v14, -v12, v236, v14
	v_fma_f32 v15, -v12, v237, v15
	v_fma_f32 v16, -v12, v238, v16
	v_fma_f32 v17, -v12, v239, v17
	s_waitcnt lgkmcnt(3)
	v_fma_f32 v14, -v13, v240, v14
	v_fma_f32 v15, -v13, v241, v15
	v_fma_f32 v16, -v13, v242, v16
	v_fma_f32 v17, -v13, v243, v17
	s_waitcnt lgkmcnt(2)
	v_fma_f32 v15, -v197, v14, v15
	v_fma_f32 v16, -v198, v14, v16
	v_fma_f32 v17, -v199, v14, v17
	s_waitcnt lgkmcnt(1)
	v_fma_f32 v16, -v206, v15, v16
	v_fma_f32 v17, -v207, v15, v17
	ds_write2_b32 v164, v147, v2 offset1:20
	ds_write2_b32 v164, v3, v4 offset0:40 offset1:60
	ds_write2_b32 v164, v5, v6 offset0:80 offset1:100
	ds_write2_b32 v164, v7, v18 offset0:120 offset1:140
	ds_write2_b32 v164, v19, v20 offset0:160 offset1:180
	ds_write2_b32 v164, v12, v13 offset0:200 offset1:220
	v_add_u32_e32 v2, 0x200, v164
	ds_write2_b32 v2, v14, v15 offset0:112 offset1:132
	v_add_u32_e32 v2, 0x400, v164
	s_waitcnt lgkmcnt(7)
	v_fma_f32 v8, -v211, v16, v17
	ds_write2_b32 v2, v16, v8 offset0:24 offset1:44

;     ...
;     {
;         const int g = lane >> 4, nn = lane & 15, cb = 16 * wid + nn;
; #pragma unroll
;         for (int blk = 0; blk < 4; ++blk) {
;             f32x4 acc;
; #pragma unroll
;             for (int r = 0; r < 4; ++r) acc[r] = rhs[(16 * blk + 4 * g + r) * 132 + cb];
; #pragma unroll
;             for (int k4 = 0; k4 < 4 * blk; ++k4) { const float av = -Lm[(4 * k4 + g) * 68 + 16 * blk + nn], bv = rhs[(4 * k4 + g) * 132 + cb];
;                 acc = __builtin_amdgcn_mfma_f32_16x16x4f32(av, bv, acc, 0, 0, 0); }
; #pragma unroll
;             for (int r = 0; r < 4; ++r) rhs[(16 * blk + 4 * g + r) * 132 + cb] = acc[r];
;             f32x4 xs = (f32x4){0.f, 0.f, 0.f, 0.f};
; #pragma unroll
;             for (int k4 = 0; k4 < 4; ++k4) { const float av = DIV[blk * 320 + nn * 20 + 4 * k4 + g], bv = rhs[(16 * blk + 4 * k4 + g) * 132 + cb];
;                 xs = __builtin_amdgcn_mfma_f32_16x16x4f32(av, bv, xs, 0, 0, 0); }
; #pragma unroll
;             for (int r = 0; r < 4; ++r) rhs[(16 * blk + 4 * g + r) * 132 + cb] = xs[r];
;         }
;     }
.LBB0_1844:
	s_waitcnt lgkmcnt(0)
	s_barrier
	s_and_b64 vcc, exec, s[40:41]
	s_cbranch_vccz .LBB0_1744
	ds_read_b32 v196, v184 offset:52288
	ds_read_b32 v197, v184 offset:53376
	ds_read_b32 v198, v184 offset:54464
	ds_read_b32 v199, v184 offset:55552
	ds_read_b32 v204, v184 offset:52352
	ds_read_b32 v205, v184 offset:53440
	ds_read_b32 v206, v184 offset:54528
	ds_read_b32 v207, v184 offset:55616
	ds_read_b32 v208, v184 offset:56704
	ds_read_b32 v209, v184 offset:57792
	ds_read_b32 v210, v184 offset:58880
	ds_read_b32 v211, v184 offset:59968
	ds_read_b32 v212, v184 offset:52416
	ds_read_b32 v213, v184 offset:53504
	ds_read_b32 v214, v184 offset:54592
	ds_read_b32 v215, v184 offset:55680
	ds_read_b32 v216, v184 offset:56768
	ds_read_b32 v217, v184 offset:57856
	ds_read_b32 v218, v184 offset:58944
	ds_read_b32 v219, v184 offset:60032
	ds_read_b32 v220, v184 offset:61120
	ds_read_b32 v221, v184 offset:62208
	ds_read_b32 v222, v184 offset:63296
	ds_read_b32 v223, v184 offset:64384
	ds_read2_b32 v[6:7], v168 offset1:4
	ds_read_b32 v2, v182
	v_add_u32_e32 v9, 0x2400, v183
	v_add_u32_e32 v12, 0x400, v168
	v_add_u32_e32 v16, 0x800, v168
	v_readlane_b32 s4, v247, 35
	s_waitcnt lgkmcnt(0)
	v_mfma_f32_16x16x4_f32 v[2:5], v6, v2, 0
	ds_read_b32 v6, v182 offset:2112
	v_readlane_b32 s5, v247, 36
	s_andn2_b64 vcc, exec, s[4:5]
	s_waitcnt lgkmcnt(0)
	v_mfma_f32_16x16x4_f32 v[2:5], v7, v6, v[2:5]
	ds_read2_b32 v[6:7], v168 offset0:8 offset1:12
	ds_read_b32 v8, v182 offset:4224
	s_waitcnt lgkmcnt(0)
	v_mfma_f32_16x16x4_f32 v[2:5], v6, v8, v[2:5]
	ds_read_b32 v6, v182 offset:6336
	v_add_u32_e32 v8, 0x400, v183
	s_waitcnt lgkmcnt(0)
	v_mfma_f32_16x16x4_f32 v[2:5], v7, v6, v[2:5]
	s_nop 9
	ds_write2_b32 v183, v2, v3 offset1:132
	ds_write2_b32 v8, v4, v5 offset0:8 offset1:140
	v_add_u32_e32 v2, 0x2000, v183
	ds_read2_b32 v[4:5], v9 offset0:72 offset1:204
	ds_read2_b32 v[2:3], v2 offset0:64 offset1:196
	ds_read_b32 v8, v182
	s_waitcnt lgkmcnt(0)
	v_xor_b32_e32 v6, 0x80000000, v196
	s_waitcnt lgkmcnt(0)
	s_nop 0
	v_mfma_f32_16x16x4_f32 v[2:5], v6, v8, v[2:5]
	ds_read_b32 v9, v182 offset:2112
	s_waitcnt lgkmcnt(0)
	v_xor_b32_e32 v6, 0x80000000, v197
	s_waitcnt lgkmcnt(0)
	s_nop 0
	v_mfma_f32_16x16x4_f32 v[2:5], v6, v9, v[2:5]
	ds_read_b32 v10, v182 offset:4224
	s_waitcnt lgkmcnt(0)
	v_xor_b32_e32 v6, 0x80000000, v198
	s_waitcnt lgkmcnt(0)
	s_nop 0
	v_mfma_f32_16x16x4_f32 v[2:5], v6, v10, v[2:5]
	ds_read_b32 v11, v182 offset:6336
	s_waitcnt lgkmcnt(0)
	v_xor_b32_e32 v6, 0x80000000, v199
	s_waitcnt lgkmcnt(0)
	s_nop 0
	v_mfma_f32_16x16x4_f32 v[2:5], v6, v11, v[2:5]
	s_nop 9
	ds_write_b32 v183, v2 offset:8448
	ds_write_b32 v183, v3 offset:8976
	ds_write_b32 v183, v4 offset:9504
	ds_write_b32 v183, v5 offset:10032
	ds_read2_b32 v[6:7], v12 offset0:64 offset1:68
	ds_read_b32 v2, v182 offset:8448
	s_waitcnt lgkmcnt(0)
	v_mfma_f32_16x16x4_f32 v[2:5], v6, v2, 0
	ds_read_b32 v6, v182 offset:10560
	s_waitcnt lgkmcnt(0)
	v_mfma_f32_16x16x4_f32 v[2:5], v7, v6, v[2:5]
	ds_read2_b32 v[6:7], v12 offset0:72 offset1:76
	ds_read_b32 v12, v182 offset:12672
	s_waitcnt lgkmcnt(0)
	v_mfma_f32_16x16x4_f32 v[2:5], v6, v12, v[2:5]
	ds_read_b32 v6, v182 offset:14784
	s_waitcnt lgkmcnt(0)
	v_mfma_f32_16x16x4_f32 v[2:5], v7, v6, v[2:5]
	s_nop 9
	ds_write_b32 v183, v2 offset:8448
	ds_write_b32 v183, v3 offset:8976
	ds_write_b32 v183, v4 offset:9504
	ds_write_b32 v183, v5 offset:10032
	v_add_u32_e32 v2, 0x4200, v183
	v_add_u32_e32 v4, 0x4600, v183
	ds_read2_b32 v[2:3], v2 offset1:132
	ds_read2_b32 v[4:5], v4 offset0:8 offset1:140
	s_waitcnt lgkmcnt(0)
	v_xor_b32_e32 v6, 0x80000000, v204
	s_waitcnt lgkmcnt(0)
	s_nop 0
	v_mfma_f32_16x16x4_f32 v[2:5], v6, v8, v[2:5]
	s_waitcnt lgkmcnt(0)
	v_xor_b32_e32 v6, 0x80000000, v205
	s_nop 1
	v_mfma_f32_16x16x4_f32 v[2:5], v6, v9, v[2:5]
	s_waitcnt lgkmcnt(0)
	v_xor_b32_e32 v6, 0x80000000, v206
	s_nop 1
	v_mfma_f32_16x16x4_f32 v[2:5], v6, v10, v[2:5]
	s_waitcnt lgkmcnt(0)
	v_xor_b32_e32 v6, 0x80000000, v207
	s_nop 1
	v_mfma_f32_16x16x4_f32 v[2:5], v6, v11, v[2:5]
	ds_read_b32 v12, v182 offset:8448
	s_waitcnt lgkmcnt(0)
	v_xor_b32_e32 v6, 0x80000000, v208
	s_waitcnt lgkmcnt(0)
	s_nop 0
	v_mfma_f32_16x16x4_f32 v[2:5], v6, v12, v[2:5]
	ds_read_b32 v13, v182 offset:10560
	s_waitcnt lgkmcnt(0)
	v_xor_b32_e32 v6, 0x80000000, v209
	s_waitcnt lgkmcnt(0)
	s_nop 0
	v_mfma_f32_16x16x4_f32 v[2:5], v6, v13, v[2:5]
	ds_read_b32 v14, v182 offset:12672
	s_waitcnt lgkmcnt(0)
	v_xor_b32_e32 v6, 0x80000000, v210
	s_waitcnt lgkmcnt(0)
	s_nop 0
	v_mfma_f32_16x16x4_f32 v[2:5], v6, v14, v[2:5]
	ds_read_b32 v15, v182 offset:14784
	s_waitcnt lgkmcnt(0)
	v_xor_b32_e32 v6, 0x80000000, v211
	s_waitcnt lgkmcnt(0)
	s_nop 0
	v_mfma_f32_16x16x4_f32 v[2:5], v6, v15, v[2:5]
	s_nop 9
	ds_write_b32 v183, v2 offset:16896
	ds_write_b32 v183, v3 offset:17424
	ds_write_b32 v183, v4 offset:17952
	ds_write_b32 v183, v5 offset:18480
	ds_read2_b32 v[6:7], v16 offset0:128 offset1:132
	ds_read_b32 v2, v182 offset:16896
	s_waitcnt lgkmcnt(0)
; #define LAS __attribute__((address_space(3)))
; DI unsigned pk2(float lo, float hi) { typedef __bf16 b2 __attribute__((ext_vector_type(2))); f32x2 v = {lo, hi}; b2 b = __builtin_convertvector(v, b2); return __builtin_bit_cast(unsigned, b); }
; #define LBAR() do { asm volatile("s_waitcnt lgkmcnt(0)" ::: "memory"); __builtin_amdgcn_s_barrier(); asm volatile("" ::: "memory"); } while (0)
; DI int crow(int r, int hi) { return (r & 3) + 8 * (r >> 2) + 4 * hi; }
;     ...
;             for (int r = 0; r < 4; ++r) acc[r] = rhs[(16 * blk + 4 * g + r) * 132 + cb];
; #pragma unroll
;             for (int k4 = 0; k4 < 4 * blk; ++k4) { const float av = -Lm[(4 * k4 + g) * 68 + 16 * blk + nn], bv = rhs[(4 * k4 + g) * 132 + cb];
;                 acc = __builtin_amdgcn_mfma_f32_16x16x4f32(av, bv, acc, 0, 0, 0); }
; #pragma unroll
;             for (int r = 0; r < 4; ++r) rhs[(16 * blk + 4 * g + r) * 132 + cb] = acc[r];
;             f32x4 xs = (f32x4){0.f, 0.f, 0.f, 0.f};
; #pragma unroll
;             for (int k4 = 0; k4 < 4; ++k4) { const float av = DIV[blk * 320 + nn * 20 + 4 * k4 + g], bv = rhs[(16 * blk + 4 * k4 + g) * 132 + cb];
;                 xs = __builtin_amdgcn_mfma_f32_16x16x4f32(av, bv, xs, 0, 0, 0); }
; #pragma unroll
;             for (int r = 0; r < 4; ++r) rhs[(16 * blk + 4 * g + r) * 132 + cb] = xs[r];
;         }
;     }
;     LBAR();
;     if (stop == 5) return;
;     {
;         const int idx = tid; const int mt = idx >> 8, ks = (idx >> 6) & 3, ln = idx & 63, i = 32 * mt + (ln & 31), hh = ln >> 5, k0 = 16 * ks + 4 * hh;
;         const f32x4 a = *(const LAS f32x4*)(rhs + i * 132 + 64 + k0), bq = *(const LAS f32x4*)(rhs + i * 132 + 64 + k0 + 8);
;         u32x4 w; w.x = pk2(-a[0], -a[1]); w.y = pk2(-a[2], -a[3]); w.z = pk2(-bq[0], -bq[1]); w.w = pk2(-bq[2], -bq[3]);
;         *(u32x4*)(gout + idx * 16) = w;
;         const int tile = idx >> 7, ln2 = (idx >> 1) & 63, half = idx & 1, ct = tile >> 1, vt = tile & 1, vcol = 32 * vt + (ln2 & 31), h2 = ln2 >> 5;
;         float v[8];
; #pragma unroll
;         for (int e = 0; e < 8; ++e) { const int r = 8 * half + e; v[e] = rhs[(32 * ct + crow(r, h2)) * 132 + vcol]; }
;         u32x4 wu; wu.x = pk2(v[0], v[1]); wu.y = pk2(v[2], v[3]); wu.z = pk2(v[4], v[5]); wu.w = pk2(v[6], v[7]);
;         *(u32x4*)(gout + 4 * 8192 + idx * 16) = wu;
;         if (tid == 0) GL[item] = expf(glog);
	v_mfma_f32_16x16x4_f32 v[2:5], v6, v2, 0
	ds_read_b32 v6, v182 offset:19008
	s_waitcnt lgkmcnt(0)
	v_mfma_f32_16x16x4_f32 v[2:5], v7, v6, v[2:5]
	ds_read2_b32 v[6:7], v16 offset0:136 offset1:140
	ds_read_b32 v16, v182 offset:21120
	s_waitcnt lgkmcnt(0)
	v_mfma_f32_16x16x4_f32 v[2:5], v6, v16, v[2:5]
	ds_read_b32 v6, v182 offset:23232
	s_waitcnt lgkmcnt(0)
	v_mfma_f32_16x16x4_f32 v[2:5], v7, v6, v[2:5]
	s_nop 9
	ds_write_b32 v183, v2 offset:16896
	ds_write_b32 v183, v3 offset:17424
	ds_write_b32 v183, v4 offset:17952
	ds_write_b32 v183, v5 offset:18480
	v_add_u32_e32 v2, 0x6200, v183
	v_add_u32_e32 v4, 0x6600, v183
	ds_read2_b32 v[2:3], v2 offset0:64 offset1:196
	ds_read2_b32 v[4:5], v4 offset0:72 offset1:204
	s_waitcnt lgkmcnt(0)
	v_xor_b32_e32 v6, 0x80000000, v212
	s_waitcnt lgkmcnt(0)
	s_nop 0
	v_mfma_f32_16x16x4_f32 v[2:5], v6, v8, v[2:5]
	v_add_u32_e32 v8, 0xc00, v168
	s_waitcnt lgkmcnt(0)
	v_xor_b32_e32 v6, 0x80000000, v213
	s_nop 1
	v_mfma_f32_16x16x4_f32 v[2:5], v6, v9, v[2:5]
	s_waitcnt lgkmcnt(0)
	v_xor_b32_e32 v6, 0x80000000, v214
	s_nop 1
	v_mfma_f32_16x16x4_f32 v[2:5], v6, v10, v[2:5]
	s_waitcnt lgkmcnt(0)
	v_xor_b32_e32 v6, 0x80000000, v215
	s_nop 1
	v_mfma_f32_16x16x4_f32 v[2:5], v6, v11, v[2:5]
	s_waitcnt lgkmcnt(0)
	v_xor_b32_e32 v6, 0x80000000, v216
	s_nop 1
	v_mfma_f32_16x16x4_f32 v[2:5], v6, v12, v[2:5]
	s_waitcnt lgkmcnt(0)
	v_xor_b32_e32 v6, 0x80000000, v217
	s_nop 1
	v_mfma_f32_16x16x4_f32 v[2:5], v6, v13, v[2:5]
	s_waitcnt lgkmcnt(0)
	v_xor_b32_e32 v6, 0x80000000, v218
	s_nop 1
	v_mfma_f32_16x16x4_f32 v[2:5], v6, v14, v[2:5]
	s_waitcnt lgkmcnt(0)
	v_xor_b32_e32 v6, 0x80000000, v219
	s_nop 1
	v_mfma_f32_16x16x4_f32 v[2:5], v6, v15, v[2:5]
	ds_read_b32 v7, v182 offset:16896
	s_waitcnt lgkmcnt(0)
	v_xor_b32_e32 v6, 0x80000000, v220
	s_waitcnt lgkmcnt(0)
	s_nop 0
	v_mfma_f32_16x16x4_f32 v[2:5], v6, v7, v[2:5]
	ds_read_b32 v7, v182 offset:19008
	s_waitcnt lgkmcnt(0)
	v_xor_b32_e32 v6, 0x80000000, v221
	s_waitcnt lgkmcnt(0)
	s_nop 0
	v_mfma_f32_16x16x4_f32 v[2:5], v6, v7, v[2:5]
	ds_read_b32 v7, v182 offset:21120
	s_waitcnt lgkmcnt(0)
	v_xor_b32_e32 v6, 0x80000000, v222
	s_waitcnt lgkmcnt(0)
	s_nop 0
	v_mfma_f32_16x16x4_f32 v[2:5], v6, v7, v[2:5]
	ds_read_b32 v7, v182 offset:23232
	s_waitcnt lgkmcnt(0)
	v_xor_b32_e32 v6, 0x80000000, v223
	s_waitcnt lgkmcnt(0)
	s_nop 0
	v_mfma_f32_16x16x4_f32 v[2:5], v6, v7, v[2:5]
	s_nop 9
	ds_write_b32 v183, v2 offset:25344
	ds_write_b32 v183, v3 offset:25872
	ds_write_b32 v183, v4 offset:26400
	ds_write_b32 v183, v5 offset:26928
	ds_read2_b32 v[6:7], v8 offset0:192 offset1:196
	ds_read_b32 v2, v182 offset:25344
	s_waitcnt lgkmcnt(0)
	v_mfma_f32_16x16x4_f32 v[2:5], v6, v2, 0
	ds_read_b32 v6, v182 offset:27456
	s_waitcnt lgkmcnt(0)
	v_mfma_f32_16x16x4_f32 v[2:5], v7, v6, v[2:5]
	ds_read2_b32 v[6:7], v8 offset0:200 offset1:204
	ds_read_b32 v8, v182 offset:29568
	s_waitcnt lgkmcnt(0)
	v_mfma_f32_16x16x4_f32 v[2:5], v6, v8, v[2:5]
	ds_read_b32 v6, v182 offset:31680
	s_waitcnt lgkmcnt(0)
	v_mfma_f32_16x16x4_f32 v[2:5], v7, v6, v[2:5]
	s_nop 9
	ds_write_b32 v183, v2 offset:25344
	ds_write_b32 v183, v3 offset:25872
	ds_write_b32 v183, v4 offset:26400
	ds_write_b32 v183, v5 offset:26928
	s_waitcnt lgkmcnt(0)
	s_barrier
	s_cbranch_vccnz .LBB0_1744
	ds_read_b128 v[2:5], v169 offset:256
	ds_read_b128 v[6:9], v169 offset:288
	s_waitcnt lgkmcnt(1)
	v_xor_b32_e32 v3, 0x80000000, v3
	v_xor_b32_e32 v2, 0x80000000, v2
	v_xor_b32_e32 v4, 0x80000000, v4
	v_xor_b32_e32 v5, 0x80000000, v5
	v_cvt_pk_bf16_f32 v2, v2, v3
	v_cvt_pk_bf16_f32 v3, v4, v5
	s_waitcnt lgkmcnt(0)
	v_xor_b32_e32 v4, 0x80000000, v7
	v_xor_b32_e32 v5, 0x80000000, v6
	v_cvt_pk_bf16_f32 v4, v5, v4
	v_xor_b32_e32 v5, 0x80000000, v8
	v_xor_b32_e32 v6, 0x80000000, v9
	ds_read_b32 v8, v185
	ds_read_b32 v9, v186
	ds_read_b32 v10, v187
	ds_read_b32 v11, v188
	ds_read_b32 v12, v189
	ds_read_b32 v13, v190
	ds_read_b32 v14, v191
	ds_read_b32 v15, v192
	v_cvt_pk_bf16_f32 v5, v5, v6
	v_lshl_add_u64 v[6:7], s[16:17], 0, v[90:91]
	global_store_dwordx4 v[6:7], v[2:5], off
	v_add_co_u32_e32 v6, vcc, 0x8000, v6
	s_waitcnt lgkmcnt(6)
	v_cvt_pk_bf16_f32 v2, v8, v9
	s_waitcnt lgkmcnt(4)
	v_cvt_pk_bf16_f32 v3, v10, v11
	s_waitcnt lgkmcnt(2)
	v_cvt_pk_bf16_f32 v4, v12, v13
	s_waitcnt lgkmcnt(0)
	v_cvt_pk_bf16_f32 v5, v14, v15
	v_addc_co_u32_e32 v7, vcc, 0, v7, vcc
	global_store_dwordx4 v[6:7], v[2:5], off
	s_and_saveexec_b64 s[16:17], s[86:87]
	s_cbranch_execz .LBB0_1743
	v_mul_f32_e32 v2, 0x3fb8aa3b, v82
	v_rndne_f32_e32 v3, v2
	v_sub_f32_e32 v4, v2, v3
	v_fma_f32 v2, v82, s2, -v2
	v_fmac_f32_e32 v2, 0x32a5705f, v82
	v_add_f32_e32 v2, v4, v2
	v_exp_f32_e32 v2, v2
	v_cvt_i32_f32_e32 v3, v3
	s_lshl_b64 s[26:27], s[68:69], 2
	v_readlane_b32 s4, v247, 33
	v_cmp_ngt_f32_e32 vcc, s3, v82
	v_ldexp_f32 v2, v2, v3
	s_add_u32 s26, s4, s26
	v_readlane_b32 s4, v247, 34
	v_cndmask_b32_e32 v2, 0, v2, vcc
	v_cmp_nlt_f32_e32 vcc, s64, v82
	s_addc_u32 s27, s4, s27
	s_nop 0
	v_cndmask_b32_e32 v2, v193, v2, vcc
	global_store_dword v83, v2, s[26:27]
	s_branch .LBB0_1743

; #define LBAR() do { asm volatile("s_waitcnt lgkmcnt(0)" ::: "memory"); __builtin_amdgcn_s_barrier(); asm volatile("" ::: "memory"); } while (0)
; #define GZLOAD(ZR, chunk) do { const bf16_t* zp_ = proj + (size_t)(b * SEQ + (chunk) * 64 + lane) * NINP + C_GZ + h * 64 + 32 * hc; \
;         _Pragma("unroll") for (int k = 0; k < 4; ++k) ZR[k] = *(const u32x4*)(zp_ + 8 * k); } while (0)
; DI void gdn_scan(const Ctx& c, int bh, const unsigned char* gbase, const float* GL, bf16_t* proj, const float* normw) {
;     ...
;         for (int n = 0; n < 64; n += 2) {
;             LBAR(); if (n > 0) GHELP(n - 1, zB); GZLOAD(zB, n + 1);
;             LBAR(); GHELP(n, zA); { const int nx = n + 2 < 64 ? n + 2 : 63; GZLOAD(zA, nx); }
.LBB0_2172:
	s_waitcnt lgkmcnt(0)
	s_barrier
	s_waitcnt vmcnt(0)
	v_add_u32_e32 v3, 0x20600, v135
	ds_read_b128 v[48:51], v3
	ds_read_b128 v[36:39], v3 offset:16
	ds_read_b128 v[28:31], v3 offset:32
	ds_read_b128 v[16:19], v3 offset:48
	ds_read_b128 v[52:55], v3 offset:64
	ds_read_b128 v[40:43], v3 offset:80
	ds_read_b128 v[32:35], v3 offset:96
	ds_read_b128 v[24:27], v3 offset:112
	s_waitcnt lgkmcnt(6)
	v_and_b32_e32 v47, 0xffff0000, v36
	v_and_b32_e32 v46, 0xffff0000, v48
	v_lshlrev_b32_e32 v45, 16, v36
	v_lshlrev_b32_e32 v44, 16, v48
	v_pk_mul_f32 v[46:47], v[46:47], v[46:47]
	s_waitcnt lgkmcnt(4)
	v_and_b32_e32 v57, 0xffff0000, v16
	v_pk_fma_f32 v[44:45], v[44:45], v[44:45], v[46:47]
	v_lshlrev_b32_e32 v47, 16, v37
	v_lshlrev_b32_e32 v46, 16, v49
	v_pk_fma_f32 v[44:45], v[46:47], v[46:47], v[44:45]
	v_and_b32_e32 v47, 0xffff0000, v37
	v_and_b32_e32 v46, 0xffff0000, v49
	v_pk_fma_f32 v[44:45], v[46:47], v[46:47], v[44:45]
	v_lshlrev_b32_e32 v47, 16, v38
	v_lshlrev_b32_e32 v46, 16, v50
	v_pk_fma_f32 v[44:45], v[46:47], v[46:47], v[44:45]
	v_and_b32_e32 v47, 0xffff0000, v38
	v_and_b32_e32 v46, 0xffff0000, v50
	v_pk_fma_f32 v[44:45], v[46:47], v[46:47], v[44:45]
	v_lshlrev_b32_e32 v47, 16, v39
	v_lshlrev_b32_e32 v46, 16, v51
	v_pk_fma_f32 v[44:45], v[46:47], v[46:47], v[44:45]
	v_and_b32_e32 v47, 0xffff0000, v39
	v_and_b32_e32 v46, 0xffff0000, v51
	v_and_b32_e32 v56, 0xffff0000, v28
	v_pk_fma_f32 v[44:45], v[46:47], v[46:47], v[44:45]
	v_lshlrev_b32_e32 v47, 16, v16
	v_lshlrev_b32_e32 v46, 16, v28
	v_pk_mul_f32 v[56:57], v[56:57], v[56:57]
	s_waitcnt lgkmcnt(2)
	v_and_b32_e32 v59, 0xffff0000, v40
	v_pk_fma_f32 v[46:47], v[46:47], v[46:47], v[56:57]
	v_lshlrev_b32_e32 v57, 16, v17
	v_lshlrev_b32_e32 v56, 16, v29
	v_pk_fma_f32 v[46:47], v[56:57], v[56:57], v[46:47]
	v_and_b32_e32 v57, 0xffff0000, v17
	v_and_b32_e32 v56, 0xffff0000, v29
	v_pk_fma_f32 v[46:47], v[56:57], v[56:57], v[46:47]
	v_lshlrev_b32_e32 v57, 16, v18
	v_lshlrev_b32_e32 v56, 16, v30
	v_pk_fma_f32 v[46:47], v[56:57], v[56:57], v[46:47]
	v_and_b32_e32 v57, 0xffff0000, v18
	v_and_b32_e32 v56, 0xffff0000, v30
	v_pk_fma_f32 v[46:47], v[56:57], v[56:57], v[46:47]
	v_lshlrev_b32_e32 v57, 16, v19
	v_lshlrev_b32_e32 v56, 16, v31
	v_pk_fma_f32 v[46:47], v[56:57], v[56:57], v[46:47]
	v_and_b32_e32 v57, 0xffff0000, v19
	v_and_b32_e32 v56, 0xffff0000, v31
	v_and_b32_e32 v58, 0xffff0000, v52
	v_pk_fma_f32 v[46:47], v[56:57], v[56:57], v[46:47]
	v_lshlrev_b32_e32 v57, 16, v40
	v_lshlrev_b32_e32 v56, 16, v52
	v_pk_mul_f32 v[58:59], v[58:59], v[58:59]
	s_waitcnt lgkmcnt(0)
	v_and_b32_e32 v61, 0xffff0000, v24
	v_pk_fma_f32 v[56:57], v[56:57], v[56:57], v[58:59]
	v_lshlrev_b32_e32 v59, 16, v41
	v_lshlrev_b32_e32 v58, 16, v53
	v_pk_fma_f32 v[56:57], v[58:59], v[58:59], v[56:57]
	v_and_b32_e32 v59, 0xffff0000, v41
	v_and_b32_e32 v58, 0xffff0000, v53
	v_pk_fma_f32 v[56:57], v[58:59], v[58:59], v[56:57]
	v_lshlrev_b32_e32 v59, 16, v42
	v_lshlrev_b32_e32 v58, 16, v54
	v_pk_fma_f32 v[56:57], v[58:59], v[58:59], v[56:57]
	v_and_b32_e32 v59, 0xffff0000, v42
	v_and_b32_e32 v58, 0xffff0000, v54
	v_pk_fma_f32 v[56:57], v[58:59], v[58:59], v[56:57]
	v_lshlrev_b32_e32 v59, 16, v43
	v_lshlrev_b32_e32 v58, 16, v55
	v_pk_fma_f32 v[56:57], v[58:59], v[58:59], v[56:57]
	v_and_b32_e32 v59, 0xffff0000, v43
	v_and_b32_e32 v58, 0xffff0000, v55
	v_and_b32_e32 v60, 0xffff0000, v32
	v_pk_fma_f32 v[56:57], v[58:59], v[58:59], v[56:57]
	v_lshlrev_b32_e32 v59, 16, v24
	v_lshlrev_b32_e32 v58, 16, v32
	v_pk_mul_f32 v[60:61], v[60:61], v[60:61]
	v_add_f32_e32 v3, v44, v45
	v_pk_fma_f32 v[58:59], v[58:59], v[58:59], v[60:61]
	v_lshlrev_b32_e32 v61, 16, v25
	v_lshlrev_b32_e32 v60, 16, v33
	v_pk_fma_f32 v[58:59], v[60:61], v[60:61], v[58:59]
	v_and_b32_e32 v61, 0xffff0000, v25
	v_and_b32_e32 v60, 0xffff0000, v33
	v_pk_fma_f32 v[58:59], v[60:61], v[60:61], v[58:59]
	v_lshlrev_b32_e32 v61, 16, v26
	v_lshlrev_b32_e32 v60, 16, v34
	v_pk_fma_f32 v[58:59], v[60:61], v[60:61], v[58:59]
	v_and_b32_e32 v61, 0xffff0000, v26
	v_and_b32_e32 v60, 0xffff0000, v34
	v_add_f32_e32 v3, v3, v46
	v_pk_fma_f32 v[58:59], v[60:61], v[60:61], v[58:59]
	v_lshlrev_b32_e32 v61, 16, v27
	v_lshlrev_b32_e32 v60, 16, v35
	v_add_f32_e32 v3, v3, v47
	v_pk_fma_f32 v[58:59], v[60:61], v[60:61], v[58:59]
	v_and_b32_e32 v61, 0xffff0000, v27
	v_and_b32_e32 v60, 0xffff0000, v35
	v_add_f32_e32 v3, v3, v56
	v_pk_fma_f32 v[58:59], v[60:61], v[60:61], v[58:59]
	v_add_f32_e32 v3, v3, v57
	v_add_f32_e32 v3, v3, v58
	v_add_f32_e32 v3, v3, v59
	v_fmamk_f32 v3, v3, 0x3c800000, v134
	v_rsq_f32_e32 v46, v3
	v_or_b32_e32 v3, s12, v132
	v_mov_b64_e32 v[44:45], s[2:3]
	v_mad_i64_i32 v[44:45], s[8:9], v3, s79, v[44:45]
	v_mov_b32_e32 v3, s75
	ds_read_b128 v[56:59], v3
	ds_read_b128 v[60:63], v3 offset:16
	ds_read_b128 v[64:67], v3 offset:32
	ds_read_b128 v[68:71], v3 offset:48
	v_cndmask_b32_e64 v54, v54, v50, s[6:7]
	v_lshlrev_b32_e32 v50, 16, v20
	s_waitcnt lgkmcnt(2)
	v_pk_mul_f32 v[62:63], v[62:63], v[46:47] op_sel_hi:[1,0]
	v_pk_mul_f32 v[58:59], v[58:59], v[46:47] op_sel_hi:[1,0]
	v_pk_mul_f32 v[56:57], v[56:57], v[46:47] op_sel_hi:[1,0]
	v_pk_mul_f32 v[60:61], v[60:61], v[46:47] op_sel_hi:[1,0]
	v_cndmask_b32_e64 v47, v55, v51, s[6:7]
	v_and_b32_e32 v51, 0xffff0000, v20
	v_mul_f32_e32 v20, 0xbfb8aa3b, v50
	v_cndmask_b32_e64 v55, v53, v49, s[6:7]
	v_exp_f32_e32 v20, v20
	v_mul_f32_e32 v49, 0xbfb8aa3b, v51
	v_exp_f32_e32 v49, v49
	v_cndmask_b32_e64 v53, v52, v48, s[6:7]
	v_add_f32_e32 v20, 1.0, v20
	v_rcp_f32_e32 v48, v20
	v_add_f32_e32 v20, 1.0, v49
	v_rcp_f32_e32 v49, v20
	v_lshlrev_b32_e32 v52, 16, v53
	v_and_b32_e32 v53, 0xffff0000, v53
	v_pk_mul_f32 v[52:53], v[56:57], v[52:53]
	v_pk_mul_f32 v[48:49], v[48:49], v[50:51]
	v_lshlrev_b32_e32 v50, 16, v21
	v_and_b32_e32 v51, 0xffff0000, v21
	v_mul_f32_e32 v20, 0xbfb8aa3b, v50
	v_exp_f32_e32 v21, v20
	v_mul_f32_e32 v20, 0xbfb8aa3b, v51
	v_pk_mul_f32 v[48:49], v[48:49], v[52:53]
	v_exp_f32_e32 v52, v20
	v_add_f32_e32 v21, 1.0, v21
	v_cvt_pk_bf16_f32 v20, v48, v49
	v_rcp_f32_e32 v48, v21
	v_add_f32_e32 v21, 1.0, v52
	v_rcp_f32_e32 v49, v21
	v_lshlrev_b32_e32 v52, 16, v55
	v_and_b32_e32 v53, 0xffff0000, v55
	v_pk_mul_f32 v[52:53], v[58:59], v[52:53]
	v_pk_mul_f32 v[48:49], v[48:49], v[50:51]
	v_lshlrev_b32_e32 v50, 16, v22
	v_and_b32_e32 v51, 0xffff0000, v22
	v_mul_f32_e32 v21, 0xbfb8aa3b, v50
	v_exp_f32_e32 v22, v21
	v_mul_f32_e32 v21, 0xbfb8aa3b, v51
	v_pk_mul_f32 v[48:49], v[48:49], v[52:53]
	v_exp_f32_e32 v52, v21
	v_add_f32_e32 v22, 1.0, v22
	v_cvt_pk_bf16_f32 v21, v48, v49
	v_rcp_f32_e32 v48, v22
	v_add_f32_e32 v22, 1.0, v52
	v_rcp_f32_e32 v49, v22
	v_lshlrev_b32_e32 v52, 16, v54
	v_and_b32_e32 v53, 0xffff0000, v54
	v_pk_mul_f32 v[52:53], v[60:61], v[52:53]
	v_pk_mul_f32 v[48:49], v[48:49], v[50:51]
	v_lshlrev_b32_e32 v50, 16, v23
	v_and_b32_e32 v51, 0xffff0000, v23
	v_mul_f32_e32 v22, 0xbfb8aa3b, v50
	v_exp_f32_e32 v23, v22
	v_mul_f32_e32 v22, 0xbfb8aa3b, v51
	v_pk_mul_f32 v[48:49], v[48:49], v[52:53]
	v_exp_f32_e32 v52, v22
	v_add_f32_e32 v23, 1.0, v23
	v_cvt_pk_bf16_f32 v22, v48, v49
	v_rcp_f32_e32 v48, v23
	v_add_f32_e32 v23, 1.0, v52
	v_rcp_f32_e32 v49, v23
	v_lshlrev_b32_e32 v52, 16, v47
	v_and_b32_e32 v53, 0xffff0000, v47
	s_lshl_b32 s12, s64, 1
	v_pk_mul_f32 v[52:53], v[62:63], v[52:53]
	v_pk_mul_f32 v[48:49], v[48:49], v[50:51]
	v_lshl_add_u64 v[44:45], v[44:45], 0, s[12:13]
	v_pk_mul_f32 v[48:49], v[48:49], v[52:53]
	v_cndmask_b32_e64 v42, v42, v38, s[6:7]
	v_lshlrev_b32_e32 v38, 16, v12
	v_lshl_add_u64 v[44:45], s[20:21], 1, v[44:45]
	v_cvt_pk_bf16_f32 v23, v48, v49
	v_cndmask_b32_e64 v43, v43, v39, s[6:7]
	v_and_b32_e32 v39, 0xffff0000, v12
	v_mul_f32_e32 v12, 0xbfb8aa3b, v38
	global_store_dwordx4 v[44:45], v[20:23], off
	s_waitcnt lgkmcnt(0)
	v_pk_mul_f32 v[48:49], v[70:71], v[46:47] op_sel_hi:[1,0]
	v_pk_mul_f32 v[50:51], v[68:69], v[46:47] op_sel_hi:[1,0]
	v_pk_mul_f32 v[20:21], v[66:67], v[46:47] op_sel_hi:[1,0]
	v_pk_mul_f32 v[22:23], v[64:65], v[46:47] op_sel_hi:[1,0]
	v_cndmask_b32_e64 v47, v41, v37, s[6:7]
	v_exp_f32_e32 v12, v12
	v_mul_f32_e32 v37, 0xbfb8aa3b, v39
	v_exp_f32_e32 v37, v37
	v_cndmask_b32_e64 v41, v40, v36, s[6:7]
	v_add_f32_e32 v12, 1.0, v12
	v_rcp_f32_e32 v36, v12
	v_add_f32_e32 v12, 1.0, v37
	v_rcp_f32_e32 v37, v12
	v_lshlrev_b32_e32 v40, 16, v41
	v_and_b32_e32 v41, 0xffff0000, v41
	v_pk_mul_f32 v[22:23], v[22:23], v[40:41]
	v_pk_mul_f32 v[36:37], v[36:37], v[38:39]
	v_and_b32_e32 v39, 0xffff0000, v47
	v_pk_mul_f32 v[22:23], v[36:37], v[22:23]
	v_lshlrev_b32_e32 v36, 16, v13
	v_and_b32_e32 v37, 0xffff0000, v13
	v_mul_f32_e32 v12, 0xbfb8aa3b, v36
	v_exp_f32_e32 v13, v12
	v_mul_f32_e32 v12, 0xbfb8aa3b, v37
	v_exp_f32_e32 v38, v12
	v_cvt_pk_bf16_f32 v12, v22, v23
	v_add_f32_e32 v13, 1.0, v13
	v_rcp_f32_e32 v22, v13
	v_add_f32_e32 v13, 1.0, v38
	v_rcp_f32_e32 v23, v13
	v_lshlrev_b32_e32 v38, 16, v47
	v_pk_mul_f32 v[20:21], v[20:21], v[38:39]
	v_cndmask_b32_e64 v34, v34, v30, s[6:7]
	v_pk_mul_f32 v[22:23], v[22:23], v[36:37]
	v_and_b32_e32 v37, 0xffff0000, v42
	v_pk_mul_f32 v[20:21], v[22:23], v[20:21]
	v_lshlrev_b32_e32 v22, 16, v14
	v_and_b32_e32 v23, 0xffff0000, v14
	v_mul_f32_e32 v13, 0xbfb8aa3b, v22
	v_exp_f32_e32 v14, v13
	v_mul_f32_e32 v13, 0xbfb8aa3b, v23
	v_exp_f32_e32 v36, v13
	v_cvt_pk_bf16_f32 v13, v20, v21
	v_add_f32_e32 v14, 1.0, v14
	v_rcp_f32_e32 v20, v14
	v_add_f32_e32 v14, 1.0, v36
	v_rcp_f32_e32 v21, v14
	v_lshlrev_b32_e32 v36, 16, v42
	v_pk_mul_f32 v[36:37], v[50:51], v[36:37]
	v_lshlrev_b32_e32 v30, 16, v8
	v_pk_mul_f32 v[20:21], v[20:21], v[22:23]
	v_lshlrev_b32_e32 v22, 16, v15
	v_and_b32_e32 v23, 0xffff0000, v15
	v_mul_f32_e32 v14, 0xbfb8aa3b, v22
	v_exp_f32_e32 v15, v14
	v_mul_f32_e32 v14, 0xbfb8aa3b, v23
	v_pk_mul_f32 v[20:21], v[20:21], v[36:37]
	v_exp_f32_e32 v36, v14
	v_add_f32_e32 v15, 1.0, v15
	v_cvt_pk_bf16_f32 v14, v20, v21
	v_rcp_f32_e32 v20, v15
	v_add_f32_e32 v15, 1.0, v36
	v_rcp_f32_e32 v21, v15
	v_lshlrev_b32_e32 v36, 16, v43
	v_and_b32_e32 v37, 0xffff0000, v43
	v_pk_mul_f32 v[36:37], v[48:49], v[36:37]
	v_pk_mul_f32 v[38:39], v[20:21], v[22:23]
	ds_read_b128 v[20:23], v3 offset:64
	v_pk_mul_f32 v[40:41], v[38:39], v[36:37]
	ds_read_b128 v[36:39], v3 offset:80
	v_cvt_pk_bf16_f32 v15, v40, v41
	v_cndmask_b32_e64 v35, v35, v31, s[6:7]
	v_and_b32_e32 v31, 0xffff0000, v8
	v_mul_f32_e32 v8, 0xbfb8aa3b, v30
	global_store_dwordx4 v[44:45], v[12:15], off offset:16
	v_exp_f32_e32 v8, v8
	s_waitcnt lgkmcnt(1)
	v_pk_mul_f32 v[12:13], v[22:23], v[46:47] op_sel_hi:[1,0]
	s_waitcnt lgkmcnt(0)
	v_pk_mul_f32 v[22:23], v[36:37], v[46:47] op_sel_hi:[1,0]
	v_cndmask_b32_e64 v36, v33, v29, s[6:7]
	v_mul_f32_e32 v29, 0xbfb8aa3b, v31
	v_exp_f32_e32 v29, v29
	v_add_f32_e32 v8, 1.0, v8
	v_cndmask_b32_e64 v33, v32, v28, s[6:7]
	v_rcp_f32_e32 v28, v8
	v_add_f32_e32 v8, 1.0, v29
	v_rcp_f32_e32 v29, v8
	v_pk_mul_f32 v[14:15], v[20:21], v[46:47] op_sel_hi:[1,0]
	v_lshlrev_b32_e32 v32, 16, v33
	v_and_b32_e32 v33, 0xffff0000, v33
	v_pk_mul_f32 v[14:15], v[14:15], v[32:33]
	v_pk_mul_f32 v[28:29], v[28:29], v[30:31]
	v_and_b32_e32 v31, 0xffff0000, v36
	v_pk_mul_f32 v[14:15], v[28:29], v[14:15]
	v_lshlrev_b32_e32 v28, 16, v9
	v_and_b32_e32 v29, 0xffff0000, v9
	v_mul_f32_e32 v8, 0xbfb8aa3b, v28
	v_exp_f32_e32 v9, v8
	v_mul_f32_e32 v8, 0xbfb8aa3b, v29
	v_exp_f32_e32 v30, v8
	v_cvt_pk_bf16_f32 v8, v14, v15
	v_add_f32_e32 v9, 1.0, v9
	v_rcp_f32_e32 v14, v9
	v_add_f32_e32 v9, 1.0, v30
	v_rcp_f32_e32 v15, v9
	v_lshlrev_b32_e32 v30, 16, v36
	v_pk_mul_f32 v[12:13], v[12:13], v[30:31]
	v_pk_mul_f32 v[20:21], v[38:39], v[46:47] op_sel_hi:[1,0]
	v_pk_mul_f32 v[14:15], v[14:15], v[28:29]
	v_and_b32_e32 v29, 0xffff0000, v34
	v_pk_mul_f32 v[12:13], v[14:15], v[12:13]
	v_lshlrev_b32_e32 v14, 16, v10
	v_and_b32_e32 v15, 0xffff0000, v10
	v_mul_f32_e32 v9, 0xbfb8aa3b, v14
	v_exp_f32_e32 v10, v9
	v_mul_f32_e32 v9, 0xbfb8aa3b, v15
	v_exp_f32_e32 v28, v9
	v_cvt_pk_bf16_f32 v9, v12, v13
	v_add_f32_e32 v10, 1.0, v10
	v_rcp_f32_e32 v12, v10
	v_add_f32_e32 v10, 1.0, v28
	v_rcp_f32_e32 v13, v10
	v_lshlrev_b32_e32 v28, 16, v34
	v_pk_mul_f32 v[22:23], v[22:23], v[28:29]
	v_pk_mul_f32 v[12:13], v[12:13], v[14:15]
	v_lshlrev_b32_e32 v14, 16, v11
	v_and_b32_e32 v15, 0xffff0000, v11
	v_mul_f32_e32 v10, 0xbfb8aa3b, v14
	v_exp_f32_e32 v11, v10
	v_mul_f32_e32 v10, 0xbfb8aa3b, v15
	v_pk_mul_f32 v[12:13], v[12:13], v[22:23]
	v_exp_f32_e32 v22, v10
	v_add_f32_e32 v11, 1.0, v11
	v_cvt_pk_bf16_f32 v10, v12, v13
	v_rcp_f32_e32 v12, v11
	v_add_f32_e32 v11, 1.0, v22
	v_rcp_f32_e32 v13, v11
	v_lshlrev_b32_e32 v22, 16, v35
	v_and_b32_e32 v23, 0xffff0000, v35
	v_pk_mul_f32 v[20:21], v[20:21], v[22:23]
	v_pk_mul_f32 v[22:23], v[12:13], v[14:15]
	ds_read_b128 v[12:15], v3 offset:96
	v_pk_mul_f32 v[28:29], v[22:23], v[20:21]
	ds_read_b128 v[20:23], v3 offset:112
	v_cvt_pk_bf16_f32 v11, v28, v29
	global_store_dwordx4 v[44:45], v[8:11], off offset:32
	v_cndmask_b32_e64 v3, v27, v19, s[6:7]
	v_and_b32_e32 v19, 0xffff0000, v4
	s_waitcnt lgkmcnt(1)
	v_pk_mul_f32 v[10:11], v[12:13], v[46:47] op_sel_hi:[1,0]
	s_waitcnt lgkmcnt(0)
	v_pk_mul_f32 v[12:13], v[22:23], v[46:47] op_sel_hi:[1,0]
	v_cndmask_b32_e64 v22, v26, v18, s[6:7]
	v_lshlrev_b32_e32 v18, 16, v4
	v_mul_f32_e32 v4, 0xbfb8aa3b, v18
	v_cndmask_b32_e64 v23, v25, v17, s[6:7]
	v_exp_f32_e32 v4, v4
	v_mul_f32_e32 v17, 0xbfb8aa3b, v19
	v_exp_f32_e32 v17, v17
	v_pk_mul_f32 v[8:9], v[14:15], v[46:47] op_sel_hi:[1,0]
	v_add_f32_e32 v4, 1.0, v4
	v_pk_mul_f32 v[14:15], v[20:21], v[46:47] op_sel_hi:[1,0]
	v_cndmask_b32_e64 v21, v24, v16, s[6:7]
	v_rcp_f32_e32 v16, v4
	v_add_f32_e32 v4, 1.0, v17
	v_rcp_f32_e32 v17, v4
	v_lshlrev_b32_e32 v20, 16, v21
	v_and_b32_e32 v21, 0xffff0000, v21
	v_pk_mul_f32 v[10:11], v[10:11], v[20:21]
	v_pk_mul_f32 v[16:17], v[16:17], v[18:19]
	v_and_b32_e32 v19, 0xffff0000, v23
	v_pk_mul_f32 v[10:11], v[16:17], v[10:11]
	v_lshlrev_b32_e32 v16, 16, v5
	v_and_b32_e32 v17, 0xffff0000, v5
	v_mul_f32_e32 v4, 0xbfb8aa3b, v16
	v_exp_f32_e32 v5, v4
	v_mul_f32_e32 v4, 0xbfb8aa3b, v17
	v_exp_f32_e32 v18, v4
	v_cvt_pk_bf16_f32 v4, v10, v11
	v_add_f32_e32 v5, 1.0, v5
	v_rcp_f32_e32 v10, v5
	v_add_f32_e32 v5, 1.0, v18
	v_rcp_f32_e32 v11, v5
	v_lshlrev_b32_e32 v18, 16, v23
	v_pk_mul_f32 v[8:9], v[8:9], v[18:19]
	v_pk_mul_f32 v[10:11], v[10:11], v[16:17]
	s_nop 0
	v_pk_mul_f32 v[8:9], v[10:11], v[8:9]
	v_lshlrev_b32_e32 v10, 16, v6
	v_and_b32_e32 v11, 0xffff0000, v6
	v_mul_f32_e32 v5, 0xbfb8aa3b, v10
	v_exp_f32_e32 v6, v5
	v_mul_f32_e32 v5, 0xbfb8aa3b, v11
	v_exp_f32_e32 v16, v5
	v_cvt_pk_bf16_f32 v5, v8, v9
	v_add_f32_e32 v6, 1.0, v6
	v_rcp_f32_e32 v8, v6
	v_add_f32_e32 v6, 1.0, v16
	v_rcp_f32_e32 v9, v6
	v_lshlrev_b32_e32 v16, 16, v22
	v_and_b32_e32 v17, 0xffff0000, v22
	v_pk_mul_f32 v[14:15], v[14:15], v[16:17]
	v_pk_mul_f32 v[8:9], v[8:9], v[10:11]
	v_lshlrev_b32_e32 v10, 16, v7
	v_and_b32_e32 v11, 0xffff0000, v7
	v_mul_f32_e32 v6, 0xbfb8aa3b, v10
	v_exp_f32_e32 v7, v6
	v_mul_f32_e32 v6, 0xbfb8aa3b, v11
	v_pk_mul_f32 v[8:9], v[8:9], v[14:15]
	v_exp_f32_e32 v14, v6
	v_add_f32_e32 v7, 1.0, v7
	v_cvt_pk_bf16_f32 v6, v8, v9
	v_rcp_f32_e32 v8, v7
	v_add_f32_e32 v7, 1.0, v14
	v_rcp_f32_e32 v9, v7
	v_lshlrev_b32_e32 v14, 16, v3
	v_and_b32_e32 v15, 0xffff0000, v3
	v_pk_mul_f32 v[12:13], v[12:13], v[14:15]
	v_pk_mul_f32 v[8:9], v[8:9], v[10:11]
	s_nop 0
	v_pk_mul_f32 v[8:9], v[8:9], v[12:13]
	s_nop 0
	v_cvt_pk_bf16_f32 v7, v8, v9
	global_store_dwordx4 v[44:45], v[4:7], off offset:48

.LBB0_2195:
	s_nop 0
	v_add_u32_e32 v4, s33, v64
	v_mov_b64_e32 v[60:61], s[8:9]
	v_mad_i64_i32 v[20:21], s[82:83], v4, s79, v[60:61]
	global_load_dwordx4 v[4:7], v[20:21], off offset:3120
	global_load_dwordx4 v[8:11], v[20:21], off offset:3104
	global_load_dwordx4 v[12:15], v[20:21], off offset:3088
	s_nop 0
	global_load_dwordx4 v[20:23], v[20:21], off offset:3072
	s_waitcnt lgkmcnt(0)
	s_barrier
	v_add_u32_e32 v40, 0x1e200, v135
	ds_read_b128 v[66:69], v40
	ds_read_b128 v[52:55], v40 offset:16
	ds_read_b128 v[44:47], v40 offset:32
	ds_read_b128 v[36:39], v40 offset:48
	ds_read_b128 v[70:73], v40 offset:64
	ds_read_b128 v[56:59], v40 offset:80
	ds_read_b128 v[48:51], v40 offset:96
	ds_read_b128 v[40:43], v40 offset:112
	s_waitcnt lgkmcnt(0)
	v_and_b32_e32 v77, 0xffff0000, v52
	v_and_b32_e32 v76, 0xffff0000, v66
	v_lshlrev_b32_e32 v75, 16, v52
	v_lshlrev_b32_e32 v74, 16, v66
	v_pk_mul_f32 v[76:77], v[76:77], v[76:77]
	v_and_b32_e32 v79, 0xffff0000, v36
	v_pk_fma_f32 v[74:75], v[74:75], v[74:75], v[76:77]
	v_lshlrev_b32_e32 v77, 16, v53
	v_lshlrev_b32_e32 v76, 16, v67
	v_pk_fma_f32 v[74:75], v[76:77], v[76:77], v[74:75]
	v_and_b32_e32 v77, 0xffff0000, v53
	v_and_b32_e32 v76, 0xffff0000, v67
	v_pk_fma_f32 v[74:75], v[76:77], v[76:77], v[74:75]
	v_lshlrev_b32_e32 v77, 16, v54
	v_lshlrev_b32_e32 v76, 16, v68
	v_pk_fma_f32 v[74:75], v[76:77], v[76:77], v[74:75]
	v_and_b32_e32 v77, 0xffff0000, v54
	v_and_b32_e32 v76, 0xffff0000, v68
	v_pk_fma_f32 v[74:75], v[76:77], v[76:77], v[74:75]
	v_lshlrev_b32_e32 v77, 16, v55
	v_lshlrev_b32_e32 v76, 16, v69
	v_pk_fma_f32 v[74:75], v[76:77], v[76:77], v[74:75]
	v_and_b32_e32 v77, 0xffff0000, v55
	v_and_b32_e32 v76, 0xffff0000, v69
	v_and_b32_e32 v78, 0xffff0000, v44
	v_pk_fma_f32 v[74:75], v[76:77], v[76:77], v[74:75]
	v_lshlrev_b32_e32 v77, 16, v36
	v_lshlrev_b32_e32 v76, 16, v44
	v_pk_mul_f32 v[78:79], v[78:79], v[78:79]
	v_and_b32_e32 v81, 0xffff0000, v56
	v_pk_fma_f32 v[76:77], v[76:77], v[76:77], v[78:79]
	v_lshlrev_b32_e32 v79, 16, v37
	v_lshlrev_b32_e32 v78, 16, v45
	v_pk_fma_f32 v[76:77], v[78:79], v[78:79], v[76:77]
	v_and_b32_e32 v79, 0xffff0000, v37
	v_and_b32_e32 v78, 0xffff0000, v45
	v_pk_fma_f32 v[76:77], v[78:79], v[78:79], v[76:77]
	v_lshlrev_b32_e32 v79, 16, v38
	v_lshlrev_b32_e32 v78, 16, v46
	v_pk_fma_f32 v[76:77], v[78:79], v[78:79], v[76:77]
	v_and_b32_e32 v79, 0xffff0000, v38
	v_and_b32_e32 v78, 0xffff0000, v46
	v_pk_fma_f32 v[76:77], v[78:79], v[78:79], v[76:77]
	v_lshlrev_b32_e32 v79, 16, v39
	v_lshlrev_b32_e32 v78, 16, v47
	v_pk_fma_f32 v[76:77], v[78:79], v[78:79], v[76:77]
	v_and_b32_e32 v79, 0xffff0000, v39
	v_and_b32_e32 v78, 0xffff0000, v47
	v_and_b32_e32 v80, 0xffff0000, v70
	v_pk_fma_f32 v[76:77], v[78:79], v[78:79], v[76:77]
	v_lshlrev_b32_e32 v79, 16, v56
	v_lshlrev_b32_e32 v78, 16, v70
	v_pk_mul_f32 v[80:81], v[80:81], v[80:81]
	v_and_b32_e32 v83, 0xffff0000, v40
	v_pk_fma_f32 v[78:79], v[78:79], v[78:79], v[80:81]
	v_lshlrev_b32_e32 v81, 16, v57
	v_lshlrev_b32_e32 v80, 16, v71
	v_pk_fma_f32 v[78:79], v[80:81], v[80:81], v[78:79]
	v_and_b32_e32 v81, 0xffff0000, v57
	v_and_b32_e32 v80, 0xffff0000, v71
	v_pk_fma_f32 v[78:79], v[80:81], v[80:81], v[78:79]
	v_lshlrev_b32_e32 v81, 16, v58
	v_lshlrev_b32_e32 v80, 16, v72
	v_pk_fma_f32 v[78:79], v[80:81], v[80:81], v[78:79]
	v_and_b32_e32 v81, 0xffff0000, v58
	v_and_b32_e32 v80, 0xffff0000, v72
	v_pk_fma_f32 v[78:79], v[80:81], v[80:81], v[78:79]
	v_lshlrev_b32_e32 v81, 16, v59
	v_lshlrev_b32_e32 v80, 16, v73
	v_pk_fma_f32 v[78:79], v[80:81], v[80:81], v[78:79]
	v_and_b32_e32 v81, 0xffff0000, v59
	v_and_b32_e32 v80, 0xffff0000, v73
	v_and_b32_e32 v82, 0xffff0000, v48
	v_pk_fma_f32 v[78:79], v[80:81], v[80:81], v[78:79]
	v_lshlrev_b32_e32 v81, 16, v40
	v_lshlrev_b32_e32 v80, 16, v48
	v_pk_mul_f32 v[82:83], v[82:83], v[82:83]
	v_add_u32_e32 v65, s33, v63
	v_pk_fma_f32 v[80:81], v[80:81], v[80:81], v[82:83]
	v_lshlrev_b32_e32 v83, 16, v41
	v_lshlrev_b32_e32 v82, 16, v49
	v_pk_fma_f32 v[80:81], v[82:83], v[82:83], v[80:81]
	v_and_b32_e32 v83, 0xffff0000, v41
	v_and_b32_e32 v82, 0xffff0000, v49
	v_cndmask_b32_e64 v72, v72, v68, s[6:7]
	s_waitcnt vmcnt(4)
	v_lshlrev_b32_e32 v68, 16, v32
	v_pk_fma_f32 v[80:81], v[82:83], v[82:83], v[80:81]
	v_lshlrev_b32_e32 v83, 16, v42
	v_lshlrev_b32_e32 v82, 16, v50
	v_add_f32_e32 v62, v74, v75
	v_mad_i64_i32 v[60:61], s[82:83], v65, s79, v[60:61]
	v_cndmask_b32_e64 v65, v73, v69, s[6:7]
	v_and_b32_e32 v69, 0xffff0000, v32
	v_mul_f32_e32 v32, 0xbfb8aa3b, v68
	v_pk_fma_f32 v[80:81], v[82:83], v[82:83], v[80:81]
	v_and_b32_e32 v83, 0xffff0000, v42
	v_and_b32_e32 v82, 0xffff0000, v50
	v_add_f32_e32 v62, v62, v76
	v_cndmask_b32_e64 v73, v71, v67, s[6:7]
	v_exp_f32_e32 v32, v32
	v_mul_f32_e32 v67, 0xbfb8aa3b, v69
	v_pk_fma_f32 v[80:81], v[82:83], v[82:83], v[80:81]
	v_lshlrev_b32_e32 v83, 16, v43
	v_lshlrev_b32_e32 v82, 16, v51
	v_add_f32_e32 v62, v62, v77
	v_exp_f32_e32 v67, v67
	v_pk_fma_f32 v[80:81], v[82:83], v[82:83], v[80:81]
	v_and_b32_e32 v83, 0xffff0000, v43
	v_and_b32_e32 v82, 0xffff0000, v51
	v_add_f32_e32 v62, v62, v78
	v_pk_fma_f32 v[80:81], v[82:83], v[82:83], v[80:81]
	v_add_f32_e32 v62, v62, v79
	v_add_f32_e32 v62, v62, v80
	v_add_f32_e32 v32, 1.0, v32
	v_add_f32_e32 v62, v62, v81
	v_mov_b32_e32 v90, s75
	v_cndmask_b32_e64 v71, v70, v66, s[6:7]
	v_rcp_f32_e32 v66, v32
	v_add_f32_e32 v32, 1.0, v67
	v_fmamk_f32 v62, v62, 0x3c800000, v134
	ds_read_b128 v[74:77], v90
	v_rcp_f32_e32 v67, v32
	v_rsq_f32_e32 v62, v62
	v_lshlrev_b32_e32 v70, 16, v71
	v_and_b32_e32 v71, 0xffff0000, v71
	v_pk_mul_f32 v[66:67], v[66:67], v[68:69]
	v_lshlrev_b32_e32 v68, 16, v33
	s_waitcnt lgkmcnt(0)
	v_pk_mul_f32 v[74:75], v[74:75], v[62:63] op_sel_hi:[1,0]
	v_and_b32_e32 v69, 0xffff0000, v33
	v_mul_f32_e32 v32, 0xbfb8aa3b, v68
	v_pk_mul_f32 v[70:71], v[74:75], v[70:71]
	v_exp_f32_e32 v33, v32
	v_mul_f32_e32 v32, 0xbfb8aa3b, v69
	v_pk_mul_f32 v[66:67], v[66:67], v[70:71]
	v_exp_f32_e32 v70, v32
	v_add_f32_e32 v33, 1.0, v33
	v_cvt_pk_bf16_f32 v32, v66, v67
	v_rcp_f32_e32 v66, v33
	v_add_f32_e32 v33, 1.0, v70
	v_rcp_f32_e32 v67, v33
	v_pk_mul_f32 v[76:77], v[76:77], v[62:63] op_sel_hi:[1,0]
	v_lshlrev_b32_e32 v70, 16, v73
	v_and_b32_e32 v71, 0xffff0000, v73
	v_pk_mul_f32 v[66:67], v[66:67], v[68:69]
	v_lshlrev_b32_e32 v68, 16, v34
	v_and_b32_e32 v69, 0xffff0000, v34
	v_mul_f32_e32 v33, 0xbfb8aa3b, v68
	v_pk_mul_f32 v[70:71], v[76:77], v[70:71]
	v_exp_f32_e32 v34, v33
	v_mul_f32_e32 v33, 0xbfb8aa3b, v69
	v_pk_mul_f32 v[66:67], v[66:67], v[70:71]
	v_exp_f32_e32 v70, v33
	v_add_f32_e32 v34, 1.0, v34
	v_cvt_pk_bf16_f32 v33, v66, v67
	v_rcp_f32_e32 v66, v34
	v_add_f32_e32 v34, 1.0, v70
	v_rcp_f32_e32 v67, v34
	ds_read_b128 v[78:81], v90 offset:16
	ds_read_b128 v[82:85], v90 offset:32
	ds_read_b128 v[86:89], v90 offset:48
	v_lshlrev_b32_e32 v70, 16, v72
	v_and_b32_e32 v71, 0xffff0000, v72
	v_pk_mul_f32 v[66:67], v[66:67], v[68:69]
	v_lshlrev_b32_e32 v68, 16, v35
	s_waitcnt lgkmcnt(2)
	v_pk_mul_f32 v[78:79], v[78:79], v[62:63] op_sel_hi:[1,0]
	v_and_b32_e32 v69, 0xffff0000, v35
	v_mul_f32_e32 v34, 0xbfb8aa3b, v68
	v_pk_mul_f32 v[70:71], v[78:79], v[70:71]
	v_exp_f32_e32 v35, v34
	v_mul_f32_e32 v34, 0xbfb8aa3b, v69
	v_pk_mul_f32 v[66:67], v[66:67], v[70:71]
	v_exp_f32_e32 v70, v34
	v_cndmask_b32_e64 v58, v58, v54, s[6:7]
	v_lshlrev_b32_e32 v54, 16, v28
	v_add_f32_e32 v35, 1.0, v35
	v_cndmask_b32_e64 v59, v59, v55, s[6:7]
	v_and_b32_e32 v55, 0xffff0000, v28
	v_mul_f32_e32 v28, 0xbfb8aa3b, v54
	v_cvt_pk_bf16_f32 v34, v66, v67
	v_rcp_f32_e32 v66, v35
	v_add_f32_e32 v35, 1.0, v70
	v_lshlrev_b32_e32 v70, 16, v65
	v_and_b32_e32 v71, 0xffff0000, v65
	v_cndmask_b32_e64 v65, v57, v53, s[6:7]
	v_exp_f32_e32 v28, v28
	v_mul_f32_e32 v53, 0xbfb8aa3b, v55
	v_exp_f32_e32 v53, v53
	v_rcp_f32_e32 v67, v35
	v_add_f32_e32 v28, 1.0, v28
	v_pk_mul_f32 v[80:81], v[80:81], v[62:63] op_sel_hi:[1,0]
	v_cndmask_b32_e64 v57, v56, v52, s[6:7]
	v_rcp_f32_e32 v52, v28
	v_add_f32_e32 v28, 1.0, v53
	v_pk_mul_f32 v[70:71], v[80:81], v[70:71]
	v_pk_mul_f32 v[66:67], v[66:67], v[68:69]
	v_rcp_f32_e32 v53, v28
	v_pk_mul_f32 v[66:67], v[66:67], v[70:71]
	v_lshlrev_b32_e32 v56, 16, v57
	v_cvt_pk_bf16_f32 v35, v66, v67
	global_store_dwordx4 v[60:61], v[32:35], off
	v_and_b32_e32 v57, 0xffff0000, v57
	v_pk_mul_f32 v[52:53], v[52:53], v[54:55]
	s_waitcnt lgkmcnt(1)
	v_pk_mul_f32 v[34:35], v[82:83], v[62:63] op_sel_hi:[1,0]
	v_pk_mul_f32 v[32:33], v[84:85], v[62:63] op_sel_hi:[1,0]
	v_pk_mul_f32 v[34:35], v[34:35], v[56:57]
	v_and_b32_e32 v55, 0xffff0000, v65
	v_pk_mul_f32 v[34:35], v[52:53], v[34:35]
	v_lshlrev_b32_e32 v52, 16, v29
	v_and_b32_e32 v53, 0xffff0000, v29
	v_mul_f32_e32 v28, 0xbfb8aa3b, v52
	v_exp_f32_e32 v29, v28
	v_mul_f32_e32 v28, 0xbfb8aa3b, v53
	v_exp_f32_e32 v54, v28
	v_cvt_pk_bf16_f32 v28, v34, v35
	v_add_f32_e32 v29, 1.0, v29
	v_rcp_f32_e32 v34, v29
	v_add_f32_e32 v29, 1.0, v54
	v_rcp_f32_e32 v35, v29
	v_lshlrev_b32_e32 v54, 16, v65
	v_pk_mul_f32 v[32:33], v[32:33], v[54:55]
	s_waitcnt lgkmcnt(0)
	v_pk_mul_f32 v[68:69], v[86:87], v[62:63] op_sel_hi:[1,0]
	v_pk_mul_f32 v[34:35], v[34:35], v[52:53]
	v_and_b32_e32 v53, 0xffff0000, v58
	v_pk_mul_f32 v[32:33], v[34:35], v[32:33]
	v_lshlrev_b32_e32 v34, 16, v30
	v_and_b32_e32 v35, 0xffff0000, v30
	v_mul_f32_e32 v29, 0xbfb8aa3b, v34
	v_exp_f32_e32 v30, v29
	v_mul_f32_e32 v29, 0xbfb8aa3b, v35
	v_exp_f32_e32 v52, v29
	v_cvt_pk_bf16_f32 v29, v32, v33
	v_add_f32_e32 v30, 1.0, v30
	v_rcp_f32_e32 v32, v30
	v_add_f32_e32 v30, 1.0, v52
	v_rcp_f32_e32 v33, v30
	v_lshlrev_b32_e32 v52, 16, v58
	v_pk_mul_f32 v[52:53], v[68:69], v[52:53]
	v_pk_mul_f32 v[66:67], v[88:89], v[62:63] op_sel_hi:[1,0]
	v_pk_mul_f32 v[32:33], v[32:33], v[34:35]
	v_lshlrev_b32_e32 v34, 16, v31
	v_and_b32_e32 v35, 0xffff0000, v31
	v_mul_f32_e32 v30, 0xbfb8aa3b, v34
	v_exp_f32_e32 v31, v30
	v_mul_f32_e32 v30, 0xbfb8aa3b, v35
	v_pk_mul_f32 v[32:33], v[32:33], v[52:53]
	v_exp_f32_e32 v52, v30
	v_add_f32_e32 v31, 1.0, v31
	v_cvt_pk_bf16_f32 v30, v32, v33
	v_rcp_f32_e32 v32, v31
	v_add_f32_e32 v31, 1.0, v52
	v_rcp_f32_e32 v33, v31
	v_lshlrev_b32_e32 v52, 16, v59
	v_and_b32_e32 v53, 0xffff0000, v59
	v_pk_mul_f32 v[52:53], v[66:67], v[52:53]
	v_pk_mul_f32 v[54:55], v[32:33], v[34:35]
	ds_read_b128 v[32:35], v90 offset:64
	v_pk_mul_f32 v[56:57], v[54:55], v[52:53]
	ds_read_b128 v[52:55], v90 offset:80
	v_cndmask_b32_e64 v50, v50, v46, s[6:7]
	v_lshlrev_b32_e32 v46, 16, v24
	v_cvt_pk_bf16_f32 v31, v56, v57
	v_cndmask_b32_e64 v51, v51, v47, s[6:7]
	v_and_b32_e32 v47, 0xffff0000, v24
	v_mul_f32_e32 v24, 0xbfb8aa3b, v46
	global_store_dwordx4 v[60:61], v[28:31], off offset:16
	v_exp_f32_e32 v24, v24
	v_cndmask_b32_e64 v41, v41, v37, s[6:7]
	s_waitcnt lgkmcnt(1)
	v_pk_mul_f32 v[28:29], v[34:35], v[62:63] op_sel_hi:[1,0]
	s_waitcnt lgkmcnt(0)
; #define LBAR() do { asm volatile("s_waitcnt lgkmcnt(0)" ::: "memory"); __builtin_amdgcn_s_barrier(); asm volatile("" ::: "memory"); } while (0)
; #define GZLOAD(ZR, chunk) do { const bf16_t* zp_ = proj + (size_t)(b * SEQ + (chunk) * 64 + lane) * NINP + C_GZ + h * 64 + 32 * hc; \
;         _Pragma("unroll") for (int k = 0; k < 4; ++k) ZR[k] = *(const u32x4*)(zp_ + 8 * k); } while (0)
; DI void gdn_scan(const Ctx& c, int bh, const unsigned char* gbase, const float* GL, bf16_t* proj, const float* normw) {
;     ...
;         for (int n = 0; n < 64; n += 2) {
;             LBAR(); if (n > 0) GHELP(n - 1, zB); GZLOAD(zB, n + 1);
;             LBAR(); GHELP(n, zA); { const int nx = n + 2 < 64 ? n + 2 : 63; GZLOAD(zA, nx); }
	v_pk_mul_f32 v[34:35], v[52:53], v[62:63] op_sel_hi:[1,0]
	v_cndmask_b32_e64 v52, v49, v45, s[6:7]
	v_mul_f32_e32 v45, 0xbfb8aa3b, v47
	v_exp_f32_e32 v45, v45
	v_add_f32_e32 v24, 1.0, v24
	v_cndmask_b32_e64 v49, v48, v44, s[6:7]
	v_rcp_f32_e32 v44, v24
	v_add_f32_e32 v24, 1.0, v45
	v_rcp_f32_e32 v45, v24
	v_pk_mul_f32 v[30:31], v[32:33], v[62:63] op_sel_hi:[1,0]
	v_lshlrev_b32_e32 v48, 16, v49
	v_and_b32_e32 v49, 0xffff0000, v49
	v_pk_mul_f32 v[30:31], v[30:31], v[48:49]
	v_pk_mul_f32 v[44:45], v[44:45], v[46:47]
	v_and_b32_e32 v47, 0xffff0000, v52
	v_pk_mul_f32 v[30:31], v[44:45], v[30:31]
	v_lshlrev_b32_e32 v44, 16, v25
	v_and_b32_e32 v45, 0xffff0000, v25
	v_mul_f32_e32 v24, 0xbfb8aa3b, v44
	v_exp_f32_e32 v25, v24
	v_mul_f32_e32 v24, 0xbfb8aa3b, v45
	v_exp_f32_e32 v46, v24
	v_cvt_pk_bf16_f32 v24, v30, v31
	v_add_f32_e32 v25, 1.0, v25
	v_rcp_f32_e32 v30, v25
	v_add_f32_e32 v25, 1.0, v46
	v_rcp_f32_e32 v31, v25
	v_lshlrev_b32_e32 v46, 16, v52
	v_pk_mul_f32 v[28:29], v[28:29], v[46:47]
	v_pk_mul_f32 v[32:33], v[54:55], v[62:63] op_sel_hi:[1,0]
	v_pk_mul_f32 v[30:31], v[30:31], v[44:45]
	v_and_b32_e32 v45, 0xffff0000, v50
	v_pk_mul_f32 v[28:29], v[30:31], v[28:29]
	v_lshlrev_b32_e32 v30, 16, v26
	v_and_b32_e32 v31, 0xffff0000, v26
	v_mul_f32_e32 v25, 0xbfb8aa3b, v30
	v_exp_f32_e32 v26, v25
	v_mul_f32_e32 v25, 0xbfb8aa3b, v31
	v_exp_f32_e32 v44, v25
	v_cvt_pk_bf16_f32 v25, v28, v29
	v_add_f32_e32 v26, 1.0, v26
	v_rcp_f32_e32 v28, v26
	v_add_f32_e32 v26, 1.0, v44
	v_rcp_f32_e32 v29, v26
	v_lshlrev_b32_e32 v44, 16, v50
	v_pk_mul_f32 v[34:35], v[34:35], v[44:45]
	v_cndmask_b32_e64 v37, v40, v36, s[6:7]
	v_pk_mul_f32 v[28:29], v[28:29], v[30:31]
	v_lshlrev_b32_e32 v30, 16, v27
	v_and_b32_e32 v31, 0xffff0000, v27
	v_mul_f32_e32 v26, 0xbfb8aa3b, v30
	v_exp_f32_e32 v27, v26
	v_mul_f32_e32 v26, 0xbfb8aa3b, v31
	v_pk_mul_f32 v[28:29], v[28:29], v[34:35]
	v_exp_f32_e32 v34, v26
	v_add_f32_e32 v27, 1.0, v27
	v_cvt_pk_bf16_f32 v26, v28, v29
	v_rcp_f32_e32 v28, v27
	v_add_f32_e32 v27, 1.0, v34
	v_rcp_f32_e32 v29, v27
	v_lshlrev_b32_e32 v34, 16, v51
	v_and_b32_e32 v35, 0xffff0000, v51
	v_pk_mul_f32 v[32:33], v[32:33], v[34:35]
	v_pk_mul_f32 v[34:35], v[28:29], v[30:31]
	ds_read_b128 v[28:31], v90 offset:96
	v_pk_mul_f32 v[44:45], v[34:35], v[32:33]
	ds_read_b128 v[32:35], v90 offset:112
	v_cvt_pk_bf16_f32 v27, v44, v45
	global_store_dwordx4 v[60:61], v[24:27], off offset:32
	v_lshlrev_b32_e32 v36, 16, v37
	v_and_b32_e32 v37, 0xffff0000, v37
	s_waitcnt lgkmcnt(1)
	v_pk_mul_f32 v[24:25], v[30:31], v[62:63] op_sel_hi:[1,0]
	s_waitcnt lgkmcnt(0)
	v_pk_mul_f32 v[30:31], v[32:33], v[62:63] op_sel_hi:[1,0]
	v_lshlrev_b32_e32 v32, 16, v16
	v_and_b32_e32 v33, 0xffff0000, v16
	v_mul_f32_e32 v16, 0xbfb8aa3b, v32
	v_pk_mul_f32 v[26:27], v[28:29], v[62:63] op_sel_hi:[1,0]
	v_pk_mul_f32 v[28:29], v[34:35], v[62:63] op_sel_hi:[1,0]
	v_exp_f32_e32 v16, v16
	v_mul_f32_e32 v34, 0xbfb8aa3b, v33
	v_exp_f32_e32 v35, v34
	v_pk_mul_f32 v[26:27], v[26:27], v[36:37]
	v_add_f32_e32 v16, 1.0, v16
	v_rcp_f32_e32 v34, v16
	v_add_f32_e32 v16, 1.0, v35
	v_rcp_f32_e32 v35, v16
	v_cndmask_b32_e64 v38, v42, v38, s[6:7]
	v_cndmask_b32_e64 v39, v43, v39, s[6:7]
	s_add_i32 s33, s66, 2
	v_pk_mul_f32 v[32:33], v[34:35], v[32:33]
	v_and_b32_e32 v35, 0xffff0000, v41
	v_pk_mul_f32 v[26:27], v[32:33], v[26:27]
	v_lshlrev_b32_e32 v32, 16, v17
	v_and_b32_e32 v33, 0xffff0000, v17
	v_mul_f32_e32 v16, 0xbfb8aa3b, v32
	v_exp_f32_e32 v17, v16
	v_mul_f32_e32 v16, 0xbfb8aa3b, v33
	v_exp_f32_e32 v34, v16
	v_cvt_pk_bf16_f32 v16, v26, v27
	v_add_f32_e32 v17, 1.0, v17
	v_rcp_f32_e32 v26, v17
	v_add_f32_e32 v17, 1.0, v34
	v_rcp_f32_e32 v27, v17
	v_lshlrev_b32_e32 v34, 16, v41
	v_pk_mul_f32 v[24:25], v[24:25], v[34:35]
	s_addk_i32 s65, 0x80
	v_pk_mul_f32 v[26:27], v[26:27], v[32:33]
	v_and_b32_e32 v33, 0xffff0000, v38
	v_pk_mul_f32 v[24:25], v[26:27], v[24:25]
	v_lshlrev_b32_e32 v26, 16, v18
	v_and_b32_e32 v27, 0xffff0000, v18
	v_mul_f32_e32 v17, 0xbfb8aa3b, v26
	v_exp_f32_e32 v18, v17
	v_mul_f32_e32 v17, 0xbfb8aa3b, v27
	v_exp_f32_e32 v32, v17
	v_cvt_pk_bf16_f32 v17, v24, v25
	v_add_f32_e32 v18, 1.0, v18
	v_rcp_f32_e32 v24, v18
	v_add_f32_e32 v18, 1.0, v32
	v_rcp_f32_e32 v25, v18
	v_lshlrev_b32_e32 v32, 16, v38
	v_pk_mul_f32 v[30:31], v[30:31], v[32:33]
	s_cmp_lt_u32 s66, 62
	v_pk_mul_f32 v[24:25], v[24:25], v[26:27]
	v_lshlrev_b32_e32 v26, 16, v19
	v_and_b32_e32 v27, 0xffff0000, v19
	v_mul_f32_e32 v18, 0xbfb8aa3b, v26
	v_exp_f32_e32 v19, v18
	v_mul_f32_e32 v18, 0xbfb8aa3b, v27
	v_pk_mul_f32 v[24:25], v[24:25], v[30:31]
	v_exp_f32_e32 v30, v18
	v_add_f32_e32 v19, 1.0, v19
	v_cvt_pk_bf16_f32 v18, v24, v25
	v_rcp_f32_e32 v24, v19
	v_add_f32_e32 v19, 1.0, v30
	v_rcp_f32_e32 v25, v19
	v_lshlrev_b32_e32 v30, 16, v39
	v_and_b32_e32 v31, 0xffff0000, v39
	v_pk_mul_f32 v[28:29], v[28:29], v[30:31]
	v_pk_mul_f32 v[24:25], v[24:25], v[26:27]
	s_cselect_b32 s67, s65, 0xfc0
	v_pk_mul_f32 v[24:25], v[24:25], v[28:29]
	s_cmp_gt_u32 s66, 61
	v_cvt_pk_bf16_f32 v19, v24, v25
	global_store_dwordx4 v[60:61], v[16:19], off offset:48
	s_mov_b32 s66, s33
	s_nop 0
	v_add_u32_e32 v16, s67, v63
	s_cbranch_scc1 .LBB0_2172
.LBB0_2196:
	v_mov_b64_e32 v[18:19], s[8:9]
	v_mad_i64_i32 v[32:33], s[82:83], v16, s79, v[18:19]
	global_load_dwordx4 v[16:19], v[32:33], off offset:3120
	global_load_dwordx4 v[24:27], v[32:33], off offset:3104
	global_load_dwordx4 v[28:31], v[32:33], off offset:3088
	s_nop 0
	global_load_dwordx4 v[32:35], v[32:33], off offset:3072
	s_waitcnt lgkmcnt(0)
	s_barrier
	s_cmp_eq_u32 s65, 0
	s_mov_b32 s33, 0
	s_cbranch_scc1 .LBB0_2195
	v_add_u32_e32 v40, 0x20600, v135
	ds_read_b128 v[66:69], v40
	ds_read_b128 v[52:55], v40 offset:16
	ds_read_b128 v[44:47], v40 offset:32
	ds_read_b128 v[36:39], v40 offset:48
	ds_read_b128 v[70:73], v40 offset:64
	ds_read_b128 v[56:59], v40 offset:80
	ds_read_b128 v[48:51], v40 offset:96
	ds_read_b128 v[40:43], v40 offset:112
	s_waitcnt lgkmcnt(0)
	s_waitcnt vmcnt(4)
	v_and_b32_e32 v75, 0xffff0000, v52
	v_and_b32_e32 v74, 0xffff0000, v66
	v_lshlrev_b32_e32 v61, 16, v52
	v_lshlrev_b32_e32 v60, 16, v66
	v_pk_mul_f32 v[74:75], v[74:75], v[74:75]
	v_and_b32_e32 v77, 0xffff0000, v36
	v_pk_fma_f32 v[60:61], v[60:61], v[60:61], v[74:75]
	v_lshlrev_b32_e32 v75, 16, v53
	v_lshlrev_b32_e32 v74, 16, v67
	v_pk_fma_f32 v[60:61], v[74:75], v[74:75], v[60:61]
	v_and_b32_e32 v75, 0xffff0000, v53
	v_and_b32_e32 v74, 0xffff0000, v67
	v_pk_fma_f32 v[60:61], v[74:75], v[74:75], v[60:61]
	v_lshlrev_b32_e32 v75, 16, v54
	v_lshlrev_b32_e32 v74, 16, v68
	v_pk_fma_f32 v[60:61], v[74:75], v[74:75], v[60:61]
	v_and_b32_e32 v75, 0xffff0000, v54
	v_and_b32_e32 v74, 0xffff0000, v68
	v_pk_fma_f32 v[60:61], v[74:75], v[74:75], v[60:61]
	v_lshlrev_b32_e32 v75, 16, v55
	v_lshlrev_b32_e32 v74, 16, v69
	v_pk_fma_f32 v[60:61], v[74:75], v[74:75], v[60:61]
	v_and_b32_e32 v75, 0xffff0000, v55
	v_and_b32_e32 v74, 0xffff0000, v69
	v_and_b32_e32 v76, 0xffff0000, v44
	v_pk_fma_f32 v[60:61], v[74:75], v[74:75], v[60:61]
	v_lshlrev_b32_e32 v75, 16, v36
	v_lshlrev_b32_e32 v74, 16, v44
	v_pk_mul_f32 v[76:77], v[76:77], v[76:77]
	v_and_b32_e32 v79, 0xffff0000, v56
	v_pk_fma_f32 v[74:75], v[74:75], v[74:75], v[76:77]
	v_lshlrev_b32_e32 v77, 16, v37
	v_lshlrev_b32_e32 v76, 16, v45
	v_pk_fma_f32 v[74:75], v[76:77], v[76:77], v[74:75]
	v_and_b32_e32 v77, 0xffff0000, v37
	v_and_b32_e32 v76, 0xffff0000, v45
	v_pk_fma_f32 v[74:75], v[76:77], v[76:77], v[74:75]
	v_lshlrev_b32_e32 v77, 16, v38
	v_lshlrev_b32_e32 v76, 16, v46
	v_pk_fma_f32 v[74:75], v[76:77], v[76:77], v[74:75]
	v_and_b32_e32 v77, 0xffff0000, v38
	v_and_b32_e32 v76, 0xffff0000, v46
	v_pk_fma_f32 v[74:75], v[76:77], v[76:77], v[74:75]
	v_lshlrev_b32_e32 v77, 16, v39
	v_lshlrev_b32_e32 v76, 16, v47
	v_pk_fma_f32 v[74:75], v[76:77], v[76:77], v[74:75]
	v_and_b32_e32 v77, 0xffff0000, v39
	v_and_b32_e32 v76, 0xffff0000, v47
	v_and_b32_e32 v78, 0xffff0000, v70
	v_pk_fma_f32 v[74:75], v[76:77], v[76:77], v[74:75]
	v_lshlrev_b32_e32 v77, 16, v56
	v_lshlrev_b32_e32 v76, 16, v70
	v_pk_mul_f32 v[78:79], v[78:79], v[78:79]
	v_and_b32_e32 v81, 0xffff0000, v40
	v_pk_fma_f32 v[76:77], v[76:77], v[76:77], v[78:79]
	v_lshlrev_b32_e32 v79, 16, v57
	v_lshlrev_b32_e32 v78, 16, v71
	v_pk_fma_f32 v[76:77], v[78:79], v[78:79], v[76:77]
	v_and_b32_e32 v79, 0xffff0000, v57
	v_and_b32_e32 v78, 0xffff0000, v71
	v_pk_fma_f32 v[76:77], v[78:79], v[78:79], v[76:77]
	v_lshlrev_b32_e32 v79, 16, v58
	v_lshlrev_b32_e32 v78, 16, v72
	v_pk_fma_f32 v[76:77], v[78:79], v[78:79], v[76:77]
	v_and_b32_e32 v79, 0xffff0000, v58
	v_and_b32_e32 v78, 0xffff0000, v72
	v_pk_fma_f32 v[76:77], v[78:79], v[78:79], v[76:77]
	v_lshlrev_b32_e32 v79, 16, v59
	v_lshlrev_b32_e32 v78, 16, v73
	v_pk_fma_f32 v[76:77], v[78:79], v[78:79], v[76:77]
	v_and_b32_e32 v79, 0xffff0000, v59
	v_and_b32_e32 v78, 0xffff0000, v73
	v_and_b32_e32 v80, 0xffff0000, v48
	v_pk_fma_f32 v[76:77], v[78:79], v[78:79], v[76:77]
	v_lshlrev_b32_e32 v79, 16, v40
	v_lshlrev_b32_e32 v78, 16, v48
	v_pk_mul_f32 v[80:81], v[80:81], v[80:81]
	v_add_f32_e32 v60, v60, v61
	v_pk_fma_f32 v[78:79], v[78:79], v[78:79], v[80:81]
	v_lshlrev_b32_e32 v81, 16, v41
	v_lshlrev_b32_e32 v80, 16, v49
	v_pk_fma_f32 v[78:79], v[80:81], v[80:81], v[78:79]
	v_and_b32_e32 v81, 0xffff0000, v41
	v_and_b32_e32 v80, 0xffff0000, v49
	v_pk_fma_f32 v[78:79], v[80:81], v[80:81], v[78:79]
	v_lshlrev_b32_e32 v81, 16, v42
	v_lshlrev_b32_e32 v80, 16, v50
	v_pk_fma_f32 v[78:79], v[80:81], v[80:81], v[78:79]
	v_and_b32_e32 v81, 0xffff0000, v42
	v_and_b32_e32 v80, 0xffff0000, v50
	v_add_f32_e32 v60, v60, v74
	v_pk_fma_f32 v[78:79], v[80:81], v[80:81], v[78:79]
	v_lshlrev_b32_e32 v81, 16, v43
	v_lshlrev_b32_e32 v80, 16, v51
	v_add_f32_e32 v60, v60, v75
	v_pk_fma_f32 v[78:79], v[80:81], v[80:81], v[78:79]
	v_and_b32_e32 v81, 0xffff0000, v43
	v_and_b32_e32 v80, 0xffff0000, v51
	v_add_f32_e32 v60, v60, v76
	v_pk_fma_f32 v[78:79], v[80:81], v[80:81], v[78:79]
	v_add_f32_e32 v60, v60, v77
	v_add_f32_e32 v60, v60, v78
	v_add_f32_e32 v60, v60, v79
	v_fmamk_f32 v60, v60, 0x3c800000, v134
	v_rsq_f32_e32 v62, v60
	v_add_u32_e32 v65, s65, v3
	v_mov_b64_e32 v[60:61], s[8:9]
	v_cndmask_b32_e64 v72, v72, v68, s[6:7]
	v_lshlrev_b32_e32 v68, 16, v20
	v_mad_i64_i32 v[60:61], s[82:83], v65, s79, v[60:61]
	v_cndmask_b32_e64 v65, v73, v69, s[6:7]
	v_and_b32_e32 v69, 0xffff0000, v20
	v_mul_f32_e32 v20, 0xbfb8aa3b, v68
	v_cndmask_b32_e64 v73, v71, v67, s[6:7]
	v_exp_f32_e32 v20, v20
	v_mul_f32_e32 v67, 0xbfb8aa3b, v69
	v_exp_f32_e32 v67, v67
	v_mov_b32_e32 v90, s75
	v_add_f32_e32 v20, 1.0, v20
	v_cndmask_b32_e64 v71, v70, v66, s[6:7]
	v_rcp_f32_e32 v66, v20
	v_add_f32_e32 v20, 1.0, v67
	ds_read_b128 v[74:77], v90
	v_rcp_f32_e32 v67, v20
	v_lshlrev_b32_e32 v70, 16, v71
	v_and_b32_e32 v71, 0xffff0000, v71
	ds_read_b128 v[78:81], v90 offset:16
	ds_read_b128 v[82:85], v90 offset:32
	ds_read_b128 v[86:89], v90 offset:48
	v_pk_mul_f32 v[66:67], v[66:67], v[68:69]
	v_lshlrev_b32_e32 v68, 16, v21
	s_waitcnt lgkmcnt(0)
	v_pk_mul_f32 v[74:75], v[74:75], v[62:63] op_sel_hi:[1,0]
	v_and_b32_e32 v69, 0xffff0000, v21
	v_mul_f32_e32 v20, 0xbfb8aa3b, v68
	v_pk_mul_f32 v[70:71], v[74:75], v[70:71]
	v_exp_f32_e32 v21, v20
	v_mul_f32_e32 v20, 0xbfb8aa3b, v69
	v_pk_mul_f32 v[66:67], v[66:67], v[70:71]
	v_exp_f32_e32 v70, v20
	v_add_f32_e32 v21, 1.0, v21
	v_cvt_pk_bf16_f32 v20, v66, v67
	v_rcp_f32_e32 v66, v21
	v_add_f32_e32 v21, 1.0, v70
	v_rcp_f32_e32 v67, v21
	v_pk_mul_f32 v[76:77], v[76:77], v[62:63] op_sel_hi:[1,0]
	v_lshlrev_b32_e32 v70, 16, v73
	v_and_b32_e32 v71, 0xffff0000, v73
	v_pk_mul_f32 v[66:67], v[66:67], v[68:69]
	v_lshlrev_b32_e32 v68, 16, v22
	v_and_b32_e32 v69, 0xffff0000, v22
	v_mul_f32_e32 v21, 0xbfb8aa3b, v68
	v_pk_mul_f32 v[70:71], v[76:77], v[70:71]
	v_exp_f32_e32 v22, v21
	v_mul_f32_e32 v21, 0xbfb8aa3b, v69
	v_pk_mul_f32 v[66:67], v[66:67], v[70:71]
	v_exp_f32_e32 v70, v21
	v_add_f32_e32 v22, 1.0, v22
	v_cvt_pk_bf16_f32 v21, v66, v67
	v_rcp_f32_e32 v66, v22
	v_add_f32_e32 v22, 1.0, v70
	v_rcp_f32_e32 v67, v22
	v_pk_mul_f32 v[78:79], v[78:79], v[62:63] op_sel_hi:[1,0]
	v_lshlrev_b32_e32 v70, 16, v72
	v_and_b32_e32 v71, 0xffff0000, v72
	v_pk_mul_f32 v[66:67], v[66:67], v[68:69]
	v_lshlrev_b32_e32 v68, 16, v23
	v_and_b32_e32 v69, 0xffff0000, v23
	v_mul_f32_e32 v22, 0xbfb8aa3b, v68
	v_pk_mul_f32 v[70:71], v[78:79], v[70:71]
	v_exp_f32_e32 v23, v22
	v_mul_f32_e32 v22, 0xbfb8aa3b, v69
	v_pk_mul_f32 v[66:67], v[66:67], v[70:71]
	v_exp_f32_e32 v70, v22
	v_cndmask_b32_e64 v58, v58, v54, s[6:7]
	v_lshlrev_b32_e32 v54, 16, v12
	v_add_f32_e32 v23, 1.0, v23
	v_cndmask_b32_e64 v59, v59, v55, s[6:7]
	v_and_b32_e32 v55, 0xffff0000, v12
	v_mul_f32_e32 v12, 0xbfb8aa3b, v54
	v_cvt_pk_bf16_f32 v22, v66, v67
	v_rcp_f32_e32 v66, v23
	v_add_f32_e32 v23, 1.0, v70
	v_lshlrev_b32_e32 v70, 16, v65
	v_and_b32_e32 v71, 0xffff0000, v65
	v_cndmask_b32_e64 v65, v57, v53, s[6:7]
	v_exp_f32_e32 v12, v12
	v_mul_f32_e32 v53, 0xbfb8aa3b, v55
	v_exp_f32_e32 v53, v53
	v_rcp_f32_e32 v67, v23
	v_add_f32_e32 v12, 1.0, v12
	v_pk_mul_f32 v[80:81], v[80:81], v[62:63] op_sel_hi:[1,0]
	v_cndmask_b32_e64 v57, v56, v52, s[6:7]
	v_rcp_f32_e32 v52, v12
	v_add_f32_e32 v12, 1.0, v53
	v_pk_mul_f32 v[70:71], v[80:81], v[70:71]
	v_pk_mul_f32 v[66:67], v[66:67], v[68:69]
	v_rcp_f32_e32 v53, v12
	v_pk_mul_f32 v[66:67], v[66:67], v[70:71]
	v_lshlrev_b32_e32 v56, 16, v57
	v_cvt_pk_bf16_f32 v23, v66, v67
	global_store_dwordx4 v[60:61], v[20:23], off
	v_and_b32_e32 v57, 0xffff0000, v57
	v_pk_mul_f32 v[52:53], v[52:53], v[54:55]
	v_pk_mul_f32 v[22:23], v[82:83], v[62:63] op_sel_hi:[1,0]
	v_pk_mul_f32 v[20:21], v[84:85], v[62:63] op_sel_hi:[1,0]
	v_pk_mul_f32 v[22:23], v[22:23], v[56:57]
	v_and_b32_e32 v55, 0xffff0000, v65
	v_pk_mul_f32 v[22:23], v[52:53], v[22:23]
	v_lshlrev_b32_e32 v52, 16, v13
	v_and_b32_e32 v53, 0xffff0000, v13
	v_mul_f32_e32 v12, 0xbfb8aa3b, v52
	v_exp_f32_e32 v13, v12
	v_mul_f32_e32 v12, 0xbfb8aa3b, v53
	v_exp_f32_e32 v54, v12
	v_cvt_pk_bf16_f32 v12, v22, v23
	v_add_f32_e32 v13, 1.0, v13
	v_rcp_f32_e32 v22, v13
	v_add_f32_e32 v13, 1.0, v54
	v_rcp_f32_e32 v23, v13
	v_lshlrev_b32_e32 v54, 16, v65
	v_pk_mul_f32 v[20:21], v[20:21], v[54:55]
	v_pk_mul_f32 v[68:69], v[86:87], v[62:63] op_sel_hi:[1,0]
	v_pk_mul_f32 v[22:23], v[22:23], v[52:53]
	v_and_b32_e32 v53, 0xffff0000, v58
	v_pk_mul_f32 v[20:21], v[22:23], v[20:21]
	v_lshlrev_b32_e32 v22, 16, v14
	v_and_b32_e32 v23, 0xffff0000, v14
	v_mul_f32_e32 v13, 0xbfb8aa3b, v22
	v_exp_f32_e32 v14, v13
	v_mul_f32_e32 v13, 0xbfb8aa3b, v23
	v_exp_f32_e32 v52, v13
	v_cvt_pk_bf16_f32 v13, v20, v21
	v_add_f32_e32 v14, 1.0, v14
	v_rcp_f32_e32 v20, v14
	v_add_f32_e32 v14, 1.0, v52
	v_rcp_f32_e32 v21, v14
	v_lshlrev_b32_e32 v52, 16, v58
	v_pk_mul_f32 v[52:53], v[68:69], v[52:53]
	v_pk_mul_f32 v[66:67], v[88:89], v[62:63] op_sel_hi:[1,0]
	v_pk_mul_f32 v[20:21], v[20:21], v[22:23]
	v_lshlrev_b32_e32 v22, 16, v15
	v_and_b32_e32 v23, 0xffff0000, v15
	v_mul_f32_e32 v14, 0xbfb8aa3b, v22
	v_exp_f32_e32 v15, v14
	v_mul_f32_e32 v14, 0xbfb8aa3b, v23
	v_pk_mul_f32 v[20:21], v[20:21], v[52:53]
	v_exp_f32_e32 v52, v14
	v_add_f32_e32 v15, 1.0, v15
	v_cvt_pk_bf16_f32 v14, v20, v21
	v_rcp_f32_e32 v20, v15
	v_add_f32_e32 v15, 1.0, v52
	v_rcp_f32_e32 v21, v15
	v_lshlrev_b32_e32 v52, 16, v59
	v_and_b32_e32 v53, 0xffff0000, v59
	v_pk_mul_f32 v[52:53], v[66:67], v[52:53]
	v_pk_mul_f32 v[54:55], v[20:21], v[22:23]
	ds_read_b128 v[20:23], v90 offset:64
	v_pk_mul_f32 v[56:57], v[54:55], v[52:53]
	ds_read_b128 v[52:55], v90 offset:80
	v_cndmask_b32_e64 v50, v50, v46, s[6:7]
	v_lshlrev_b32_e32 v46, 16, v8
	v_cvt_pk_bf16_f32 v15, v56, v57
	v_cndmask_b32_e64 v51, v51, v47, s[6:7]
	v_and_b32_e32 v47, 0xffff0000, v8
	v_mul_f32_e32 v8, 0xbfb8aa3b, v46
	global_store_dwordx4 v[60:61], v[12:15], off offset:16
	v_exp_f32_e32 v8, v8
	v_cndmask_b32_e64 v41, v41, v37, s[6:7]
	s_waitcnt lgkmcnt(0)
	v_pk_mul_f32 v[12:13], v[22:23], v[62:63] op_sel_hi:[1,0]
	v_pk_mul_f32 v[22:23], v[52:53], v[62:63] op_sel_hi:[1,0]
	v_cndmask_b32_e64 v52, v49, v45, s[6:7]
	v_mul_f32_e32 v45, 0xbfb8aa3b, v47
	v_exp_f32_e32 v45, v45
	v_add_f32_e32 v8, 1.0, v8
	v_cndmask_b32_e64 v49, v48, v44, s[6:7]
	v_rcp_f32_e32 v44, v8
	v_add_f32_e32 v8, 1.0, v45
	v_rcp_f32_e32 v45, v8
	v_pk_mul_f32 v[14:15], v[20:21], v[62:63] op_sel_hi:[1,0]
	v_lshlrev_b32_e32 v48, 16, v49
	v_and_b32_e32 v49, 0xffff0000, v49
	v_pk_mul_f32 v[14:15], v[14:15], v[48:49]
	v_pk_mul_f32 v[44:45], v[44:45], v[46:47]
	v_and_b32_e32 v47, 0xffff0000, v52
	v_pk_mul_f32 v[14:15], v[44:45], v[14:15]
	v_lshlrev_b32_e32 v44, 16, v9
	v_and_b32_e32 v45, 0xffff0000, v9
	v_mul_f32_e32 v8, 0xbfb8aa3b, v44
	v_exp_f32_e32 v9, v8
	v_mul_f32_e32 v8, 0xbfb8aa3b, v45
	v_exp_f32_e32 v46, v8
	v_cvt_pk_bf16_f32 v8, v14, v15
	v_add_f32_e32 v9, 1.0, v9
	v_rcp_f32_e32 v14, v9
	v_add_f32_e32 v9, 1.0, v46
	v_rcp_f32_e32 v15, v9
	v_lshlrev_b32_e32 v46, 16, v52
	v_pk_mul_f32 v[12:13], v[12:13], v[46:47]
	v_pk_mul_f32 v[20:21], v[54:55], v[62:63] op_sel_hi:[1,0]
	v_pk_mul_f32 v[14:15], v[14:15], v[44:45]
	v_and_b32_e32 v45, 0xffff0000, v50
	v_pk_mul_f32 v[12:13], v[14:15], v[12:13]
	v_lshlrev_b32_e32 v14, 16, v10
	v_and_b32_e32 v15, 0xffff0000, v10
	v_mul_f32_e32 v9, 0xbfb8aa3b, v14
	v_exp_f32_e32 v10, v9
	v_mul_f32_e32 v9, 0xbfb8aa3b, v15
	v_exp_f32_e32 v44, v9
	v_cvt_pk_bf16_f32 v9, v12, v13
	v_add_f32_e32 v10, 1.0, v10
	v_rcp_f32_e32 v12, v10
	v_add_f32_e32 v10, 1.0, v44
	v_rcp_f32_e32 v13, v10
	v_lshlrev_b32_e32 v44, 16, v50
	v_pk_mul_f32 v[22:23], v[22:23], v[44:45]
	v_cndmask_b32_e64 v37, v40, v36, s[6:7]
	v_pk_mul_f32 v[12:13], v[12:13], v[14:15]
	v_lshlrev_b32_e32 v14, 16, v11
	v_and_b32_e32 v15, 0xffff0000, v11
	v_mul_f32_e32 v10, 0xbfb8aa3b, v14
	v_exp_f32_e32 v11, v10
	v_mul_f32_e32 v10, 0xbfb8aa3b, v15
	v_pk_mul_f32 v[12:13], v[12:13], v[22:23]
	v_exp_f32_e32 v22, v10
	v_add_f32_e32 v11, 1.0, v11
	v_cvt_pk_bf16_f32 v10, v12, v13
	v_rcp_f32_e32 v12, v11
	v_add_f32_e32 v11, 1.0, v22
	v_rcp_f32_e32 v13, v11
	v_lshlrev_b32_e32 v22, 16, v51
	v_and_b32_e32 v23, 0xffff0000, v51
	v_pk_mul_f32 v[20:21], v[20:21], v[22:23]
	v_pk_mul_f32 v[22:23], v[12:13], v[14:15]
	ds_read_b128 v[12:15], v90 offset:96
	v_pk_mul_f32 v[44:45], v[22:23], v[20:21]
	ds_read_b128 v[20:23], v90 offset:112
	v_cvt_pk_bf16_f32 v11, v44, v45
	global_store_dwordx4 v[60:61], v[8:11], off offset:32
	v_lshlrev_b32_e32 v36, 16, v37
	v_and_b32_e32 v37, 0xffff0000, v37
	s_waitcnt lgkmcnt(0)
	v_pk_mul_f32 v[8:9], v[14:15], v[62:63] op_sel_hi:[1,0]
	v_pk_mul_f32 v[14:15], v[20:21], v[62:63] op_sel_hi:[1,0]
	v_lshlrev_b32_e32 v20, 16, v4
	v_and_b32_e32 v21, 0xffff0000, v4
	v_mul_f32_e32 v4, 0xbfb8aa3b, v20
	v_pk_mul_f32 v[10:11], v[12:13], v[62:63] op_sel_hi:[1,0]
	v_pk_mul_f32 v[12:13], v[22:23], v[62:63] op_sel_hi:[1,0]
	v_exp_f32_e32 v4, v4
	v_mul_f32_e32 v22, 0xbfb8aa3b, v21
	v_exp_f32_e32 v23, v22
	v_pk_mul_f32 v[10:11], v[10:11], v[36:37]
	v_add_f32_e32 v4, 1.0, v4
	v_rcp_f32_e32 v22, v4
	v_add_f32_e32 v4, 1.0, v23
	v_rcp_f32_e32 v23, v4
	v_cndmask_b32_e64 v38, v42, v38, s[6:7]
	v_cndmask_b32_e64 v39, v43, v39, s[6:7]
	s_mov_b32 s33, s65
	v_pk_mul_f32 v[20:21], v[22:23], v[20:21]
	v_and_b32_e32 v23, 0xffff0000, v41
	v_pk_mul_f32 v[10:11], v[20:21], v[10:11]
	v_lshlrev_b32_e32 v20, 16, v5
	v_and_b32_e32 v21, 0xffff0000, v5
	v_mul_f32_e32 v4, 0xbfb8aa3b, v20
	v_exp_f32_e32 v5, v4
	v_mul_f32_e32 v4, 0xbfb8aa3b, v21
	v_exp_f32_e32 v22, v4
	v_cvt_pk_bf16_f32 v4, v10, v11
	v_add_f32_e32 v5, 1.0, v5
	v_rcp_f32_e32 v10, v5
	v_add_f32_e32 v5, 1.0, v22
	v_rcp_f32_e32 v11, v5
	v_lshlrev_b32_e32 v22, 16, v41
	v_pk_mul_f32 v[8:9], v[8:9], v[22:23]
	v_pk_mul_f32 v[10:11], v[10:11], v[20:21]
	s_nop 0
	v_pk_mul_f32 v[8:9], v[10:11], v[8:9]
	v_lshlrev_b32_e32 v10, 16, v6
	v_and_b32_e32 v11, 0xffff0000, v6
	v_mul_f32_e32 v5, 0xbfb8aa3b, v10
	v_exp_f32_e32 v6, v5
	v_mul_f32_e32 v5, 0xbfb8aa3b, v11
	v_exp_f32_e32 v20, v5
	v_cvt_pk_bf16_f32 v5, v8, v9
	v_add_f32_e32 v6, 1.0, v6
	v_rcp_f32_e32 v8, v6
	v_add_f32_e32 v6, 1.0, v20
	v_rcp_f32_e32 v9, v6
	v_lshlrev_b32_e32 v20, 16, v38
	v_and_b32_e32 v21, 0xffff0000, v38
	v_pk_mul_f32 v[14:15], v[14:15], v[20:21]
	v_pk_mul_f32 v[8:9], v[8:9], v[10:11]
	v_lshlrev_b32_e32 v10, 16, v7
	v_and_b32_e32 v11, 0xffff0000, v7
	v_mul_f32_e32 v6, 0xbfb8aa3b, v10
	v_exp_f32_e32 v7, v6
	v_mul_f32_e32 v6, 0xbfb8aa3b, v11
	v_pk_mul_f32 v[8:9], v[8:9], v[14:15]
	v_exp_f32_e32 v14, v6
	v_add_f32_e32 v7, 1.0, v7
	v_cvt_pk_bf16_f32 v6, v8, v9
	v_rcp_f32_e32 v8, v7
	v_add_f32_e32 v7, 1.0, v14
	v_rcp_f32_e32 v9, v7
	v_lshlrev_b32_e32 v14, 16, v39
	v_and_b32_e32 v15, 0xffff0000, v39
	v_pk_mul_f32 v[12:13], v[12:13], v[14:15]
	v_pk_mul_f32 v[8:9], v[8:9], v[10:11]
	s_nop 0
	v_pk_mul_f32 v[8:9], v[8:9], v[12:13]
	s_nop 0
	v_cvt_pk_bf16_f32 v7, v8, v9
	global_store_dwordx4 v[60:61], v[4:7], off offset:48
	s_branch .LBB0_2195
